# k16 + asymmetric DMA wait: leading half (wr==0) defers K-loop vmcnt(8) to after its MFMA segment, trailing half waits early (one more slot of DMA latency tolerance)
# speedup vs baseline: 1.0057x; 1.0057x over previous
; #define PG8_STAGE(bufoff, gbase, voff) do { _Pragma("unroll") for (int _i = 0; _i < 2; ++_i) \
;         __builtin_amdgcn_global_load_lds((const unsigned*)((const char*)(gbase) + (voff)[_i]), (LAS unsigned*)(lds + (bufoff) + ldsw + _i * 8192), 16, 0, 0); } while (0)
; #define PG8_LDA(dst, b, h) do { _Pragma("unroll") for (int m = 0; m < 4; ++m) _Pragma("unroll") for (int k = 0; k < 2; ++k) dst[m][k] = *(const LAS bf16x8*)(lds + PG8_SA(b, h) + aoff + m * 2048 + k * 1024); } while (0)
; #define PG8_LDB(dst, b, h) do { _Pragma("unroll") for (int n = 0; n < 2; ++n) _Pragma("unroll") for (int k = 0; k < 2; ++k) dst[n][k] = *(const LAS bf16x8*)(lds + PG8_SB(b, h) + boff + n * 2048 + k * 1024); } while (0)
; #define PG8_MMA(ai, bj, At, Bt) do { __builtin_amdgcn_s_setprio(1); _Pragma("unroll") for (int m = 0; m < 4; ++m) _Pragma("unroll") for (int n = 0; n < 2; ++n) _Pragma("unroll") for (int k = 0; k < 2; ++k) \
;         acc[ai][bj][m][n] = __builtin_amdgcn_mfma_f32_16x16x32_bf16(Bt[n][k], At[m][k], acc[ai][bj][m][n], 0, 0, 0); __builtin_amdgcn_s_setprio(0); } while (0)
; #define PG8_WAIT_V(n) asm volatile("s_waitcnt vmcnt(" #n ")" ::: "memory")
; #define PG8_WAIT_L(n) asm volatile("s_waitcnt lgkmcnt(" #n ")" ::: "memory")
; #define PG8_BAR __builtin_amdgcn_s_barrier()
; #define PG8_SCHED __builtin_amdgcn_sched_barrier(0)
; template <class Epi>
; __device__ __forceinline__ void gemm_phase(LAS unsigned char* lds, const int tid, const Gemm g, const StaticOrder& S, const Epi& E) {
;     ...
;             PG8_LDB(B0, 0, 0); PG8_LDB(B1, 0, 1); PG8_SCHED; PG8_LDA(At, 0, 0); PG8_STAGE(PG8_SA(1, 1), a1 + hstepA, voffA);
;             PG8_WAIT_V(8); PG8_WAIT_L(0); PG8_BAR; PG8_MMA(0, 0, At, B0); PG8_MMA(0, 1, At, B1); PG8_BAR; PG8_SCHED;
;             PG8_LDA(At, 0, 1); PG8_STAGE(PG8_SB(0, 0), b2, voffB); PG8_STAGE(PG8_SB(0, 1), b2 + hstepB, voffB); PG8_STAGE(PG8_SA(0, 0), a2, voffA);
.LBB0_414:
	s_add_u32 s10, s68, 0xfffc0080
	s_addc_u32 s11, s69, -1
	s_add_i32 s17, 0, 0x10000
	s_cmp_eq_u32 s16, 12
	s_cselect_b32 s73, s7, s11
	s_cselect_b32 s72, s67, s10
	s_cselect_b32 s71, s5, s76
	s_cselect_b32 s70, vcc_lo, vcc_hi
	s_add_i32 s0, 0, 0x14000
	v_add_u32_e32 v70, s17, v202
	v_add_u32_e32 v160, s0, v202
	ds_read_b128 v[50:53], v70
	ds_read_b128 v[54:57], v70 offset:1024
	ds_read_b128 v[66:69], v70 offset:2048
	ds_read_b128 v[70:73], v70 offset:3072
	ds_read_b128 v[156:159], v160
	ds_read_b128 v[170:173], v160 offset:1024
	ds_read_b128 v[174:177], v160 offset:2048
	ds_read_b128 v[178:181], v160 offset:3072
	v_lshl_add_u64 v[160:161], s[68:69], 0, v[152:153]
	s_add_i32 m0, s83, 0xc000
	s_nop 0
	global_load_lds_dwordx4 v[160:161], off
	v_lshl_add_u64 v[160:161], s[68:69], 0, v[154:155]
	s_add_i32 m0, s83, 0xe000
	s_nop 0
	global_load_lds_dwordx4 v[160:161], off
	ds_read_b128 v[216:219], v215
	ds_read_b128 v[220:223], v215 offset:1024
	ds_read_b128 v[224:227], v215 offset:2048
	ds_read_b128 v[228:231], v215 offset:3072
	ds_read_b128 v[232:235], v215 offset:4096
	ds_read_b128 v[236:239], v215 offset:5120
	ds_read_b128 v[240:243], v215 offset:6144
	ds_read_b128 v[244:247], v215 offset:7168
	s_cmp_lg_u64 s[2:3], 0
	s_cbranch_scc1 .Lkw_36
	s_waitcnt vmcnt(8)
.Lkw_36:
	s_waitcnt lgkmcnt(0)
	s_barrier
	s_setprio 1
	s_waitcnt lgkmcnt(0)
	v_mfma_f32_16x16x32_bf16 v[142:145], v[50:53], v[216:219], v[142:145]
	v_mfma_f32_16x16x32_bf16 v[138:141], v[66:69], v[216:219], v[138:141]
	v_mfma_f32_16x16x32_bf16 v[126:129], v[50:53], v[224:227], v[126:129]
	v_mfma_f32_16x16x32_bf16 v[122:125], v[66:69], v[224:227], v[122:125]
	v_mfma_f32_16x16x32_bf16 v[110:113], v[50:53], v[232:235], v[110:113]
	v_mfma_f32_16x16x32_bf16 v[106:109], v[66:69], v[232:235], v[106:109]
	v_mfma_f32_16x16x32_bf16 v[94:97], v[50:53], v[240:243], v[94:97]
	v_mfma_f32_16x16x32_bf16 v[90:93], v[66:69], v[240:243], v[90:93]
	v_mfma_f32_16x16x32_bf16 v[142:145], v[54:57], v[220:223], v[142:145]
	v_mfma_f32_16x16x32_bf16 v[138:141], v[70:73], v[220:223], v[138:141]
	v_mfma_f32_16x16x32_bf16 v[126:129], v[54:57], v[228:231], v[126:129]
	v_mfma_f32_16x16x32_bf16 v[122:125], v[70:73], v[228:231], v[122:125]
	v_mfma_f32_16x16x32_bf16 v[110:113], v[54:57], v[236:239], v[110:113]
	v_mfma_f32_16x16x32_bf16 v[106:109], v[70:73], v[236:239], v[106:109]
	v_mfma_f32_16x16x32_bf16 v[94:97], v[54:57], v[244:247], v[94:97]
	v_mfma_f32_16x16x32_bf16 v[90:93], v[70:73], v[244:247], v[90:93]
	s_setprio 0
	s_setprio 1
	v_mfma_f32_16x16x32_bf16 v[134:137], v[156:159], v[216:219], v[134:137]
	v_mfma_f32_16x16x32_bf16 v[130:133], v[174:177], v[216:219], v[130:133]
	v_mfma_f32_16x16x32_bf16 v[118:121], v[156:159], v[224:227], v[118:121]
	v_mfma_f32_16x16x32_bf16 v[114:117], v[174:177], v[224:227], v[114:117]
	v_mfma_f32_16x16x32_bf16 v[102:105], v[156:159], v[232:235], v[102:105]
	v_mfma_f32_16x16x32_bf16 v[98:101], v[174:177], v[232:235], v[98:101]
	v_mfma_f32_16x16x32_bf16 v[86:89], v[156:159], v[240:243], v[86:89]
	v_mfma_f32_16x16x32_bf16 v[82:85], v[174:177], v[240:243], v[82:85]
	v_mfma_f32_16x16x32_bf16 v[134:137], v[170:173], v[220:223], v[134:137]
	v_mfma_f32_16x16x32_bf16 v[130:133], v[178:181], v[220:223], v[130:133]
	v_mfma_f32_16x16x32_bf16 v[118:121], v[170:173], v[228:231], v[118:121]
	v_mfma_f32_16x16x32_bf16 v[114:117], v[178:181], v[228:231], v[114:117]
	v_mfma_f32_16x16x32_bf16 v[102:105], v[170:173], v[236:239], v[102:105]
	v_mfma_f32_16x16x32_bf16 v[98:101], v[178:181], v[236:239], v[98:101]
	v_mfma_f32_16x16x32_bf16 v[86:89], v[170:173], v[244:247], v[86:89]
	v_mfma_f32_16x16x32_bf16 v[82:85], v[178:181], v[244:247], v[82:85]
	s_setprio 0
	s_waitcnt vmcnt(8)
	s_barrier
	s_add_i32 s1, s17, s82
	v_lshl_add_u64 v[160:161], s[70:71], 0, v[0:1]
	s_mov_b32 m0, s1
	s_nop 0
	global_load_lds_dwordx4 v[160:161], off
	s_add_i32 m0, s1, 0x2000
	s_add_u32 s10, s70, 0x40000
	v_lshl_add_u64 v[182:183], s[70:71], 0, v[146:147]
	s_addc_u32 s11, s71, 0
	s_add_i32 s0, s0, s82
	global_load_lds_dwordx4 v[182:183], off
	v_lshl_add_u64 v[162:163], s[10:11], 0, v[0:1]
	s_mov_b32 m0, s0
	v_lshl_add_u64 v[164:165], s[72:73], 0, v[150:151]
	global_load_lds_dwordx4 v[162:163], off
	v_lshl_add_u64 v[162:163], s[10:11], 0, v[146:147]
	s_add_i32 m0, s0, 0x2000
	s_nop 0
	global_load_lds_dwordx4 v[162:163], off
	v_lshl_add_u64 v[162:163], s[72:73], 0, v[148:149]
	s_mov_b32 m0, s83
	s_nop 0
	global_load_lds_dwordx4 v[162:163], off
	s_mov_b32 m0, s88
	s_nop 0
	global_load_lds_dwordx4 v[164:165], off
	ds_read_b128 v[216:219], v215 offset:16384
	ds_read_b128 v[220:223], v215 offset:17408
	ds_read_b128 v[224:227], v215 offset:18432
	ds_read_b128 v[228:231], v215 offset:19456
	ds_read_b128 v[232:235], v215 offset:20480
	ds_read_b128 v[236:239], v215 offset:21504
	ds_read_b128 v[240:243], v215 offset:22528
	ds_read_b128 v[244:247], v215 offset:23552
	s_cmp_lg_u64 s[2:3], 0
	s_cbranch_scc1 .Lkw_35
	s_waitcnt vmcnt(8)
; #define PG8_STAGE(bufoff, gbase, voff) do { _Pragma("unroll") for (int _i = 0; _i < 2; ++_i) \
;         __builtin_amdgcn_global_load_lds((const unsigned*)((const char*)(gbase) + (voff)[_i]), (LAS unsigned*)(lds + (bufoff) + ldsw + _i * 8192), 16, 0, 0); } while (0)
; #define PG8_LDA(dst, b, h) do { _Pragma("unroll") for (int m = 0; m < 4; ++m) _Pragma("unroll") for (int k = 0; k < 2; ++k) dst[m][k] = *(const LAS bf16x8*)(lds + PG8_SA(b, h) + aoff + m * 2048 + k * 1024); } while (0)
; #define PG8_LDB(dst, b, h) do { _Pragma("unroll") for (int n = 0; n < 2; ++n) _Pragma("unroll") for (int k = 0; k < 2; ++k) dst[n][k] = *(const LAS bf16x8*)(lds + PG8_SB(b, h) + boff + n * 2048 + k * 1024); } while (0)
; #define PG8_MMA(ai, bj, At, Bt) do { __builtin_amdgcn_s_setprio(1); _Pragma("unroll") for (int m = 0; m < 4; ++m) _Pragma("unroll") for (int n = 0; n < 2; ++n) _Pragma("unroll") for (int k = 0; k < 2; ++k) \
;         acc[ai][bj][m][n] = __builtin_amdgcn_mfma_f32_16x16x32_bf16(Bt[n][k], At[m][k], acc[ai][bj][m][n], 0, 0, 0); __builtin_amdgcn_s_setprio(0); } while (0)
; #define PG8_WAIT_V(n) asm volatile("s_waitcnt vmcnt(" #n ")" ::: "memory")
; #define PG8_WAIT_L(n) asm volatile("s_waitcnt lgkmcnt(" #n ")" ::: "memory")
; #define PG8_BAR __builtin_amdgcn_s_barrier()
; #define PG8_SCHED __builtin_amdgcn_sched_barrier(0)
; template <class Epi>
; __device__ __forceinline__ void gemm_phase(LAS unsigned char* lds, const int tid, const Gemm g, const StaticOrder& S, const Epi& E) {
;     ...
;             PG8_LDA(At, 0, 1); PG8_STAGE(PG8_SB(0, 0), b2, voffB); PG8_STAGE(PG8_SB(0, 1), b2 + hstepB, voffB); PG8_STAGE(PG8_SA(0, 0), a2, voffA);
;             PG8_WAIT_V(8); PG8_WAIT_L(0); PG8_BAR; PG8_MMA(1, 0, At, B0); PG8_MMA(1, 1, At, B1); PG8_BAR; PG8_SCHED;
;             PG8_LDB(B0, 1, 0); PG8_LDB(B1, 1, 1); PG8_SCHED; PG8_LDA(At, 1, 0); PG8_STAGE(PG8_SA(0, 1), a2 + hstepA, voffA);
;             PG8_WAIT_V(8); PG8_WAIT_L(0); PG8_BAR; PG8_MMA(0, 0, At, B0); PG8_MMA(0, 1, At, B1); PG8_BAR; PG8_SCHED;
.Lkw_35:
	s_waitcnt lgkmcnt(0)
	s_barrier
	s_setprio 1
	s_waitcnt lgkmcnt(0)
	v_mfma_f32_16x16x32_bf16 v[78:81], v[50:53], v[216:219], v[78:81]
	v_mfma_f32_16x16x32_bf16 v[74:77], v[66:69], v[216:219], v[74:77]
	v_mfma_f32_16x16x32_bf16 v[46:49], v[50:53], v[224:227], v[46:49]
	v_mfma_f32_16x16x32_bf16 v[42:45], v[66:69], v[224:227], v[42:45]
	v_mfma_f32_16x16x32_bf16 v[30:33], v[50:53], v[232:235], v[30:33]
	v_mfma_f32_16x16x32_bf16 v[26:29], v[66:69], v[232:235], v[26:29]
	v_mfma_f32_16x16x32_bf16 v[14:17], v[50:53], v[240:243], v[14:17]
	v_mfma_f32_16x16x32_bf16 v[10:13], v[66:69], v[240:243], v[10:13]
	v_mfma_f32_16x16x32_bf16 v[78:81], v[54:57], v[220:223], v[78:81]
	v_mfma_f32_16x16x32_bf16 v[74:77], v[70:73], v[220:223], v[74:77]
	v_mfma_f32_16x16x32_bf16 v[46:49], v[54:57], v[228:231], v[46:49]
	v_mfma_f32_16x16x32_bf16 v[42:45], v[70:73], v[228:231], v[42:45]
	v_mfma_f32_16x16x32_bf16 v[30:33], v[54:57], v[236:239], v[30:33]
	v_mfma_f32_16x16x32_bf16 v[26:29], v[70:73], v[236:239], v[26:29]
	v_mfma_f32_16x16x32_bf16 v[14:17], v[54:57], v[244:247], v[14:17]
	v_mfma_f32_16x16x32_bf16 v[10:13], v[70:73], v[244:247], v[10:13]
	s_setprio 0
	s_setprio 1
	v_mfma_f32_16x16x32_bf16 v[38:41], v[156:159], v[224:227], v[38:41]
	v_mfma_f32_16x16x32_bf16 v[34:37], v[174:177], v[224:227], v[34:37]
	v_mfma_f32_16x16x32_bf16 v[22:25], v[156:159], v[232:235], v[22:25]
	v_mfma_f32_16x16x32_bf16 v[18:21], v[174:177], v[232:235], v[18:21]
	v_mfma_f32_16x16x32_bf16 v[6:9], v[156:159], v[240:243], v[6:9]
	v_mfma_f32_16x16x32_bf16 v[2:5], v[174:177], v[240:243], v[2:5]
	v_mfma_f32_16x16x32_bf16 v[50:53], v[156:159], v[216:219], v[62:65]
	v_mfma_f32_16x16x32_bf16 v[54:57], v[174:177], v[216:219], v[58:61]
	v_mfma_f32_16x16x32_bf16 v[38:41], v[170:173], v[228:231], v[38:41]
	v_mfma_f32_16x16x32_bf16 v[34:37], v[178:181], v[228:231], v[34:37]
	v_mfma_f32_16x16x32_bf16 v[22:25], v[170:173], v[236:239], v[22:25]
	v_mfma_f32_16x16x32_bf16 v[18:21], v[178:181], v[236:239], v[18:21]
	v_mfma_f32_16x16x32_bf16 v[6:9], v[170:173], v[244:247], v[6:9]
	v_mfma_f32_16x16x32_bf16 v[2:5], v[178:181], v[244:247], v[2:5]
	v_mfma_f32_16x16x32_bf16 v[50:53], v[170:173], v[220:223], v[50:53]
	v_mfma_f32_16x16x32_bf16 v[54:57], v[178:181], v[220:223], v[54:57]
	s_setprio 0
	s_waitcnt vmcnt(8)
	s_barrier
	s_add_i32 s0, 0, 0x18000
	s_add_i32 s1, 0, 0x1c000
	v_add_u32_e32 v70, s0, v202
	v_add_u32_e32 v178, s1, v202
	ds_read_b128 v[58:61], v70
	ds_read_b128 v[62:65], v70 offset:1024
	ds_read_b128 v[66:69], v70 offset:2048
	ds_read_b128 v[70:73], v70 offset:3072
	ds_read_b128 v[156:159], v178
	ds_read_b128 v[170:173], v178 offset:1024
	ds_read_b128 v[174:177], v178 offset:2048
	ds_read_b128 v[178:181], v178 offset:3072
	s_add_u32 s10, s72, 0x40000
	s_addc_u32 s11, s73, 0
	s_mov_b32 m0, s89
	v_lshl_add_u64 v[206:207], s[10:11], 0, v[148:149]
	global_load_lds_dwordx4 v[206:207], off
	v_lshl_add_u64 v[206:207], s[10:11], 0, v[150:151]
	s_mov_b32 m0, s92
	s_nop 0
	global_load_lds_dwordx4 v[206:207], off
	ds_read_b128 v[216:219], v215 offset:32768
	ds_read_b128 v[220:223], v215 offset:33792
	ds_read_b128 v[224:227], v215 offset:34816
	ds_read_b128 v[228:231], v215 offset:35840
	ds_read_b128 v[232:235], v215 offset:36864
	ds_read_b128 v[236:239], v215 offset:37888
	ds_read_b128 v[240:243], v215 offset:38912
	ds_read_b128 v[244:247], v215 offset:39936
	s_cmp_lg_u64 s[2:3], 0
	s_cbranch_scc1 .Lkw_34
	s_waitcnt vmcnt(8)
; #define PG8_STAGE(bufoff, gbase, voff) do { _Pragma("unroll") for (int _i = 0; _i < 2; ++_i) \
;         __builtin_amdgcn_global_load_lds((const unsigned*)((const char*)(gbase) + (voff)[_i]), (LAS unsigned*)(lds + (bufoff) + ldsw + _i * 8192), 16, 0, 0); } while (0)
; #define PG8_LDA(dst, b, h) do { _Pragma("unroll") for (int m = 0; m < 4; ++m) _Pragma("unroll") for (int k = 0; k < 2; ++k) dst[m][k] = *(const LAS bf16x8*)(lds + PG8_SA(b, h) + aoff + m * 2048 + k * 1024); } while (0)
; #define PG8_MMA(ai, bj, At, Bt) do { __builtin_amdgcn_s_setprio(1); _Pragma("unroll") for (int m = 0; m < 4; ++m) _Pragma("unroll") for (int n = 0; n < 2; ++n) _Pragma("unroll") for (int k = 0; k < 2; ++k) \
;         acc[ai][bj][m][n] = __builtin_amdgcn_mfma_f32_16x16x32_bf16(Bt[n][k], At[m][k], acc[ai][bj][m][n], 0, 0, 0); __builtin_amdgcn_s_setprio(0); } while (0)
; #define PG8_WAIT_V(n) asm volatile("s_waitcnt vmcnt(" #n ")" ::: "memory")
; #define PG8_WAIT_L(n) asm volatile("s_waitcnt lgkmcnt(" #n ")" ::: "memory")
; #define PG8_BAR __builtin_amdgcn_s_barrier()
; #define PG8_SCHED __builtin_amdgcn_sched_barrier(0)
; template <class Epi>
; __device__ __forceinline__ void gemm_phase(LAS unsigned char* lds, const int tid, const Gemm g, const StaticOrder& S, const Epi& E) {
;     ...
;             PG8_WAIT_V(8); PG8_WAIT_L(0); PG8_BAR; PG8_MMA(0, 0, At, B0); PG8_MMA(0, 1, At, B1); PG8_BAR; PG8_SCHED;
;             PG8_LDA(At, 1, 1); PG8_STAGE(PG8_SB(1, 0), b3, voffB); PG8_STAGE(PG8_SB(1, 1), b3 + hstepB, voffB); PG8_STAGE(PG8_SA(1, 0), a3, voffA);
;             PG8_WAIT_V(8); PG8_WAIT_L(0); PG8_BAR; PG8_MMA(1, 0, At, B0); PG8_MMA(1, 1, At, B1); PG8_BAR; PG8_SCHED;
;         }
;         if (wr == 0) PG8_BAR;
.Lkw_34:
	s_waitcnt lgkmcnt(0)
	s_barrier
	s_setprio 1
	s_waitcnt lgkmcnt(0)
	v_mfma_f32_16x16x32_bf16 v[142:145], v[58:61], v[216:219], v[142:145]
	v_mfma_f32_16x16x32_bf16 v[138:141], v[66:69], v[216:219], v[138:141]
	v_mfma_f32_16x16x32_bf16 v[126:129], v[58:61], v[224:227], v[126:129]
	v_mfma_f32_16x16x32_bf16 v[122:125], v[66:69], v[224:227], v[122:125]
	v_mfma_f32_16x16x32_bf16 v[110:113], v[58:61], v[232:235], v[110:113]
	v_mfma_f32_16x16x32_bf16 v[106:109], v[66:69], v[232:235], v[106:109]
	v_mfma_f32_16x16x32_bf16 v[94:97], v[58:61], v[240:243], v[94:97]
	v_mfma_f32_16x16x32_bf16 v[90:93], v[66:69], v[240:243], v[90:93]
	v_mfma_f32_16x16x32_bf16 v[142:145], v[62:65], v[220:223], v[142:145]
	v_mfma_f32_16x16x32_bf16 v[138:141], v[70:73], v[220:223], v[138:141]
	v_mfma_f32_16x16x32_bf16 v[126:129], v[62:65], v[228:231], v[126:129]
	v_mfma_f32_16x16x32_bf16 v[122:125], v[70:73], v[228:231], v[122:125]
	v_mfma_f32_16x16x32_bf16 v[110:113], v[62:65], v[236:239], v[110:113]
	v_mfma_f32_16x16x32_bf16 v[106:109], v[70:73], v[236:239], v[106:109]
	v_mfma_f32_16x16x32_bf16 v[94:97], v[62:65], v[244:247], v[94:97]
	v_mfma_f32_16x16x32_bf16 v[90:93], v[70:73], v[244:247], v[90:93]
	s_setprio 0
	s_setprio 1
	v_mfma_f32_16x16x32_bf16 v[134:137], v[156:159], v[216:219], v[134:137]
	v_mfma_f32_16x16x32_bf16 v[130:133], v[174:177], v[216:219], v[130:133]
	v_mfma_f32_16x16x32_bf16 v[118:121], v[156:159], v[224:227], v[118:121]
	v_mfma_f32_16x16x32_bf16 v[114:117], v[174:177], v[224:227], v[114:117]
	v_mfma_f32_16x16x32_bf16 v[102:105], v[156:159], v[232:235], v[102:105]
	v_mfma_f32_16x16x32_bf16 v[98:101], v[174:177], v[232:235], v[98:101]
	v_mfma_f32_16x16x32_bf16 v[86:89], v[156:159], v[240:243], v[86:89]
	v_mfma_f32_16x16x32_bf16 v[82:85], v[174:177], v[240:243], v[82:85]
	v_mfma_f32_16x16x32_bf16 v[134:137], v[170:173], v[220:223], v[134:137]
	v_mfma_f32_16x16x32_bf16 v[130:133], v[178:181], v[220:223], v[130:133]
	v_mfma_f32_16x16x32_bf16 v[118:121], v[170:173], v[228:231], v[118:121]
	v_mfma_f32_16x16x32_bf16 v[114:117], v[178:181], v[228:231], v[114:117]
	v_mfma_f32_16x16x32_bf16 v[102:105], v[170:173], v[236:239], v[102:105]
	v_mfma_f32_16x16x32_bf16 v[98:101], v[178:181], v[236:239], v[98:101]
	v_mfma_f32_16x16x32_bf16 v[86:89], v[170:173], v[244:247], v[86:89]
	v_mfma_f32_16x16x32_bf16 v[82:85], v[178:181], v[244:247], v[82:85]
	s_setprio 0
	s_waitcnt vmcnt(8)
	s_barrier
	s_add_i32 s0, s0, s82
	v_lshl_add_u64 v[160:161], v[160:161], 0, s[36:37]
	s_mov_b32 m0, s0
	s_nop 0
	global_load_lds_dwordx4 v[160:161], off
	s_add_i32 m0, s0, 0x2000
	s_add_u32 s10, s70, 0x40080
	v_lshl_add_u64 v[160:161], v[182:183], 0, s[36:37]
	s_addc_u32 s11, s71, 0
	s_add_i32 s0, s1, s82
	global_load_lds_dwordx4 v[160:161], off
	v_lshl_add_u64 v[160:161], s[10:11], 0, v[0:1]
	s_mov_b32 m0, s0
	s_nop 0
	global_load_lds_dwordx4 v[160:161], off
	v_lshl_add_u64 v[160:161], s[10:11], 0, v[146:147]
	s_add_i32 m0, s0, 0x2000
	s_nop 0
	global_load_lds_dwordx4 v[160:161], off
	v_lshl_add_u64 v[160:161], v[162:163], 0, s[36:37]
	s_mov_b32 m0, s93
	s_nop 0
	global_load_lds_dwordx4 v[160:161], off
	v_lshl_add_u64 v[160:161], v[164:165], 0, s[36:37]
	s_mov_b32 m0, s74
	s_nop 0
	global_load_lds_dwordx4 v[160:161], off
	ds_read_b128 v[216:219], v215 offset:49152
	ds_read_b128 v[220:223], v215 offset:50176
	ds_read_b128 v[224:227], v215 offset:51200
	ds_read_b128 v[228:231], v215 offset:52224
	ds_read_b128 v[232:235], v215 offset:53248
	ds_read_b128 v[236:239], v215 offset:54272
	ds_read_b128 v[240:243], v215 offset:55296
	ds_read_b128 v[244:247], v215 offset:56320
	s_cmp_lg_u64 s[2:3], 0
	s_cbranch_scc1 .Lkw_33
	s_waitcnt vmcnt(8)
.Lkw_33:
	s_waitcnt lgkmcnt(0)
	s_barrier
	s_setprio 1
	s_waitcnt lgkmcnt(0)
	v_mfma_f32_16x16x32_bf16 v[78:81], v[58:61], v[216:219], v[78:81]
	v_mfma_f32_16x16x32_bf16 v[74:77], v[66:69], v[216:219], v[74:77]
	v_mfma_f32_16x16x32_bf16 v[46:49], v[58:61], v[224:227], v[46:49]
	v_mfma_f32_16x16x32_bf16 v[42:45], v[66:69], v[224:227], v[42:45]
	v_mfma_f32_16x16x32_bf16 v[30:33], v[58:61], v[232:235], v[30:33]
	v_mfma_f32_16x16x32_bf16 v[26:29], v[66:69], v[232:235], v[26:29]
	v_mfma_f32_16x16x32_bf16 v[14:17], v[58:61], v[240:243], v[14:17]
	v_mfma_f32_16x16x32_bf16 v[10:13], v[66:69], v[240:243], v[10:13]
	v_mfma_f32_16x16x32_bf16 v[78:81], v[62:65], v[220:223], v[78:81]
	v_mfma_f32_16x16x32_bf16 v[74:77], v[70:73], v[220:223], v[74:77]
	v_mfma_f32_16x16x32_bf16 v[46:49], v[62:65], v[228:231], v[46:49]
	v_mfma_f32_16x16x32_bf16 v[42:45], v[70:73], v[228:231], v[42:45]
	v_mfma_f32_16x16x32_bf16 v[30:33], v[62:65], v[236:239], v[30:33]
	v_mfma_f32_16x16x32_bf16 v[26:29], v[70:73], v[236:239], v[26:29]
	v_mfma_f32_16x16x32_bf16 v[14:17], v[62:65], v[244:247], v[14:17]
	v_mfma_f32_16x16x32_bf16 v[10:13], v[70:73], v[244:247], v[10:13]
	s_setprio 0
	s_setprio 1
	v_mfma_f32_16x16x32_bf16 v[50:53], v[156:159], v[216:219], v[50:53]
	v_mfma_f32_16x16x32_bf16 v[62:65], v[170:173], v[220:223], v[50:53]
	v_mfma_f32_16x16x32_bf16 v[50:53], v[174:177], v[216:219], v[54:57]
	v_mfma_f32_16x16x32_bf16 v[38:41], v[156:159], v[224:227], v[38:41]
	v_mfma_f32_16x16x32_bf16 v[34:37], v[174:177], v[224:227], v[34:37]
	v_mfma_f32_16x16x32_bf16 v[22:25], v[156:159], v[232:235], v[22:25]
	v_mfma_f32_16x16x32_bf16 v[18:21], v[174:177], v[232:235], v[18:21]
	v_mfma_f32_16x16x32_bf16 v[6:9], v[156:159], v[240:243], v[6:9]
	v_mfma_f32_16x16x32_bf16 v[2:5], v[174:177], v[240:243], v[2:5]
	v_mfma_f32_16x16x32_bf16 v[58:61], v[178:181], v[220:223], v[50:53]
	v_mfma_f32_16x16x32_bf16 v[38:41], v[170:173], v[228:231], v[38:41]
	v_mfma_f32_16x16x32_bf16 v[34:37], v[178:181], v[228:231], v[34:37]
	v_mfma_f32_16x16x32_bf16 v[22:25], v[170:173], v[236:239], v[22:25]
	v_mfma_f32_16x16x32_bf16 v[18:21], v[178:181], v[236:239], v[18:21]
	v_mfma_f32_16x16x32_bf16 v[6:9], v[170:173], v[244:247], v[6:9]
	v_mfma_f32_16x16x32_bf16 v[2:5], v[178:181], v[244:247], v[2:5]
	s_setprio 0
	s_waitcnt vmcnt(8)
	s_barrier
	s_add_i32 s16, s16, 2
	s_add_u32 s68, s68, 0x100
	s_addc_u32 s69, s69, 0
	s_add_u32 vcc_hi, vcc_hi, 0x100
	s_addc_u32 s76, s76, 0
	s_cmp_gt_u32 s16, 13
	s_cbranch_scc0 .LBB0_414
	s_and_b64 vcc, exec, s[2:3]
	s_cbranch_vccz .LBB0_417
	s_barrier

; #define PG8_STAGE(bufoff, gbase, voff) do { _Pragma("unroll") for (int _i = 0; _i < 2; ++_i) \
;         __builtin_amdgcn_global_load_lds((const unsigned*)((const char*)(gbase) + (voff)[_i]), (LAS unsigned*)(lds + (bufoff) + ldsw + _i * 8192), 16, 0, 0); } while (0)
; #define PG8_LDA(dst, b, h) do { _Pragma("unroll") for (int m = 0; m < 4; ++m) _Pragma("unroll") for (int k = 0; k < 2; ++k) dst[m][k] = *(const LAS bf16x8*)(lds + PG8_SA(b, h) + aoff + m * 2048 + k * 1024); } while (0)
; #define PG8_LDB(dst, b, h) do { _Pragma("unroll") for (int n = 0; n < 2; ++n) _Pragma("unroll") for (int k = 0; k < 2; ++k) dst[n][k] = *(const LAS bf16x8*)(lds + PG8_SB(b, h) + boff + n * 2048 + k * 1024); } while (0)
; #define PG8_MMA(ai, bj, At, Bt) do { __builtin_amdgcn_s_setprio(1); _Pragma("unroll") for (int m = 0; m < 4; ++m) _Pragma("unroll") for (int n = 0; n < 2; ++n) _Pragma("unroll") for (int k = 0; k < 2; ++k) \
;         acc[ai][bj][m][n] = __builtin_amdgcn_mfma_f32_16x16x32_bf16(Bt[n][k], At[m][k], acc[ai][bj][m][n], 0, 0, 0); __builtin_amdgcn_s_setprio(0); } while (0)
; #define PG8_WAIT_V(n) asm volatile("s_waitcnt vmcnt(" #n ")" ::: "memory")
; #define PG8_WAIT_L(n) asm volatile("s_waitcnt lgkmcnt(" #n ")" ::: "memory")
; #define PG8_BAR __builtin_amdgcn_s_barrier()
; #define PG8_SCHED __builtin_amdgcn_sched_barrier(0)
; template <class Epi>
; __device__ __forceinline__ void gemm_phase(LAS unsigned char* lds, const int tid, const Gemm g, const StaticOrder& S, const Epi& E) {
;     ...
;             PG8_LDB(B0, 0, 0); PG8_LDB(B1, 0, 1); PG8_SCHED; PG8_LDA(At, 0, 0); PG8_STAGE(PG8_SA(1, 1), a1 + hstepA, voffA);
;             PG8_WAIT_V(8); PG8_WAIT_L(0); PG8_BAR; PG8_MMA(0, 0, At, B0); PG8_MMA(0, 1, At, B1); PG8_BAR; PG8_SCHED;
;             PG8_LDA(At, 0, 1); PG8_STAGE(PG8_SB(0, 0), b2, voffB); PG8_STAGE(PG8_SB(0, 1), b2 + hstepB, voffB); PG8_STAGE(PG8_SA(0, 0), a2, voffA);
.LBB0_945:
	s_add_u32 s30, s72, 0xfffc0080
	s_addc_u32 s31, s73, -1
	s_add_i32 s76, 0, 0x10000
	s_cmp_eq_u32 vcc_hi, 12
	s_cselect_b32 s75, s9, s31
	s_cselect_b32 s74, s27, s30
	v_add_u32_e32 v0, s76, v178
	s_cselect_b32 s31, s7, vcc_lo
	s_cselect_b32 s30, s28, s65
	s_add_i32 s0, 0, 0x14000
	ds_read_b128 v[18:21], v0
	ds_read_b128 v[22:25], v0 offset:1024
	ds_read_b128 v[26:29], v0 offset:2048
	ds_read_b128 v[30:33], v0 offset:3072
	v_add_u32_e32 v0, s0, v178
	ds_read_b128 v[170:173], v0
	ds_read_b128 v[174:177], v0 offset:1024
	ds_read_b128 v[190:193], v0 offset:2048
	ds_read_b128 v[194:197], v0 offset:3072
	v_lshl_add_u64 v[162:163], s[72:73], 0, v[158:159]
	s_add_i32 m0, s71, 0xc000
	s_nop 0
	global_load_lds_dwordx4 v[162:163], off
	v_lshl_add_u64 v[162:163], s[72:73], 0, v[160:161]
	s_add_i32 m0, s71, 0xe000
	s_nop 0
	global_load_lds_dwordx4 v[162:163], off
	ds_read_b128 v[198:201], v189
	ds_read_b128 v[210:213], v189 offset:1024
	ds_read_b128 v[214:217], v189 offset:2048
	ds_read_b128 v[218:221], v189 offset:3072
	ds_read_b128 v[222:225], v189 offset:4096
	ds_read_b128 v[226:229], v189 offset:5120
	ds_read_b128 v[230:233], v189 offset:6144
	ds_read_b128 v[234:237], v189 offset:7168
	s_cmp_lg_u64 s[4:5], 0
	s_cbranch_scc1 .Lkw_32
	s_waitcnt vmcnt(8)
.Lkw_32:
	s_waitcnt lgkmcnt(0)
	s_barrier
	s_setprio 1
	s_waitcnt lgkmcnt(0)
	v_mfma_f32_16x16x32_bf16 v[142:145], v[18:21], v[198:201], v[142:145]
	v_mfma_f32_16x16x32_bf16 v[138:141], v[26:29], v[198:201], v[138:141]
	v_mfma_f32_16x16x32_bf16 v[126:129], v[18:21], v[214:217], v[126:129]
	v_mfma_f32_16x16x32_bf16 v[122:125], v[26:29], v[214:217], v[122:125]
	v_mfma_f32_16x16x32_bf16 v[110:113], v[18:21], v[222:225], v[110:113]
	v_mfma_f32_16x16x32_bf16 v[106:109], v[26:29], v[222:225], v[106:109]
	v_mfma_f32_16x16x32_bf16 v[94:97], v[18:21], v[230:233], v[94:97]
	v_mfma_f32_16x16x32_bf16 v[90:93], v[26:29], v[230:233], v[90:93]
	v_mfma_f32_16x16x32_bf16 v[142:145], v[22:25], v[210:213], v[142:145]
	v_mfma_f32_16x16x32_bf16 v[138:141], v[30:33], v[210:213], v[138:141]
	v_mfma_f32_16x16x32_bf16 v[126:129], v[22:25], v[218:221], v[126:129]
	v_mfma_f32_16x16x32_bf16 v[122:125], v[30:33], v[218:221], v[122:125]
	v_mfma_f32_16x16x32_bf16 v[110:113], v[22:25], v[226:229], v[110:113]
	v_mfma_f32_16x16x32_bf16 v[106:109], v[30:33], v[226:229], v[106:109]
	v_mfma_f32_16x16x32_bf16 v[94:97], v[22:25], v[234:237], v[94:97]
	v_mfma_f32_16x16x32_bf16 v[90:93], v[30:33], v[234:237], v[90:93]
	s_setprio 0
	s_setprio 1
	v_mfma_f32_16x16x32_bf16 v[134:137], v[170:173], v[198:201], v[134:137]
	v_mfma_f32_16x16x32_bf16 v[130:133], v[190:193], v[198:201], v[130:133]
	v_mfma_f32_16x16x32_bf16 v[118:121], v[170:173], v[214:217], v[118:121]
	v_mfma_f32_16x16x32_bf16 v[114:117], v[190:193], v[214:217], v[114:117]
	v_mfma_f32_16x16x32_bf16 v[102:105], v[170:173], v[222:225], v[102:105]
	v_mfma_f32_16x16x32_bf16 v[98:101], v[190:193], v[222:225], v[98:101]
	v_mfma_f32_16x16x32_bf16 v[86:89], v[170:173], v[230:233], v[86:89]
	v_mfma_f32_16x16x32_bf16 v[82:85], v[190:193], v[230:233], v[82:85]
	v_mfma_f32_16x16x32_bf16 v[134:137], v[174:177], v[210:213], v[134:137]
	v_mfma_f32_16x16x32_bf16 v[130:133], v[194:197], v[210:213], v[130:133]
	v_mfma_f32_16x16x32_bf16 v[118:121], v[174:177], v[218:221], v[118:121]
	v_mfma_f32_16x16x32_bf16 v[114:117], v[194:197], v[218:221], v[114:117]
	v_mfma_f32_16x16x32_bf16 v[102:105], v[174:177], v[226:229], v[102:105]
	v_mfma_f32_16x16x32_bf16 v[98:101], v[194:197], v[226:229], v[98:101]
	v_mfma_f32_16x16x32_bf16 v[86:89], v[174:177], v[234:237], v[86:89]
	v_mfma_f32_16x16x32_bf16 v[82:85], v[194:197], v[234:237], v[82:85]
	s_setprio 0
	s_waitcnt vmcnt(8)
	s_barrier
	s_add_i32 s1, s76, s93
	v_lshl_add_u64 v[162:163], s[30:31], 0, v[150:151]
	s_mov_b32 m0, s1
	s_nop 0
	global_load_lds_dwordx4 v[162:163], off
	s_add_i32 m0, s1, 0x2000
	s_add_u32 s76, s30, 0x40000
	v_lshl_add_u64 v[164:165], s[30:31], 0, v[154:155]
	s_addc_u32 s77, s31, 0
	s_add_i32 s0, s0, s93
	global_load_lds_dwordx4 v[164:165], off
	v_lshl_add_u64 v[202:203], s[76:77], 0, v[150:151]
	s_mov_b32 m0, s0
	v_lshl_add_u64 v[206:207], s[74:75], 0, v[152:153]
	global_load_lds_dwordx4 v[202:203], off
	v_lshl_add_u64 v[202:203], s[76:77], 0, v[154:155]
	s_add_i32 m0, s0, 0x2000
	s_nop 0
	global_load_lds_dwordx4 v[202:203], off
	v_lshl_add_u64 v[202:203], s[74:75], 0, v[148:149]
	s_mov_b32 m0, s71
	s_nop 0
	global_load_lds_dwordx4 v[202:203], off
	s_mov_b32 m0, s88
	s_nop 0
	global_load_lds_dwordx4 v[206:207], off
	ds_read_b128 v[198:201], v189 offset:16384
	ds_read_b128 v[210:213], v189 offset:17408
	ds_read_b128 v[214:217], v189 offset:18432
	ds_read_b128 v[218:221], v189 offset:19456
	ds_read_b128 v[222:225], v189 offset:20480
	ds_read_b128 v[226:229], v189 offset:21504
	ds_read_b128 v[230:233], v189 offset:22528
	ds_read_b128 v[234:237], v189 offset:23552
	s_cmp_lg_u64 s[4:5], 0
	s_cbranch_scc1 .Lkw_31
	s_waitcnt vmcnt(8)
; #define PG8_STAGE(bufoff, gbase, voff) do { _Pragma("unroll") for (int _i = 0; _i < 2; ++_i) \
;         __builtin_amdgcn_global_load_lds((const unsigned*)((const char*)(gbase) + (voff)[_i]), (LAS unsigned*)(lds + (bufoff) + ldsw + _i * 8192), 16, 0, 0); } while (0)
; #define PG8_LDA(dst, b, h) do { _Pragma("unroll") for (int m = 0; m < 4; ++m) _Pragma("unroll") for (int k = 0; k < 2; ++k) dst[m][k] = *(const LAS bf16x8*)(lds + PG8_SA(b, h) + aoff + m * 2048 + k * 1024); } while (0)
; #define PG8_LDB(dst, b, h) do { _Pragma("unroll") for (int n = 0; n < 2; ++n) _Pragma("unroll") for (int k = 0; k < 2; ++k) dst[n][k] = *(const LAS bf16x8*)(lds + PG8_SB(b, h) + boff + n * 2048 + k * 1024); } while (0)
; #define PG8_MMA(ai, bj, At, Bt) do { __builtin_amdgcn_s_setprio(1); _Pragma("unroll") for (int m = 0; m < 4; ++m) _Pragma("unroll") for (int n = 0; n < 2; ++n) _Pragma("unroll") for (int k = 0; k < 2; ++k) \
;         acc[ai][bj][m][n] = __builtin_amdgcn_mfma_f32_16x16x32_bf16(Bt[n][k], At[m][k], acc[ai][bj][m][n], 0, 0, 0); __builtin_amdgcn_s_setprio(0); } while (0)
; #define PG8_WAIT_V(n) asm volatile("s_waitcnt vmcnt(" #n ")" ::: "memory")
; #define PG8_WAIT_L(n) asm volatile("s_waitcnt lgkmcnt(" #n ")" ::: "memory")
; #define PG8_BAR __builtin_amdgcn_s_barrier()
; #define PG8_SCHED __builtin_amdgcn_sched_barrier(0)
; template <class Epi>
; __device__ __forceinline__ void gemm_phase(LAS unsigned char* lds, const int tid, const Gemm g, const StaticOrder& S, const Epi& E) {
;     ...
;             PG8_LDA(At, 0, 1); PG8_STAGE(PG8_SB(0, 0), b2, voffB); PG8_STAGE(PG8_SB(0, 1), b2 + hstepB, voffB); PG8_STAGE(PG8_SA(0, 0), a2, voffA);
;             PG8_WAIT_V(8); PG8_WAIT_L(0); PG8_BAR; PG8_MMA(1, 0, At, B0); PG8_MMA(1, 1, At, B1); PG8_BAR; PG8_SCHED;
;             PG8_LDB(B0, 1, 0); PG8_LDB(B1, 1, 1); PG8_SCHED; PG8_LDA(At, 1, 0); PG8_STAGE(PG8_SA(0, 1), a2 + hstepA, voffA);
;             PG8_WAIT_V(8); PG8_WAIT_L(0); PG8_BAR; PG8_MMA(0, 0, At, B0); PG8_MMA(0, 1, At, B1); PG8_BAR; PG8_SCHED;
.Lkw_31:
	s_waitcnt lgkmcnt(0)
	s_barrier
	s_setprio 1
	s_waitcnt lgkmcnt(0)
	v_mfma_f32_16x16x32_bf16 v[78:81], v[18:21], v[198:201], v[78:81]
	v_mfma_f32_16x16x32_bf16 v[74:77], v[26:29], v[198:201], v[74:77]
	v_mfma_f32_16x16x32_bf16 v[62:65], v[18:21], v[214:217], v[62:65]
	v_mfma_f32_16x16x32_bf16 v[58:61], v[26:29], v[214:217], v[58:61]
	v_mfma_f32_16x16x32_bf16 v[46:49], v[18:21], v[222:225], v[46:49]
	v_mfma_f32_16x16x32_bf16 v[42:45], v[26:29], v[222:225], v[42:45]
	v_mfma_f32_16x16x32_bf16 v[14:17], v[18:21], v[230:233], v[14:17]
	v_mfma_f32_16x16x32_bf16 v[10:13], v[26:29], v[230:233], v[10:13]
	v_mfma_f32_16x16x32_bf16 v[78:81], v[22:25], v[210:213], v[78:81]
	v_mfma_f32_16x16x32_bf16 v[74:77], v[30:33], v[210:213], v[74:77]
	v_mfma_f32_16x16x32_bf16 v[62:65], v[22:25], v[218:221], v[62:65]
	v_mfma_f32_16x16x32_bf16 v[58:61], v[30:33], v[218:221], v[58:61]
	v_mfma_f32_16x16x32_bf16 v[46:49], v[22:25], v[226:229], v[46:49]
	v_mfma_f32_16x16x32_bf16 v[42:45], v[30:33], v[226:229], v[42:45]
	v_mfma_f32_16x16x32_bf16 v[14:17], v[22:25], v[234:237], v[14:17]
	v_mfma_f32_16x16x32_bf16 v[10:13], v[30:33], v[234:237], v[10:13]
	s_setprio 0
	s_setprio 1
	v_mfma_f32_16x16x32_bf16 v[38:41], v[170:173], v[222:225], v[38:41]
	v_mfma_f32_16x16x32_bf16 v[34:37], v[190:193], v[222:225], v[34:37]
	v_mfma_f32_16x16x32_bf16 v[6:9], v[170:173], v[230:233], v[6:9]
	v_mfma_f32_16x16x32_bf16 v[2:5], v[190:193], v[230:233], v[2:5]
	v_mfma_f32_16x16x32_bf16 v[18:21], v[170:173], v[198:201], v[70:73]
	v_mfma_f32_16x16x32_bf16 v[22:25], v[190:193], v[198:201], v[66:69]
	v_mfma_f32_16x16x32_bf16 v[26:29], v[170:173], v[214:217], v[54:57]
	v_mfma_f32_16x16x32_bf16 v[30:33], v[190:193], v[214:217], v[50:53]
	v_mfma_f32_16x16x32_bf16 v[38:41], v[174:177], v[226:229], v[38:41]
	v_mfma_f32_16x16x32_bf16 v[34:37], v[194:197], v[226:229], v[34:37]
	v_mfma_f32_16x16x32_bf16 v[6:9], v[174:177], v[234:237], v[6:9]
	v_mfma_f32_16x16x32_bf16 v[2:5], v[194:197], v[234:237], v[2:5]
	v_mfma_f32_16x16x32_bf16 v[18:21], v[174:177], v[210:213], v[18:21]
	v_mfma_f32_16x16x32_bf16 v[22:25], v[194:197], v[210:213], v[22:25]
	v_mfma_f32_16x16x32_bf16 v[26:29], v[174:177], v[218:221], v[26:29]
	v_mfma_f32_16x16x32_bf16 v[30:33], v[194:197], v[218:221], v[30:33]
	s_setprio 0
	s_waitcnt vmcnt(8)
	s_barrier
	s_add_i32 s0, 0, 0x18000
	v_add_u32_e32 v0, s0, v178
	s_add_i32 s1, 0, 0x1c000
	ds_read_b128 v[50:53], v0
	ds_read_b128 v[54:57], v0 offset:1024
	ds_read_b128 v[66:69], v0 offset:2048
	ds_read_b128 v[70:73], v0 offset:3072
	v_add_u32_e32 v0, s1, v178
	ds_read_b128 v[170:173], v0
	ds_read_b128 v[174:177], v0 offset:1024
	ds_read_b128 v[190:193], v0 offset:2048
	ds_read_b128 v[194:197], v0 offset:3072
	s_add_u32 s74, s74, 0x40000
	s_addc_u32 s75, s75, 0
	s_mov_b32 m0, s83
	v_lshl_add_u64 v[238:239], s[74:75], 0, v[148:149]
	global_load_lds_dwordx4 v[238:239], off
	v_lshl_add_u64 v[238:239], s[74:75], 0, v[152:153]
	s_mov_b32 m0, s16
	s_nop 0
	global_load_lds_dwordx4 v[238:239], off
	ds_read_b128 v[198:201], v189 offset:32768
	ds_read_b128 v[210:213], v189 offset:33792
	ds_read_b128 v[214:217], v189 offset:34816
	ds_read_b128 v[218:221], v189 offset:35840
	ds_read_b128 v[222:225], v189 offset:36864
	ds_read_b128 v[226:229], v189 offset:37888
	ds_read_b128 v[230:233], v189 offset:38912
	ds_read_b128 v[234:237], v189 offset:39936
	s_cmp_lg_u64 s[4:5], 0
	s_cbranch_scc1 .Lkw_30
	s_waitcnt vmcnt(8)
; #define PG8_STAGE(bufoff, gbase, voff) do { _Pragma("unroll") for (int _i = 0; _i < 2; ++_i) \
;         __builtin_amdgcn_global_load_lds((const unsigned*)((const char*)(gbase) + (voff)[_i]), (LAS unsigned*)(lds + (bufoff) + ldsw + _i * 8192), 16, 0, 0); } while (0)
; #define PG8_LDA(dst, b, h) do { _Pragma("unroll") for (int m = 0; m < 4; ++m) _Pragma("unroll") for (int k = 0; k < 2; ++k) dst[m][k] = *(const LAS bf16x8*)(lds + PG8_SA(b, h) + aoff + m * 2048 + k * 1024); } while (0)
; #define PG8_MMA(ai, bj, At, Bt) do { __builtin_amdgcn_s_setprio(1); _Pragma("unroll") for (int m = 0; m < 4; ++m) _Pragma("unroll") for (int n = 0; n < 2; ++n) _Pragma("unroll") for (int k = 0; k < 2; ++k) \
;         acc[ai][bj][m][n] = __builtin_amdgcn_mfma_f32_16x16x32_bf16(Bt[n][k], At[m][k], acc[ai][bj][m][n], 0, 0, 0); __builtin_amdgcn_s_setprio(0); } while (0)
; #define PG8_WAIT_V(n) asm volatile("s_waitcnt vmcnt(" #n ")" ::: "memory")
; #define PG8_WAIT_L(n) asm volatile("s_waitcnt lgkmcnt(" #n ")" ::: "memory")
; #define PG8_BAR __builtin_amdgcn_s_barrier()
; #define PG8_SCHED __builtin_amdgcn_sched_barrier(0)
; template <class Epi>
; __device__ __forceinline__ void gemm_phase(LAS unsigned char* lds, const int tid, const Gemm g, const StaticOrder& S, const Epi& E) {
;     ...
;             PG8_WAIT_V(8); PG8_WAIT_L(0); PG8_BAR; PG8_MMA(0, 0, At, B0); PG8_MMA(0, 1, At, B1); PG8_BAR; PG8_SCHED;
;             PG8_LDA(At, 1, 1); PG8_STAGE(PG8_SB(1, 0), b3, voffB); PG8_STAGE(PG8_SB(1, 1), b3 + hstepB, voffB); PG8_STAGE(PG8_SA(1, 0), a3, voffA);
;             PG8_WAIT_V(8); PG8_WAIT_L(0); PG8_BAR; PG8_MMA(1, 0, At, B0); PG8_MMA(1, 1, At, B1); PG8_BAR; PG8_SCHED;
;         }
;         if (wr == 0) PG8_BAR;
.Lkw_30:
	s_waitcnt lgkmcnt(0)
	s_barrier
	s_setprio 1
	s_waitcnt lgkmcnt(0)
	v_mfma_f32_16x16x32_bf16 v[142:145], v[50:53], v[198:201], v[142:145]
	v_mfma_f32_16x16x32_bf16 v[138:141], v[66:69], v[198:201], v[138:141]
	v_mfma_f32_16x16x32_bf16 v[126:129], v[50:53], v[214:217], v[126:129]
	v_mfma_f32_16x16x32_bf16 v[122:125], v[66:69], v[214:217], v[122:125]
	v_mfma_f32_16x16x32_bf16 v[110:113], v[50:53], v[222:225], v[110:113]
	v_mfma_f32_16x16x32_bf16 v[106:109], v[66:69], v[222:225], v[106:109]
	v_mfma_f32_16x16x32_bf16 v[94:97], v[50:53], v[230:233], v[94:97]
	v_mfma_f32_16x16x32_bf16 v[90:93], v[66:69], v[230:233], v[90:93]
	v_mfma_f32_16x16x32_bf16 v[142:145], v[54:57], v[210:213], v[142:145]
	v_mfma_f32_16x16x32_bf16 v[138:141], v[70:73], v[210:213], v[138:141]
	v_mfma_f32_16x16x32_bf16 v[126:129], v[54:57], v[218:221], v[126:129]
	v_mfma_f32_16x16x32_bf16 v[122:125], v[70:73], v[218:221], v[122:125]
	v_mfma_f32_16x16x32_bf16 v[110:113], v[54:57], v[226:229], v[110:113]
	v_mfma_f32_16x16x32_bf16 v[106:109], v[70:73], v[226:229], v[106:109]
	v_mfma_f32_16x16x32_bf16 v[94:97], v[54:57], v[234:237], v[94:97]
	v_mfma_f32_16x16x32_bf16 v[90:93], v[70:73], v[234:237], v[90:93]
	s_setprio 0
	s_setprio 1
	v_mfma_f32_16x16x32_bf16 v[134:137], v[170:173], v[198:201], v[134:137]
	v_mfma_f32_16x16x32_bf16 v[130:133], v[190:193], v[198:201], v[130:133]
	v_mfma_f32_16x16x32_bf16 v[118:121], v[170:173], v[214:217], v[118:121]
	v_mfma_f32_16x16x32_bf16 v[114:117], v[190:193], v[214:217], v[114:117]
	v_mfma_f32_16x16x32_bf16 v[102:105], v[170:173], v[222:225], v[102:105]
	v_mfma_f32_16x16x32_bf16 v[98:101], v[190:193], v[222:225], v[98:101]
	v_mfma_f32_16x16x32_bf16 v[86:89], v[170:173], v[230:233], v[86:89]
	v_mfma_f32_16x16x32_bf16 v[82:85], v[190:193], v[230:233], v[82:85]
	v_mfma_f32_16x16x32_bf16 v[134:137], v[174:177], v[210:213], v[134:137]
	v_mfma_f32_16x16x32_bf16 v[130:133], v[194:197], v[210:213], v[130:133]
	v_mfma_f32_16x16x32_bf16 v[118:121], v[174:177], v[218:221], v[118:121]
	v_mfma_f32_16x16x32_bf16 v[114:117], v[194:197], v[218:221], v[114:117]
	v_mfma_f32_16x16x32_bf16 v[102:105], v[174:177], v[226:229], v[102:105]
	v_mfma_f32_16x16x32_bf16 v[98:101], v[194:197], v[226:229], v[98:101]
	v_mfma_f32_16x16x32_bf16 v[86:89], v[174:177], v[234:237], v[86:89]
	v_mfma_f32_16x16x32_bf16 v[82:85], v[194:197], v[234:237], v[82:85]
	s_setprio 0
	s_waitcnt vmcnt(8)
	s_barrier
	s_add_i32 s0, s0, s93
	v_lshl_add_u64 v[162:163], v[162:163], 0, s[36:37]
	s_mov_b32 m0, s0
	s_nop 0
	global_load_lds_dwordx4 v[162:163], off
	s_add_i32 m0, s0, 0x2000
	s_add_u32 s30, s30, 0x40080
	v_lshl_add_u64 v[162:163], v[164:165], 0, s[36:37]
	s_addc_u32 s31, s31, 0
	s_add_i32 s0, s1, s93
	global_load_lds_dwordx4 v[162:163], off
	v_lshl_add_u64 v[162:163], s[30:31], 0, v[150:151]
	s_mov_b32 m0, s0
	s_nop 0
	global_load_lds_dwordx4 v[162:163], off
	v_lshl_add_u64 v[162:163], s[30:31], 0, v[154:155]
	s_add_i32 m0, s0, 0x2000
	s_nop 0
	global_load_lds_dwordx4 v[162:163], off
	v_lshl_add_u64 v[162:163], v[202:203], 0, s[36:37]
	s_mov_b32 m0, s92
	s_nop 0
	global_load_lds_dwordx4 v[162:163], off
	v_lshl_add_u64 v[162:163], v[206:207], 0, s[36:37]
	s_mov_b32 m0, s89
	s_nop 0
	global_load_lds_dwordx4 v[162:163], off
	ds_read_b128 v[198:201], v189 offset:49152
	ds_read_b128 v[210:213], v189 offset:50176
	ds_read_b128 v[214:217], v189 offset:51200
	ds_read_b128 v[218:221], v189 offset:52224
	ds_read_b128 v[222:225], v189 offset:53248
	ds_read_b128 v[226:229], v189 offset:54272
	ds_read_b128 v[230:233], v189 offset:55296
	ds_read_b128 v[234:237], v189 offset:56320
	s_cmp_lg_u64 s[4:5], 0
	s_cbranch_scc1 .Lkw_29
	s_waitcnt vmcnt(8)
.Lkw_29:
	s_waitcnt lgkmcnt(0)
	s_barrier
	s_setprio 1
	s_waitcnt lgkmcnt(0)
	v_mfma_f32_16x16x32_bf16 v[78:81], v[50:53], v[198:201], v[78:81]
	v_mfma_f32_16x16x32_bf16 v[74:77], v[66:69], v[198:201], v[74:77]
	v_mfma_f32_16x16x32_bf16 v[62:65], v[50:53], v[214:217], v[62:65]
	v_mfma_f32_16x16x32_bf16 v[58:61], v[66:69], v[214:217], v[58:61]
	v_mfma_f32_16x16x32_bf16 v[46:49], v[50:53], v[222:225], v[46:49]
	v_mfma_f32_16x16x32_bf16 v[42:45], v[66:69], v[222:225], v[42:45]
	v_mfma_f32_16x16x32_bf16 v[14:17], v[50:53], v[230:233], v[14:17]
	v_mfma_f32_16x16x32_bf16 v[10:13], v[66:69], v[230:233], v[10:13]
	v_mfma_f32_16x16x32_bf16 v[78:81], v[54:57], v[210:213], v[78:81]
	v_mfma_f32_16x16x32_bf16 v[74:77], v[70:73], v[210:213], v[74:77]
	v_mfma_f32_16x16x32_bf16 v[62:65], v[54:57], v[218:221], v[62:65]
	v_mfma_f32_16x16x32_bf16 v[58:61], v[70:73], v[218:221], v[58:61]
	v_mfma_f32_16x16x32_bf16 v[46:49], v[54:57], v[226:229], v[46:49]
	v_mfma_f32_16x16x32_bf16 v[42:45], v[70:73], v[226:229], v[42:45]
	v_mfma_f32_16x16x32_bf16 v[14:17], v[54:57], v[234:237], v[14:17]
	v_mfma_f32_16x16x32_bf16 v[10:13], v[70:73], v[234:237], v[10:13]
	s_setprio 0
	s_setprio 1
	v_mfma_f32_16x16x32_bf16 v[18:21], v[170:173], v[198:201], v[18:21]
	v_mfma_f32_16x16x32_bf16 v[70:73], v[174:177], v[210:213], v[18:21]
	v_mfma_f32_16x16x32_bf16 v[18:21], v[190:193], v[198:201], v[22:25]
	v_mfma_f32_16x16x32_bf16 v[66:69], v[194:197], v[210:213], v[18:21]
	v_mfma_f32_16x16x32_bf16 v[18:21], v[170:173], v[214:217], v[26:29]
	v_mfma_f32_16x16x32_bf16 v[54:57], v[174:177], v[218:221], v[18:21]
	v_mfma_f32_16x16x32_bf16 v[18:21], v[190:193], v[214:217], v[30:33]
	v_mfma_f32_16x16x32_bf16 v[50:53], v[194:197], v[218:221], v[18:21]
	v_mfma_f32_16x16x32_bf16 v[18:21], v[170:173], v[222:225], v[38:41]
	v_mfma_f32_16x16x32_bf16 v[38:41], v[174:177], v[226:229], v[18:21]
	v_mfma_f32_16x16x32_bf16 v[18:21], v[190:193], v[222:225], v[34:37]
	v_mfma_f32_16x16x32_bf16 v[6:9], v[170:173], v[230:233], v[6:9]
	v_mfma_f32_16x16x32_bf16 v[2:5], v[190:193], v[230:233], v[2:5]
	v_mfma_f32_16x16x32_bf16 v[34:37], v[194:197], v[226:229], v[18:21]
	v_mfma_f32_16x16x32_bf16 v[6:9], v[174:177], v[234:237], v[6:9]
	v_mfma_f32_16x16x32_bf16 v[2:5], v[194:197], v[234:237], v[2:5]
	s_setprio 0
	s_waitcnt vmcnt(8)
	s_barrier
	s_add_i32 vcc_hi, vcc_hi, 2
	s_add_u32 s72, s72, 0x100
	s_addc_u32 s73, s73, 0
	s_add_u32 s65, s65, 0x100
	s_addc_u32 vcc_lo, vcc_lo, 0
	s_cmp_gt_u32 vcc_hi, 13
	s_cbranch_scc0 .LBB0_945
	s_and_b64 vcc, exec, s[4:5]
	s_cbranch_vccz .LBB0_948
	s_barrier

; #define PG8_STAGE(bufoff, gbase, voff) do { _Pragma("unroll") for (int _i = 0; _i < 2; ++_i) \
;         __builtin_amdgcn_global_load_lds((const unsigned*)((const char*)(gbase) + (voff)[_i]), (LAS unsigned*)(lds + (bufoff) + ldsw + _i * 8192), 16, 0, 0); } while (0)
; #define PG8_LDA(dst, b, h) do { _Pragma("unroll") for (int m = 0; m < 4; ++m) _Pragma("unroll") for (int k = 0; k < 2; ++k) dst[m][k] = *(const LAS bf16x8*)(lds + PG8_SA(b, h) + aoff + m * 2048 + k * 1024); } while (0)
; #define PG8_LDB(dst, b, h) do { _Pragma("unroll") for (int n = 0; n < 2; ++n) _Pragma("unroll") for (int k = 0; k < 2; ++k) dst[n][k] = *(const LAS bf16x8*)(lds + PG8_SB(b, h) + boff + n * 2048 + k * 1024); } while (0)
; #define PG8_MMA(ai, bj, At, Bt) do { __builtin_amdgcn_s_setprio(1); _Pragma("unroll") for (int m = 0; m < 4; ++m) _Pragma("unroll") for (int n = 0; n < 2; ++n) _Pragma("unroll") for (int k = 0; k < 2; ++k) \
;         acc[ai][bj][m][n] = __builtin_amdgcn_mfma_f32_16x16x32_bf16(Bt[n][k], At[m][k], acc[ai][bj][m][n], 0, 0, 0); __builtin_amdgcn_s_setprio(0); } while (0)
; #define PG8_WAIT_V(n) asm volatile("s_waitcnt vmcnt(" #n ")" ::: "memory")
; #define PG8_WAIT_L(n) asm volatile("s_waitcnt lgkmcnt(" #n ")" ::: "memory")
; #define PG8_BAR __builtin_amdgcn_s_barrier()
; #define PG8_SCHED __builtin_amdgcn_sched_barrier(0)
; template <class Epi>
; __device__ __forceinline__ void gemm_phase(LAS unsigned char* lds, const int tid, const Gemm g, const StaticOrder& S, const Epi& E) {
;     ...
;             PG8_LDB(B0, 0, 0); PG8_LDB(B1, 0, 1); PG8_SCHED; PG8_LDA(At, 0, 0); PG8_STAGE(PG8_SA(1, 1), a1 + hstepA, voffA);
;             PG8_WAIT_V(8); PG8_WAIT_L(0); PG8_BAR; PG8_MMA(0, 0, At, B0); PG8_MMA(0, 1, At, B1); PG8_BAR; PG8_SCHED;
;             PG8_LDA(At, 0, 1); PG8_STAGE(PG8_SB(0, 0), b2, voffB); PG8_STAGE(PG8_SB(0, 1), b2 + hstepB, voffB); PG8_STAGE(PG8_SA(0, 0), a2, voffA);
.LBB0_1284:
	s_add_u32 s2, s66, 0xfff80080
	s_addc_u32 s3, s67, -1
	s_add_i32 vcc_hi, 0, 0x10000
	s_cmp_eq_u32 vcc_lo, 12
	s_cselect_b32 s69, s11, s3
	s_cselect_b32 s68, s88, s2
	v_add_u32_e32 v144, vcc_hi, v171
	s_cselect_b32 s31, s9, s93
	s_cselect_b32 s30, s89, s92
	s_add_i32 s0, 0, 0x14000
	ds_read_b128 v[140:143], v144
	ds_read_b128 v[176:179], v144 offset:1024
	ds_read_b128 v[180:183], v144 offset:2048
	ds_read_b128 v[184:187], v144 offset:3072
	v_add_u32_e32 v144, s0, v171
	ds_read_b128 v[188:191], v144
	ds_read_b128 v[192:195], v144 offset:1024
	ds_read_b128 v[196:199], v144 offset:2048
	ds_read_b128 v[200:203], v144 offset:3072
	v_lshl_add_u64 v[144:145], s[66:67], 0, v[136:137]
	s_add_i32 m0, s71, 0xc000
	s_nop 0
	global_load_lds_dwordx4 v[144:145], off
	v_lshl_add_u64 v[144:145], s[66:67], 0, v[138:139]
	s_add_i32 m0, s71, 0xe000
	s_nop 0
	global_load_lds_dwordx4 v[144:145], off
	ds_read_b128 v[210:213], v174
	ds_read_b128 v[214:217], v174 offset:1024
	ds_read_b128 v[218:221], v174 offset:2048
	ds_read_b128 v[222:225], v174 offset:3072
	ds_read_b128 v[226:229], v174 offset:4096
	ds_read_b128 v[230:233], v174 offset:5120
	ds_read_b128 v[234:237], v174 offset:6144
	ds_read_b128 v[238:241], v174 offset:7168
	s_cmp_lg_u64 s[6:7], 0
	s_cbranch_scc1 .Lkw_28
	s_waitcnt vmcnt(8)
.Lkw_28:
	s_waitcnt lgkmcnt(0)
	s_barrier
	s_setprio 1
	s_waitcnt lgkmcnt(0)
	v_mfma_f32_16x16x32_bf16 v[126:129], v[140:143], v[210:213], v[126:129]
	v_mfma_f32_16x16x32_bf16 v[122:125], v[180:183], v[210:213], v[122:125]
	v_mfma_f32_16x16x32_bf16 v[118:121], v[140:143], v[218:221], v[118:121]
	v_mfma_f32_16x16x32_bf16 v[110:113], v[180:183], v[218:221], v[110:113]
	v_mfma_f32_16x16x32_bf16 v[94:97], v[140:143], v[226:229], v[94:97]
	v_mfma_f32_16x16x32_bf16 v[90:93], v[180:183], v[226:229], v[90:93]
	v_mfma_f32_16x16x32_bf16 v[86:89], v[140:143], v[234:237], v[86:89]
	v_mfma_f32_16x16x32_bf16 v[78:81], v[180:183], v[234:237], v[78:81]
	v_mfma_f32_16x16x32_bf16 v[126:129], v[176:179], v[214:217], v[126:129]
	v_mfma_f32_16x16x32_bf16 v[122:125], v[184:187], v[214:217], v[122:125]
	v_mfma_f32_16x16x32_bf16 v[118:121], v[176:179], v[222:225], v[118:121]
	v_mfma_f32_16x16x32_bf16 v[110:113], v[184:187], v[222:225], v[110:113]
	v_mfma_f32_16x16x32_bf16 v[94:97], v[176:179], v[230:233], v[94:97]
	v_mfma_f32_16x16x32_bf16 v[90:93], v[184:187], v[230:233], v[90:93]
	v_mfma_f32_16x16x32_bf16 v[86:89], v[176:179], v[238:241], v[86:89]
	v_mfma_f32_16x16x32_bf16 v[78:81], v[184:187], v[238:241], v[78:81]
	s_setprio 0
	s_setprio 1
	v_mfma_f32_16x16x32_bf16 v[114:117], v[188:191], v[210:213], v[114:117]
	v_mfma_f32_16x16x32_bf16 v[106:109], v[196:199], v[210:213], v[106:109]
	v_mfma_f32_16x16x32_bf16 v[102:105], v[188:191], v[218:221], v[102:105]
	v_mfma_f32_16x16x32_bf16 v[98:101], v[196:199], v[218:221], v[98:101]
	v_mfma_f32_16x16x32_bf16 v[82:85], v[188:191], v[226:229], v[82:85]
	v_mfma_f32_16x16x32_bf16 v[74:77], v[196:199], v[226:229], v[74:77]
	v_mfma_f32_16x16x32_bf16 v[70:73], v[188:191], v[234:237], v[70:73]
	v_mfma_f32_16x16x32_bf16 v[66:69], v[196:199], v[234:237], v[66:69]
	v_mfma_f32_16x16x32_bf16 v[114:117], v[192:195], v[214:217], v[114:117]
	v_mfma_f32_16x16x32_bf16 v[106:109], v[200:203], v[214:217], v[106:109]
	v_mfma_f32_16x16x32_bf16 v[102:105], v[192:195], v[222:225], v[102:105]
	v_mfma_f32_16x16x32_bf16 v[98:101], v[200:203], v[222:225], v[98:101]
	v_mfma_f32_16x16x32_bf16 v[82:85], v[192:195], v[230:233], v[82:85]
	v_mfma_f32_16x16x32_bf16 v[74:77], v[200:203], v[230:233], v[74:77]
	v_mfma_f32_16x16x32_bf16 v[70:73], v[192:195], v[238:241], v[70:73]
	v_mfma_f32_16x16x32_bf16 v[66:69], v[200:203], v[238:241], v[66:69]
	s_setprio 0
	s_waitcnt vmcnt(8)
	s_barrier
	s_add_i32 s1, vcc_hi, s28
	v_lshl_add_u64 v[144:145], s[30:31], 0, v[0:1]
	s_mov_b32 m0, s1
	s_nop 0
	global_load_lds_dwordx4 v[144:145], off
	s_add_i32 m0, s1, 0x2000
	s_add_u32 s2, s30, 0x40000
	v_lshl_add_u64 v[162:163], s[30:31], 0, v[130:131]
	s_addc_u32 s3, s31, 0
	s_add_i32 s0, s0, s28
	global_load_lds_dwordx4 v[162:163], off
	v_lshl_add_u64 v[164:165], s[2:3], 0, v[0:1]
	s_mov_b32 m0, s0
	v_lshl_add_u64 v[206:207], s[68:69], 0, v[132:133]
	global_load_lds_dwordx4 v[164:165], off
	v_lshl_add_u64 v[164:165], s[2:3], 0, v[130:131]
	s_add_i32 m0, s0, 0x2000
	s_nop 0
	global_load_lds_dwordx4 v[164:165], off
	v_lshl_add_u64 v[164:165], s[68:69], 0, v[134:135]
	s_mov_b32 m0, s71
	s_nop 0
	global_load_lds_dwordx4 v[164:165], off
	s_mov_b32 m0, s72
	s_nop 0
	global_load_lds_dwordx4 v[206:207], off
	ds_read_b128 v[210:213], v174 offset:16384
	ds_read_b128 v[214:217], v174 offset:17408
	ds_read_b128 v[218:221], v174 offset:18432
	ds_read_b128 v[222:225], v174 offset:19456
	ds_read_b128 v[226:229], v174 offset:20480
	ds_read_b128 v[230:233], v174 offset:21504
	ds_read_b128 v[234:237], v174 offset:22528
	ds_read_b128 v[238:241], v174 offset:23552
	s_cmp_lg_u64 s[6:7], 0
	s_cbranch_scc1 .Lkw_27
	s_waitcnt vmcnt(8)
; #define PG8_STAGE(bufoff, gbase, voff) do { _Pragma("unroll") for (int _i = 0; _i < 2; ++_i) \
;         __builtin_amdgcn_global_load_lds((const unsigned*)((const char*)(gbase) + (voff)[_i]), (LAS unsigned*)(lds + (bufoff) + ldsw + _i * 8192), 16, 0, 0); } while (0)
; #define PG8_LDA(dst, b, h) do { _Pragma("unroll") for (int m = 0; m < 4; ++m) _Pragma("unroll") for (int k = 0; k < 2; ++k) dst[m][k] = *(const LAS bf16x8*)(lds + PG8_SA(b, h) + aoff + m * 2048 + k * 1024); } while (0)
; #define PG8_LDB(dst, b, h) do { _Pragma("unroll") for (int n = 0; n < 2; ++n) _Pragma("unroll") for (int k = 0; k < 2; ++k) dst[n][k] = *(const LAS bf16x8*)(lds + PG8_SB(b, h) + boff + n * 2048 + k * 1024); } while (0)
; #define PG8_MMA(ai, bj, At, Bt) do { __builtin_amdgcn_s_setprio(1); _Pragma("unroll") for (int m = 0; m < 4; ++m) _Pragma("unroll") for (int n = 0; n < 2; ++n) _Pragma("unroll") for (int k = 0; k < 2; ++k) \
;         acc[ai][bj][m][n] = __builtin_amdgcn_mfma_f32_16x16x32_bf16(Bt[n][k], At[m][k], acc[ai][bj][m][n], 0, 0, 0); __builtin_amdgcn_s_setprio(0); } while (0)
; #define PG8_WAIT_V(n) asm volatile("s_waitcnt vmcnt(" #n ")" ::: "memory")
; #define PG8_WAIT_L(n) asm volatile("s_waitcnt lgkmcnt(" #n ")" ::: "memory")
; #define PG8_BAR __builtin_amdgcn_s_barrier()
; #define PG8_SCHED __builtin_amdgcn_sched_barrier(0)
; template <class Epi>
; __device__ __forceinline__ void gemm_phase(LAS unsigned char* lds, const int tid, const Gemm g, const StaticOrder& S, const Epi& E) {
;     ...
;             PG8_LDA(At, 0, 1); PG8_STAGE(PG8_SB(0, 0), b2, voffB); PG8_STAGE(PG8_SB(0, 1), b2 + hstepB, voffB); PG8_STAGE(PG8_SA(0, 0), a2, voffA);
;             PG8_WAIT_V(8); PG8_WAIT_L(0); PG8_BAR; PG8_MMA(1, 0, At, B0); PG8_MMA(1, 1, At, B1); PG8_BAR; PG8_SCHED;
;             PG8_LDB(B0, 1, 0); PG8_LDB(B1, 1, 1); PG8_SCHED; PG8_LDA(At, 1, 0); PG8_STAGE(PG8_SA(0, 1), a2 + hstepA, voffA);
;             PG8_WAIT_V(8); PG8_WAIT_L(0); PG8_BAR; PG8_MMA(0, 0, At, B0); PG8_MMA(0, 1, At, B1); PG8_BAR; PG8_SCHED;
.Lkw_27:
	s_waitcnt lgkmcnt(0)
	s_barrier
	s_setprio 1
	s_waitcnt lgkmcnt(0)
	v_mfma_f32_16x16x32_bf16 v[62:65], v[140:143], v[210:213], v[62:65]
	v_mfma_f32_16x16x32_bf16 v[58:61], v[180:183], v[210:213], v[58:61]
	v_mfma_f32_16x16x32_bf16 v[54:57], v[140:143], v[218:221], v[54:57]
	v_mfma_f32_16x16x32_bf16 v[46:49], v[180:183], v[218:221], v[46:49]
	v_mfma_f32_16x16x32_bf16 v[30:33], v[140:143], v[226:229], v[30:33]
	v_mfma_f32_16x16x32_bf16 v[26:29], v[180:183], v[226:229], v[26:29]
	v_mfma_f32_16x16x32_bf16 v[22:25], v[140:143], v[234:237], v[22:25]
	v_mfma_f32_16x16x32_bf16 v[14:17], v[180:183], v[234:237], v[14:17]
	v_mfma_f32_16x16x32_bf16 v[62:65], v[176:179], v[214:217], v[62:65]
	v_mfma_f32_16x16x32_bf16 v[58:61], v[184:187], v[214:217], v[58:61]
	v_mfma_f32_16x16x32_bf16 v[54:57], v[176:179], v[222:225], v[54:57]
	v_mfma_f32_16x16x32_bf16 v[46:49], v[184:187], v[222:225], v[46:49]
	v_mfma_f32_16x16x32_bf16 v[30:33], v[176:179], v[230:233], v[30:33]
	v_mfma_f32_16x16x32_bf16 v[26:29], v[184:187], v[230:233], v[26:29]
	v_mfma_f32_16x16x32_bf16 v[22:25], v[176:179], v[238:241], v[22:25]
	v_mfma_f32_16x16x32_bf16 v[14:17], v[184:187], v[238:241], v[14:17]
	s_setprio 0
	s_setprio 1
	v_mfma_f32_16x16x32_bf16 v[50:53], v[188:191], v[210:213], v[50:53]
	v_mfma_f32_16x16x32_bf16 v[42:45], v[196:199], v[210:213], v[42:45]
	v_mfma_f32_16x16x32_bf16 v[38:41], v[188:191], v[218:221], v[38:41]
	v_mfma_f32_16x16x32_bf16 v[34:37], v[196:199], v[218:221], v[34:37]
	v_mfma_f32_16x16x32_bf16 v[18:21], v[188:191], v[226:229], v[18:21]
	v_mfma_f32_16x16x32_bf16 v[10:13], v[196:199], v[226:229], v[10:13]
	v_mfma_f32_16x16x32_bf16 v[6:9], v[188:191], v[234:237], v[6:9]
	v_mfma_f32_16x16x32_bf16 v[2:5], v[196:199], v[234:237], v[2:5]
	v_mfma_f32_16x16x32_bf16 v[50:53], v[192:195], v[214:217], v[50:53]
	v_mfma_f32_16x16x32_bf16 v[42:45], v[200:203], v[214:217], v[42:45]
	v_mfma_f32_16x16x32_bf16 v[38:41], v[192:195], v[222:225], v[38:41]
	v_mfma_f32_16x16x32_bf16 v[34:37], v[200:203], v[222:225], v[34:37]
	v_mfma_f32_16x16x32_bf16 v[18:21], v[192:195], v[230:233], v[18:21]
	v_mfma_f32_16x16x32_bf16 v[10:13], v[200:203], v[230:233], v[10:13]
	v_mfma_f32_16x16x32_bf16 v[6:9], v[192:195], v[238:241], v[6:9]
	v_mfma_f32_16x16x32_bf16 v[2:5], v[200:203], v[238:241], v[2:5]
	s_setprio 0
	s_waitcnt vmcnt(8)
	s_barrier
	s_add_i32 s0, 0, 0x18000
	v_add_u32_e32 v175, s0, v171
	s_add_i32 s1, 0, 0x1c000
	ds_read_b128 v[140:143], v175
	ds_read_b128 v[176:179], v175 offset:1024
	ds_read_b128 v[180:183], v175 offset:2048
	ds_read_b128 v[184:187], v175 offset:3072
	v_add_u32_e32 v175, s1, v171
	ds_read_b128 v[188:191], v175
	ds_read_b128 v[192:195], v175 offset:1024
	ds_read_b128 v[196:199], v175 offset:2048
	ds_read_b128 v[200:203], v175 offset:3072
	s_add_u32 s2, s68, 0x80000
	s_addc_u32 s3, s69, 0
	s_mov_b32 m0, s73
	v_lshl_add_u64 v[242:243], s[2:3], 0, v[134:135]
	global_load_lds_dwordx4 v[242:243], off
	v_lshl_add_u64 v[242:243], s[2:3], 0, v[132:133]
	s_mov_b32 m0, s74
	s_nop 0
	global_load_lds_dwordx4 v[242:243], off
	ds_read_b128 v[210:213], v174 offset:32768
	ds_read_b128 v[214:217], v174 offset:33792
	ds_read_b128 v[218:221], v174 offset:34816
	ds_read_b128 v[222:225], v174 offset:35840
	ds_read_b128 v[226:229], v174 offset:36864
	ds_read_b128 v[230:233], v174 offset:37888
	ds_read_b128 v[234:237], v174 offset:38912
	ds_read_b128 v[238:241], v174 offset:39936
	s_cmp_lg_u64 s[6:7], 0
	s_cbranch_scc1 .Lkw_26
	s_waitcnt vmcnt(8)
; #define PG8_STAGE(bufoff, gbase, voff) do { _Pragma("unroll") for (int _i = 0; _i < 2; ++_i) \
;         __builtin_amdgcn_global_load_lds((const unsigned*)((const char*)(gbase) + (voff)[_i]), (LAS unsigned*)(lds + (bufoff) + ldsw + _i * 8192), 16, 0, 0); } while (0)
; #define PG8_LDA(dst, b, h) do { _Pragma("unroll") for (int m = 0; m < 4; ++m) _Pragma("unroll") for (int k = 0; k < 2; ++k) dst[m][k] = *(const LAS bf16x8*)(lds + PG8_SA(b, h) + aoff + m * 2048 + k * 1024); } while (0)
; #define PG8_MMA(ai, bj, At, Bt) do { __builtin_amdgcn_s_setprio(1); _Pragma("unroll") for (int m = 0; m < 4; ++m) _Pragma("unroll") for (int n = 0; n < 2; ++n) _Pragma("unroll") for (int k = 0; k < 2; ++k) \
;         acc[ai][bj][m][n] = __builtin_amdgcn_mfma_f32_16x16x32_bf16(Bt[n][k], At[m][k], acc[ai][bj][m][n], 0, 0, 0); __builtin_amdgcn_s_setprio(0); } while (0)
; #define PG8_WAIT_V(n) asm volatile("s_waitcnt vmcnt(" #n ")" ::: "memory")
; #define PG8_WAIT_L(n) asm volatile("s_waitcnt lgkmcnt(" #n ")" ::: "memory")
; #define PG8_BAR __builtin_amdgcn_s_barrier()
; #define PG8_SCHED __builtin_amdgcn_sched_barrier(0)
; template <class Epi>
; __device__ __forceinline__ void gemm_phase(LAS unsigned char* lds, const int tid, const Gemm g, const StaticOrder& S, const Epi& E) {
;     ...
;             PG8_WAIT_V(8); PG8_WAIT_L(0); PG8_BAR; PG8_MMA(0, 0, At, B0); PG8_MMA(0, 1, At, B1); PG8_BAR; PG8_SCHED;
;             PG8_LDA(At, 1, 1); PG8_STAGE(PG8_SB(1, 0), b3, voffB); PG8_STAGE(PG8_SB(1, 1), b3 + hstepB, voffB); PG8_STAGE(PG8_SA(1, 0), a3, voffA);
;             PG8_WAIT_V(8); PG8_WAIT_L(0); PG8_BAR; PG8_MMA(1, 0, At, B0); PG8_MMA(1, 1, At, B1); PG8_BAR; PG8_SCHED;
;         }
;         if (wr == 0) PG8_BAR;
.Lkw_26:
	s_waitcnt lgkmcnt(0)
	s_barrier
	s_setprio 1
	s_waitcnt lgkmcnt(0)
	v_mfma_f32_16x16x32_bf16 v[126:129], v[140:143], v[210:213], v[126:129]
	v_mfma_f32_16x16x32_bf16 v[122:125], v[180:183], v[210:213], v[122:125]
	v_mfma_f32_16x16x32_bf16 v[118:121], v[140:143], v[218:221], v[118:121]
	v_mfma_f32_16x16x32_bf16 v[110:113], v[180:183], v[218:221], v[110:113]
	v_mfma_f32_16x16x32_bf16 v[94:97], v[140:143], v[226:229], v[94:97]
	v_mfma_f32_16x16x32_bf16 v[90:93], v[180:183], v[226:229], v[90:93]
	v_mfma_f32_16x16x32_bf16 v[86:89], v[140:143], v[234:237], v[86:89]
	v_mfma_f32_16x16x32_bf16 v[78:81], v[180:183], v[234:237], v[78:81]
	v_mfma_f32_16x16x32_bf16 v[126:129], v[176:179], v[214:217], v[126:129]
	v_mfma_f32_16x16x32_bf16 v[122:125], v[184:187], v[214:217], v[122:125]
	v_mfma_f32_16x16x32_bf16 v[118:121], v[176:179], v[222:225], v[118:121]
	v_mfma_f32_16x16x32_bf16 v[110:113], v[184:187], v[222:225], v[110:113]
	v_mfma_f32_16x16x32_bf16 v[94:97], v[176:179], v[230:233], v[94:97]
	v_mfma_f32_16x16x32_bf16 v[90:93], v[184:187], v[230:233], v[90:93]
	v_mfma_f32_16x16x32_bf16 v[86:89], v[176:179], v[238:241], v[86:89]
	v_mfma_f32_16x16x32_bf16 v[78:81], v[184:187], v[238:241], v[78:81]
	s_setprio 0
	s_setprio 1
	v_mfma_f32_16x16x32_bf16 v[114:117], v[188:191], v[210:213], v[114:117]
	v_mfma_f32_16x16x32_bf16 v[106:109], v[196:199], v[210:213], v[106:109]
	v_mfma_f32_16x16x32_bf16 v[102:105], v[188:191], v[218:221], v[102:105]
	v_mfma_f32_16x16x32_bf16 v[98:101], v[196:199], v[218:221], v[98:101]
	v_mfma_f32_16x16x32_bf16 v[82:85], v[188:191], v[226:229], v[82:85]
	v_mfma_f32_16x16x32_bf16 v[74:77], v[196:199], v[226:229], v[74:77]
	v_mfma_f32_16x16x32_bf16 v[70:73], v[188:191], v[234:237], v[70:73]
	v_mfma_f32_16x16x32_bf16 v[66:69], v[196:199], v[234:237], v[66:69]
	v_mfma_f32_16x16x32_bf16 v[114:117], v[192:195], v[214:217], v[114:117]
	v_mfma_f32_16x16x32_bf16 v[106:109], v[200:203], v[214:217], v[106:109]
	v_mfma_f32_16x16x32_bf16 v[102:105], v[192:195], v[222:225], v[102:105]
	v_mfma_f32_16x16x32_bf16 v[98:101], v[200:203], v[222:225], v[98:101]
	v_mfma_f32_16x16x32_bf16 v[82:85], v[192:195], v[230:233], v[82:85]
	v_mfma_f32_16x16x32_bf16 v[74:77], v[200:203], v[230:233], v[74:77]
	v_mfma_f32_16x16x32_bf16 v[70:73], v[192:195], v[238:241], v[70:73]
	v_mfma_f32_16x16x32_bf16 v[66:69], v[200:203], v[238:241], v[66:69]
	s_setprio 0
	s_waitcnt vmcnt(8)
	s_barrier
	s_add_i32 s0, s0, s28
	v_lshl_add_u64 v[144:145], v[144:145], 0, s[36:37]
	s_mov_b32 m0, s0
	s_nop 0
	global_load_lds_dwordx4 v[144:145], off
	s_add_i32 m0, s0, 0x2000
	s_add_u32 s2, s30, 0x40080
	v_lshl_add_u64 v[144:145], v[162:163], 0, s[36:37]
	s_addc_u32 s3, s31, 0
	s_add_i32 s0, s1, s28
	global_load_lds_dwordx4 v[144:145], off
	v_lshl_add_u64 v[144:145], s[2:3], 0, v[0:1]
	s_mov_b32 m0, s0
	s_nop 0
	global_load_lds_dwordx4 v[144:145], off
	v_lshl_add_u64 v[144:145], s[2:3], 0, v[130:131]
	s_add_i32 m0, s0, 0x2000
	s_nop 0
	global_load_lds_dwordx4 v[144:145], off
	v_lshl_add_u64 v[144:145], v[164:165], 0, s[36:37]
	s_mov_b32 m0, s75
	s_nop 0
	global_load_lds_dwordx4 v[144:145], off
	v_lshl_add_u64 v[144:145], v[206:207], 0, s[36:37]
	s_mov_b32 m0, s76
	s_nop 0
	global_load_lds_dwordx4 v[144:145], off
	ds_read_b128 v[210:213], v174 offset:49152
	ds_read_b128 v[214:217], v174 offset:50176
	ds_read_b128 v[218:221], v174 offset:51200
	ds_read_b128 v[222:225], v174 offset:52224
	ds_read_b128 v[226:229], v174 offset:53248
	ds_read_b128 v[230:233], v174 offset:54272
	ds_read_b128 v[234:237], v174 offset:55296
	ds_read_b128 v[238:241], v174 offset:56320
	s_cmp_lg_u64 s[6:7], 0
	s_cbranch_scc1 .Lkw_25
	s_waitcnt vmcnt(8)
.Lkw_25:
	s_waitcnt lgkmcnt(0)
	s_barrier
	s_setprio 1
	s_waitcnt lgkmcnt(0)
	v_mfma_f32_16x16x32_bf16 v[62:65], v[140:143], v[210:213], v[62:65]
	v_mfma_f32_16x16x32_bf16 v[58:61], v[180:183], v[210:213], v[58:61]
	v_mfma_f32_16x16x32_bf16 v[54:57], v[140:143], v[218:221], v[54:57]
	v_mfma_f32_16x16x32_bf16 v[46:49], v[180:183], v[218:221], v[46:49]
	v_mfma_f32_16x16x32_bf16 v[30:33], v[140:143], v[226:229], v[30:33]
	v_mfma_f32_16x16x32_bf16 v[26:29], v[180:183], v[226:229], v[26:29]
	v_mfma_f32_16x16x32_bf16 v[22:25], v[140:143], v[234:237], v[22:25]
	v_mfma_f32_16x16x32_bf16 v[14:17], v[180:183], v[234:237], v[14:17]
	v_mfma_f32_16x16x32_bf16 v[62:65], v[176:179], v[214:217], v[62:65]
	v_mfma_f32_16x16x32_bf16 v[58:61], v[184:187], v[214:217], v[58:61]
	v_mfma_f32_16x16x32_bf16 v[54:57], v[176:179], v[222:225], v[54:57]
	v_mfma_f32_16x16x32_bf16 v[46:49], v[184:187], v[222:225], v[46:49]
	v_mfma_f32_16x16x32_bf16 v[30:33], v[176:179], v[230:233], v[30:33]
	v_mfma_f32_16x16x32_bf16 v[26:29], v[184:187], v[230:233], v[26:29]
	v_mfma_f32_16x16x32_bf16 v[22:25], v[176:179], v[238:241], v[22:25]
	v_mfma_f32_16x16x32_bf16 v[14:17], v[184:187], v[238:241], v[14:17]
	s_setprio 0
	s_setprio 1
	v_mfma_f32_16x16x32_bf16 v[50:53], v[188:191], v[210:213], v[50:53]
	v_mfma_f32_16x16x32_bf16 v[42:45], v[196:199], v[210:213], v[42:45]
	v_mfma_f32_16x16x32_bf16 v[38:41], v[188:191], v[218:221], v[38:41]
	v_mfma_f32_16x16x32_bf16 v[34:37], v[196:199], v[218:221], v[34:37]
	v_mfma_f32_16x16x32_bf16 v[18:21], v[188:191], v[226:229], v[18:21]
	v_mfma_f32_16x16x32_bf16 v[10:13], v[196:199], v[226:229], v[10:13]
	v_mfma_f32_16x16x32_bf16 v[6:9], v[188:191], v[234:237], v[6:9]
	v_mfma_f32_16x16x32_bf16 v[2:5], v[196:199], v[234:237], v[2:5]
	v_mfma_f32_16x16x32_bf16 v[50:53], v[192:195], v[214:217], v[50:53]
	v_mfma_f32_16x16x32_bf16 v[42:45], v[200:203], v[214:217], v[42:45]
	v_mfma_f32_16x16x32_bf16 v[38:41], v[192:195], v[222:225], v[38:41]
	v_mfma_f32_16x16x32_bf16 v[34:37], v[200:203], v[222:225], v[34:37]
	v_mfma_f32_16x16x32_bf16 v[18:21], v[192:195], v[230:233], v[18:21]
	v_mfma_f32_16x16x32_bf16 v[10:13], v[200:203], v[230:233], v[10:13]
	v_mfma_f32_16x16x32_bf16 v[6:9], v[192:195], v[238:241], v[6:9]
	v_mfma_f32_16x16x32_bf16 v[2:5], v[200:203], v[238:241], v[2:5]
	s_setprio 0
	s_waitcnt vmcnt(8)
	s_barrier
	s_add_i32 vcc_lo, vcc_lo, 2
	s_add_u32 s66, s66, 0x100
	s_addc_u32 s67, s67, 0
	s_add_u32 s92, s92, 0x100
	s_addc_u32 s93, s93, 0
	s_cmp_gt_u32 vcc_lo, 13
	s_cbranch_scc0 .LBB0_1284
	s_and_b64 vcc, exec, s[6:7]
	s_mov_b32 s92, 0x2c000
	s_mov_b32 s93, 0x2e000
	s_cbranch_vccz .LBB0_1287
	s_barrier

; #define PG8_STAGE(bufoff, gbase, voff) do { _Pragma("unroll") for (int _i = 0; _i < 2; ++_i) \
;         __builtin_amdgcn_global_load_lds((const unsigned*)((const char*)(gbase) + (voff)[_i]), (LAS unsigned*)(lds + (bufoff) + ldsw + _i * 8192), 16, 0, 0); } while (0)
; #define PG8_LDA(dst, b, h) do { _Pragma("unroll") for (int m = 0; m < 4; ++m) _Pragma("unroll") for (int k = 0; k < 2; ++k) dst[m][k] = *(const LAS bf16x8*)(lds + PG8_SA(b, h) + aoff + m * 2048 + k * 1024); } while (0)
; #define PG8_LDB(dst, b, h) do { _Pragma("unroll") for (int n = 0; n < 2; ++n) _Pragma("unroll") for (int k = 0; k < 2; ++k) dst[n][k] = *(const LAS bf16x8*)(lds + PG8_SB(b, h) + boff + n * 2048 + k * 1024); } while (0)
; #define PG8_MMA(ai, bj, At, Bt) do { __builtin_amdgcn_s_setprio(1); _Pragma("unroll") for (int m = 0; m < 4; ++m) _Pragma("unroll") for (int n = 0; n < 2; ++n) _Pragma("unroll") for (int k = 0; k < 2; ++k) \
;         acc[ai][bj][m][n] = __builtin_amdgcn_mfma_f32_16x16x32_bf16(Bt[n][k], At[m][k], acc[ai][bj][m][n], 0, 0, 0); __builtin_amdgcn_s_setprio(0); } while (0)
; #define PG8_WAIT_V(n) asm volatile("s_waitcnt vmcnt(" #n ")" ::: "memory")
; #define PG8_WAIT_L(n) asm volatile("s_waitcnt lgkmcnt(" #n ")" ::: "memory")
; #define PG8_BAR __builtin_amdgcn_s_barrier()
; #define PG8_SCHED __builtin_amdgcn_sched_barrier(0)
; template <class Epi>
; __device__ __forceinline__ void gemm_phase(LAS unsigned char* lds, const int tid, const Gemm g, const StaticOrder& S, const Epi& E) {
;     ...
;             PG8_LDB(B0, 0, 0); PG8_LDB(B1, 0, 1); PG8_SCHED; PG8_LDA(At, 0, 0); PG8_STAGE(PG8_SA(1, 1), a1 + hstepA, voffA);
;             PG8_WAIT_V(8); PG8_WAIT_L(0); PG8_BAR; PG8_MMA(0, 0, At, B0); PG8_MMA(0, 1, At, B1); PG8_BAR; PG8_SCHED;
;             PG8_LDA(At, 0, 1); PG8_STAGE(PG8_SB(0, 0), b2, voffB); PG8_STAGE(PG8_SB(0, 1), b2 + hstepB, voffB); PG8_STAGE(PG8_SA(0, 0), a2, voffA);
.LBB0_1333:
	s_add_u32 s0, s66, 0xfff80080
	s_addc_u32 s1, s67, -1
	s_add_i32 s2, 0, 0x10000
	s_cmp_eq_u32 vcc_lo, 12
	s_cselect_b32 s69, s11, s1
	s_cselect_b32 s68, s88, s0
	s_cselect_b32 s31, s9, s93
	s_cselect_b32 s30, s89, s92
	s_add_i32 s0, 0, 0x14000
	v_add_u32_e32 v142, s2, v189
	v_add_u32_e32 v162, s0, v189
	ds_read_b128 v[130:133], v142
	ds_read_b128 v[134:137], v142 offset:1024
	ds_read_b128 v[138:141], v142 offset:2048
	ds_read_b128 v[142:145], v142 offset:3072
	ds_read_b128 v[158:161], v162
	ds_read_b128 v[192:195], v162 offset:1024
	ds_read_b128 v[196:199], v162 offset:2048
	ds_read_b128 v[200:203], v162 offset:3072
	v_lshl_add_u64 v[162:163], s[66:67], 0, v[154:155]
	s_add_i32 m0, s71, 0xc000
	s_nop 0
	global_load_lds_dwordx4 v[162:163], off
	v_lshl_add_u64 v[162:163], s[66:67], 0, v[156:157]
	s_add_i32 m0, s71, 0xe000
	s_nop 0
	global_load_lds_dwordx4 v[162:163], off
	ds_read_b128 v[210:213], v191
	ds_read_b128 v[214:217], v191 offset:1024
	ds_read_b128 v[218:221], v191 offset:2048
	ds_read_b128 v[222:225], v191 offset:3072
	ds_read_b128 v[226:229], v191 offset:4096
	ds_read_b128 v[230:233], v191 offset:5120
	ds_read_b128 v[234:237], v191 offset:6144
	ds_read_b128 v[238:241], v191 offset:7168
	s_cmp_lg_u64 s[6:7], 0
	s_cbranch_scc1 .Lkw_24
	s_waitcnt vmcnt(8)
.Lkw_24:
	s_waitcnt lgkmcnt(0)
	s_barrier
	s_setprio 1
	s_waitcnt lgkmcnt(0)
	v_mfma_f32_16x16x32_bf16 v[126:129], v[130:133], v[210:213], v[126:129]
	v_mfma_f32_16x16x32_bf16 v[122:125], v[138:141], v[210:213], v[122:125]
	v_mfma_f32_16x16x32_bf16 v[110:113], v[130:133], v[218:221], v[110:113]
	v_mfma_f32_16x16x32_bf16 v[106:109], v[138:141], v[218:221], v[106:109]
	v_mfma_f32_16x16x32_bf16 v[94:97], v[130:133], v[226:229], v[94:97]
	v_mfma_f32_16x16x32_bf16 v[90:93], v[138:141], v[226:229], v[90:93]
	v_mfma_f32_16x16x32_bf16 v[78:81], v[130:133], v[234:237], v[78:81]
	v_mfma_f32_16x16x32_bf16 v[74:77], v[138:141], v[234:237], v[74:77]
	v_mfma_f32_16x16x32_bf16 v[126:129], v[134:137], v[214:217], v[126:129]
	v_mfma_f32_16x16x32_bf16 v[122:125], v[142:145], v[214:217], v[122:125]
	v_mfma_f32_16x16x32_bf16 v[110:113], v[134:137], v[222:225], v[110:113]
	v_mfma_f32_16x16x32_bf16 v[106:109], v[142:145], v[222:225], v[106:109]
	v_mfma_f32_16x16x32_bf16 v[94:97], v[134:137], v[230:233], v[94:97]
	v_mfma_f32_16x16x32_bf16 v[90:93], v[142:145], v[230:233], v[90:93]
	v_mfma_f32_16x16x32_bf16 v[78:81], v[134:137], v[238:241], v[78:81]
	v_mfma_f32_16x16x32_bf16 v[74:77], v[142:145], v[238:241], v[74:77]
	s_setprio 0
	s_setprio 1
	v_mfma_f32_16x16x32_bf16 v[118:121], v[158:161], v[210:213], v[118:121]
	v_mfma_f32_16x16x32_bf16 v[114:117], v[196:199], v[210:213], v[114:117]
	v_mfma_f32_16x16x32_bf16 v[102:105], v[158:161], v[218:221], v[102:105]
	v_mfma_f32_16x16x32_bf16 v[98:101], v[196:199], v[218:221], v[98:101]
	v_mfma_f32_16x16x32_bf16 v[86:89], v[158:161], v[226:229], v[86:89]
	v_mfma_f32_16x16x32_bf16 v[82:85], v[196:199], v[226:229], v[82:85]
	v_mfma_f32_16x16x32_bf16 v[70:73], v[158:161], v[234:237], v[70:73]
	v_mfma_f32_16x16x32_bf16 v[66:69], v[196:199], v[234:237], v[66:69]
	v_mfma_f32_16x16x32_bf16 v[118:121], v[192:195], v[214:217], v[118:121]
	v_mfma_f32_16x16x32_bf16 v[114:117], v[200:203], v[214:217], v[114:117]
	v_mfma_f32_16x16x32_bf16 v[102:105], v[192:195], v[222:225], v[102:105]
	v_mfma_f32_16x16x32_bf16 v[98:101], v[200:203], v[222:225], v[98:101]
	v_mfma_f32_16x16x32_bf16 v[86:89], v[192:195], v[230:233], v[86:89]
	v_mfma_f32_16x16x32_bf16 v[82:85], v[200:203], v[230:233], v[82:85]
	v_mfma_f32_16x16x32_bf16 v[70:73], v[192:195], v[238:241], v[70:73]
	v_mfma_f32_16x16x32_bf16 v[66:69], v[200:203], v[238:241], v[66:69]
	s_setprio 0
	s_waitcnt vmcnt(8)
	s_barrier
	s_add_i32 s1, s2, s28
	v_lshl_add_u64 v[162:163], s[30:31], 0, v[0:1]
	s_mov_b32 m0, s1
	s_nop 0
	global_load_lds_dwordx4 v[162:163], off
	s_add_i32 m0, s1, 0x2000
	s_add_u32 s2, s30, 0x40000
	v_lshl_add_u64 v[164:165], s[30:31], 0, v[148:149]
	s_addc_u32 s3, s31, 0
	s_add_i32 s0, s0, s28
	global_load_lds_dwordx4 v[164:165], off
	v_lshl_add_u64 v[170:171], s[2:3], 0, v[0:1]
	s_mov_b32 m0, s0
	v_lshl_add_u64 v[206:207], s[68:69], 0, v[150:151]
	global_load_lds_dwordx4 v[170:171], off
	v_lshl_add_u64 v[170:171], s[2:3], 0, v[148:149]
	s_add_i32 m0, s0, 0x2000
	s_nop 0
	global_load_lds_dwordx4 v[170:171], off
	v_lshl_add_u64 v[170:171], s[68:69], 0, v[152:153]
	s_mov_b32 m0, s71
	s_nop 0
	global_load_lds_dwordx4 v[170:171], off
	s_mov_b32 m0, s72
	s_nop 0
	global_load_lds_dwordx4 v[206:207], off
	ds_read_b128 v[210:213], v191 offset:16384
	ds_read_b128 v[214:217], v191 offset:17408
	ds_read_b128 v[218:221], v191 offset:18432
	ds_read_b128 v[222:225], v191 offset:19456
	ds_read_b128 v[226:229], v191 offset:20480
	ds_read_b128 v[230:233], v191 offset:21504
	ds_read_b128 v[234:237], v191 offset:22528
	ds_read_b128 v[238:241], v191 offset:23552
	s_cmp_lg_u64 s[6:7], 0
	s_cbranch_scc1 .Lkw_23
	s_waitcnt vmcnt(8)
; #define PG8_STAGE(bufoff, gbase, voff) do { _Pragma("unroll") for (int _i = 0; _i < 2; ++_i) \
;         __builtin_amdgcn_global_load_lds((const unsigned*)((const char*)(gbase) + (voff)[_i]), (LAS unsigned*)(lds + (bufoff) + ldsw + _i * 8192), 16, 0, 0); } while (0)
; #define PG8_LDA(dst, b, h) do { _Pragma("unroll") for (int m = 0; m < 4; ++m) _Pragma("unroll") for (int k = 0; k < 2; ++k) dst[m][k] = *(const LAS bf16x8*)(lds + PG8_SA(b, h) + aoff + m * 2048 + k * 1024); } while (0)
; #define PG8_LDB(dst, b, h) do { _Pragma("unroll") for (int n = 0; n < 2; ++n) _Pragma("unroll") for (int k = 0; k < 2; ++k) dst[n][k] = *(const LAS bf16x8*)(lds + PG8_SB(b, h) + boff + n * 2048 + k * 1024); } while (0)
; #define PG8_MMA(ai, bj, At, Bt) do { __builtin_amdgcn_s_setprio(1); _Pragma("unroll") for (int m = 0; m < 4; ++m) _Pragma("unroll") for (int n = 0; n < 2; ++n) _Pragma("unroll") for (int k = 0; k < 2; ++k) \
;         acc[ai][bj][m][n] = __builtin_amdgcn_mfma_f32_16x16x32_bf16(Bt[n][k], At[m][k], acc[ai][bj][m][n], 0, 0, 0); __builtin_amdgcn_s_setprio(0); } while (0)
; #define PG8_WAIT_V(n) asm volatile("s_waitcnt vmcnt(" #n ")" ::: "memory")
; #define PG8_WAIT_L(n) asm volatile("s_waitcnt lgkmcnt(" #n ")" ::: "memory")
; #define PG8_BAR __builtin_amdgcn_s_barrier()
; #define PG8_SCHED __builtin_amdgcn_sched_barrier(0)
; template <class Epi>
; __device__ __forceinline__ void gemm_phase(LAS unsigned char* lds, const int tid, const Gemm g, const StaticOrder& S, const Epi& E) {
;     ...
;             PG8_LDA(At, 0, 1); PG8_STAGE(PG8_SB(0, 0), b2, voffB); PG8_STAGE(PG8_SB(0, 1), b2 + hstepB, voffB); PG8_STAGE(PG8_SA(0, 0), a2, voffA);
;             PG8_WAIT_V(8); PG8_WAIT_L(0); PG8_BAR; PG8_MMA(1, 0, At, B0); PG8_MMA(1, 1, At, B1); PG8_BAR; PG8_SCHED;
;             PG8_LDB(B0, 1, 0); PG8_LDB(B1, 1, 1); PG8_SCHED; PG8_LDA(At, 1, 0); PG8_STAGE(PG8_SA(0, 1), a2 + hstepA, voffA);
;             PG8_WAIT_V(8); PG8_WAIT_L(0); PG8_BAR; PG8_MMA(0, 0, At, B0); PG8_MMA(0, 1, At, B1); PG8_BAR; PG8_SCHED;
.Lkw_23:
	s_waitcnt lgkmcnt(0)
	s_barrier
	s_setprio 1
	s_waitcnt lgkmcnt(0)
	v_mfma_f32_16x16x32_bf16 v[62:65], v[130:133], v[210:213], v[62:65]
	v_mfma_f32_16x16x32_bf16 v[58:61], v[138:141], v[210:213], v[58:61]
	v_mfma_f32_16x16x32_bf16 v[46:49], v[130:133], v[218:221], v[46:49]
	v_mfma_f32_16x16x32_bf16 v[42:45], v[138:141], v[218:221], v[42:45]
	v_mfma_f32_16x16x32_bf16 v[30:33], v[130:133], v[226:229], v[30:33]
	v_mfma_f32_16x16x32_bf16 v[26:29], v[138:141], v[226:229], v[26:29]
	v_mfma_f32_16x16x32_bf16 v[14:17], v[130:133], v[234:237], v[14:17]
	v_mfma_f32_16x16x32_bf16 v[10:13], v[138:141], v[234:237], v[10:13]
	v_mfma_f32_16x16x32_bf16 v[62:65], v[134:137], v[214:217], v[62:65]
	v_mfma_f32_16x16x32_bf16 v[58:61], v[142:145], v[214:217], v[58:61]
	v_mfma_f32_16x16x32_bf16 v[46:49], v[134:137], v[222:225], v[46:49]
	v_mfma_f32_16x16x32_bf16 v[42:45], v[142:145], v[222:225], v[42:45]
	v_mfma_f32_16x16x32_bf16 v[30:33], v[134:137], v[230:233], v[30:33]
	v_mfma_f32_16x16x32_bf16 v[26:29], v[142:145], v[230:233], v[26:29]
	v_mfma_f32_16x16x32_bf16 v[14:17], v[134:137], v[238:241], v[14:17]
	v_mfma_f32_16x16x32_bf16 v[10:13], v[142:145], v[238:241], v[10:13]
	s_setprio 0
	s_setprio 1
	v_mfma_f32_16x16x32_bf16 v[54:57], v[158:161], v[210:213], v[54:57]
	v_mfma_f32_16x16x32_bf16 v[50:53], v[196:199], v[210:213], v[50:53]
	v_mfma_f32_16x16x32_bf16 v[38:41], v[158:161], v[218:221], v[38:41]
	v_mfma_f32_16x16x32_bf16 v[34:37], v[196:199], v[218:221], v[34:37]
	v_mfma_f32_16x16x32_bf16 v[22:25], v[158:161], v[226:229], v[22:25]
	v_mfma_f32_16x16x32_bf16 v[18:21], v[196:199], v[226:229], v[18:21]
	v_mfma_f32_16x16x32_bf16 v[6:9], v[158:161], v[234:237], v[6:9]
	v_mfma_f32_16x16x32_bf16 v[2:5], v[196:199], v[234:237], v[2:5]
	v_mfma_f32_16x16x32_bf16 v[54:57], v[192:195], v[214:217], v[54:57]
	v_mfma_f32_16x16x32_bf16 v[50:53], v[200:203], v[214:217], v[50:53]
	v_mfma_f32_16x16x32_bf16 v[38:41], v[192:195], v[222:225], v[38:41]
	v_mfma_f32_16x16x32_bf16 v[34:37], v[200:203], v[222:225], v[34:37]
	v_mfma_f32_16x16x32_bf16 v[22:25], v[192:195], v[230:233], v[22:25]
	v_mfma_f32_16x16x32_bf16 v[18:21], v[200:203], v[230:233], v[18:21]
	v_mfma_f32_16x16x32_bf16 v[6:9], v[192:195], v[238:241], v[6:9]
	v_mfma_f32_16x16x32_bf16 v[2:5], v[200:203], v[238:241], v[2:5]
	s_setprio 0
	s_waitcnt vmcnt(8)
	s_barrier
	s_add_i32 s0, 0, 0x18000
	s_add_i32 s1, 0, 0x1c000
	v_add_u32_e32 v142, s0, v189
	v_add_u32_e32 v200, s1, v189
	ds_read_b128 v[130:133], v142
	ds_read_b128 v[134:137], v142 offset:1024
	ds_read_b128 v[138:141], v142 offset:2048
	ds_read_b128 v[142:145], v142 offset:3072
	ds_read_b128 v[158:161], v200
	ds_read_b128 v[192:195], v200 offset:1024
	ds_read_b128 v[196:199], v200 offset:2048
	ds_read_b128 v[200:203], v200 offset:3072
	s_add_u32 s2, s68, 0x80000
	s_addc_u32 s3, s69, 0
	s_mov_b32 m0, s73
	v_lshl_add_u64 v[242:243], s[2:3], 0, v[152:153]
	global_load_lds_dwordx4 v[242:243], off
	v_lshl_add_u64 v[242:243], s[2:3], 0, v[150:151]
	s_mov_b32 m0, s74
	s_nop 0
	global_load_lds_dwordx4 v[242:243], off
	ds_read_b128 v[210:213], v191 offset:32768
	ds_read_b128 v[214:217], v191 offset:33792
	ds_read_b128 v[218:221], v191 offset:34816
	ds_read_b128 v[222:225], v191 offset:35840
	ds_read_b128 v[226:229], v191 offset:36864
	ds_read_b128 v[230:233], v191 offset:37888
	ds_read_b128 v[234:237], v191 offset:38912
	ds_read_b128 v[238:241], v191 offset:39936
	s_cmp_lg_u64 s[6:7], 0
	s_cbranch_scc1 .Lkw_22
	s_waitcnt vmcnt(8)
; #define PG8_STAGE(bufoff, gbase, voff) do { _Pragma("unroll") for (int _i = 0; _i < 2; ++_i) \
;         __builtin_amdgcn_global_load_lds((const unsigned*)((const char*)(gbase) + (voff)[_i]), (LAS unsigned*)(lds + (bufoff) + ldsw + _i * 8192), 16, 0, 0); } while (0)
; #define PG8_LDA(dst, b, h) do { _Pragma("unroll") for (int m = 0; m < 4; ++m) _Pragma("unroll") for (int k = 0; k < 2; ++k) dst[m][k] = *(const LAS bf16x8*)(lds + PG8_SA(b, h) + aoff + m * 2048 + k * 1024); } while (0)
; #define PG8_MMA(ai, bj, At, Bt) do { __builtin_amdgcn_s_setprio(1); _Pragma("unroll") for (int m = 0; m < 4; ++m) _Pragma("unroll") for (int n = 0; n < 2; ++n) _Pragma("unroll") for (int k = 0; k < 2; ++k) \
;         acc[ai][bj][m][n] = __builtin_amdgcn_mfma_f32_16x16x32_bf16(Bt[n][k], At[m][k], acc[ai][bj][m][n], 0, 0, 0); __builtin_amdgcn_s_setprio(0); } while (0)
; #define PG8_WAIT_V(n) asm volatile("s_waitcnt vmcnt(" #n ")" ::: "memory")
; #define PG8_WAIT_L(n) asm volatile("s_waitcnt lgkmcnt(" #n ")" ::: "memory")
; #define PG8_BAR __builtin_amdgcn_s_barrier()
; #define PG8_SCHED __builtin_amdgcn_sched_barrier(0)
; template <class Epi>
; __device__ __forceinline__ void gemm_phase(LAS unsigned char* lds, const int tid, const Gemm g, const StaticOrder& S, const Epi& E) {
;     ...
;             PG8_WAIT_V(8); PG8_WAIT_L(0); PG8_BAR; PG8_MMA(0, 0, At, B0); PG8_MMA(0, 1, At, B1); PG8_BAR; PG8_SCHED;
;             PG8_LDA(At, 1, 1); PG8_STAGE(PG8_SB(1, 0), b3, voffB); PG8_STAGE(PG8_SB(1, 1), b3 + hstepB, voffB); PG8_STAGE(PG8_SA(1, 0), a3, voffA);
;             PG8_WAIT_V(8); PG8_WAIT_L(0); PG8_BAR; PG8_MMA(1, 0, At, B0); PG8_MMA(1, 1, At, B1); PG8_BAR; PG8_SCHED;
;         }
;         if (wr == 0) PG8_BAR;
.Lkw_22:
	s_waitcnt lgkmcnt(0)
	s_barrier
	s_setprio 1
	s_waitcnt lgkmcnt(0)
	v_mfma_f32_16x16x32_bf16 v[126:129], v[130:133], v[210:213], v[126:129]
	v_mfma_f32_16x16x32_bf16 v[122:125], v[138:141], v[210:213], v[122:125]
	v_mfma_f32_16x16x32_bf16 v[110:113], v[130:133], v[218:221], v[110:113]
	v_mfma_f32_16x16x32_bf16 v[106:109], v[138:141], v[218:221], v[106:109]
	v_mfma_f32_16x16x32_bf16 v[94:97], v[130:133], v[226:229], v[94:97]
	v_mfma_f32_16x16x32_bf16 v[90:93], v[138:141], v[226:229], v[90:93]
	v_mfma_f32_16x16x32_bf16 v[78:81], v[130:133], v[234:237], v[78:81]
	v_mfma_f32_16x16x32_bf16 v[74:77], v[138:141], v[234:237], v[74:77]
	v_mfma_f32_16x16x32_bf16 v[126:129], v[134:137], v[214:217], v[126:129]
	v_mfma_f32_16x16x32_bf16 v[122:125], v[142:145], v[214:217], v[122:125]
	v_mfma_f32_16x16x32_bf16 v[110:113], v[134:137], v[222:225], v[110:113]
	v_mfma_f32_16x16x32_bf16 v[106:109], v[142:145], v[222:225], v[106:109]
	v_mfma_f32_16x16x32_bf16 v[94:97], v[134:137], v[230:233], v[94:97]
	v_mfma_f32_16x16x32_bf16 v[90:93], v[142:145], v[230:233], v[90:93]
	v_mfma_f32_16x16x32_bf16 v[78:81], v[134:137], v[238:241], v[78:81]
	v_mfma_f32_16x16x32_bf16 v[74:77], v[142:145], v[238:241], v[74:77]
	s_setprio 0
	s_setprio 1
	v_mfma_f32_16x16x32_bf16 v[118:121], v[158:161], v[210:213], v[118:121]
	v_mfma_f32_16x16x32_bf16 v[114:117], v[196:199], v[210:213], v[114:117]
	v_mfma_f32_16x16x32_bf16 v[102:105], v[158:161], v[218:221], v[102:105]
	v_mfma_f32_16x16x32_bf16 v[98:101], v[196:199], v[218:221], v[98:101]
	v_mfma_f32_16x16x32_bf16 v[86:89], v[158:161], v[226:229], v[86:89]
	v_mfma_f32_16x16x32_bf16 v[82:85], v[196:199], v[226:229], v[82:85]
	v_mfma_f32_16x16x32_bf16 v[70:73], v[158:161], v[234:237], v[70:73]
	v_mfma_f32_16x16x32_bf16 v[66:69], v[196:199], v[234:237], v[66:69]
	v_mfma_f32_16x16x32_bf16 v[118:121], v[192:195], v[214:217], v[118:121]
	v_mfma_f32_16x16x32_bf16 v[114:117], v[200:203], v[214:217], v[114:117]
	v_mfma_f32_16x16x32_bf16 v[102:105], v[192:195], v[222:225], v[102:105]
	v_mfma_f32_16x16x32_bf16 v[98:101], v[200:203], v[222:225], v[98:101]
	v_mfma_f32_16x16x32_bf16 v[86:89], v[192:195], v[230:233], v[86:89]
	v_mfma_f32_16x16x32_bf16 v[82:85], v[200:203], v[230:233], v[82:85]
	v_mfma_f32_16x16x32_bf16 v[70:73], v[192:195], v[238:241], v[70:73]
	v_mfma_f32_16x16x32_bf16 v[66:69], v[200:203], v[238:241], v[66:69]
	s_setprio 0
	s_waitcnt vmcnt(8)
	s_barrier
	s_add_i32 s0, s0, s28
	v_lshl_add_u64 v[162:163], v[162:163], 0, s[36:37]
	s_mov_b32 m0, s0
	s_nop 0
	global_load_lds_dwordx4 v[162:163], off
	s_add_i32 m0, s0, 0x2000
	s_add_u32 s2, s30, 0x40080
	v_lshl_add_u64 v[162:163], v[164:165], 0, s[36:37]
	s_addc_u32 s3, s31, 0
	s_add_i32 s0, s1, s28
	global_load_lds_dwordx4 v[162:163], off
	v_lshl_add_u64 v[162:163], s[2:3], 0, v[0:1]
	s_mov_b32 m0, s0
	s_nop 0
	global_load_lds_dwordx4 v[162:163], off
	v_lshl_add_u64 v[162:163], s[2:3], 0, v[148:149]
	s_add_i32 m0, s0, 0x2000
	s_nop 0
	global_load_lds_dwordx4 v[162:163], off
	v_lshl_add_u64 v[162:163], v[170:171], 0, s[36:37]
	s_mov_b32 m0, s75
	s_nop 0
	global_load_lds_dwordx4 v[162:163], off
	v_lshl_add_u64 v[162:163], v[206:207], 0, s[36:37]
	s_mov_b32 m0, s76
	s_nop 0
	global_load_lds_dwordx4 v[162:163], off
	ds_read_b128 v[210:213], v191 offset:49152
	ds_read_b128 v[214:217], v191 offset:50176
	ds_read_b128 v[218:221], v191 offset:51200
	ds_read_b128 v[222:225], v191 offset:52224
	ds_read_b128 v[226:229], v191 offset:53248
	ds_read_b128 v[230:233], v191 offset:54272
	ds_read_b128 v[234:237], v191 offset:55296
	ds_read_b128 v[238:241], v191 offset:56320
	s_cmp_lg_u64 s[6:7], 0
	s_cbranch_scc1 .Lkw_21
	s_waitcnt vmcnt(8)
.Lkw_21:
	s_waitcnt lgkmcnt(0)
	s_barrier
	s_setprio 1
	s_waitcnt lgkmcnt(0)
	v_mfma_f32_16x16x32_bf16 v[62:65], v[130:133], v[210:213], v[62:65]
	v_mfma_f32_16x16x32_bf16 v[58:61], v[138:141], v[210:213], v[58:61]
	v_mfma_f32_16x16x32_bf16 v[46:49], v[130:133], v[218:221], v[46:49]
	v_mfma_f32_16x16x32_bf16 v[42:45], v[138:141], v[218:221], v[42:45]
	v_mfma_f32_16x16x32_bf16 v[30:33], v[130:133], v[226:229], v[30:33]
	v_mfma_f32_16x16x32_bf16 v[26:29], v[138:141], v[226:229], v[26:29]
	v_mfma_f32_16x16x32_bf16 v[14:17], v[130:133], v[234:237], v[14:17]
	v_mfma_f32_16x16x32_bf16 v[10:13], v[138:141], v[234:237], v[10:13]
	v_mfma_f32_16x16x32_bf16 v[62:65], v[134:137], v[214:217], v[62:65]
	v_mfma_f32_16x16x32_bf16 v[58:61], v[142:145], v[214:217], v[58:61]
	v_mfma_f32_16x16x32_bf16 v[46:49], v[134:137], v[222:225], v[46:49]
	v_mfma_f32_16x16x32_bf16 v[42:45], v[142:145], v[222:225], v[42:45]
	v_mfma_f32_16x16x32_bf16 v[30:33], v[134:137], v[230:233], v[30:33]
	v_mfma_f32_16x16x32_bf16 v[26:29], v[142:145], v[230:233], v[26:29]
	v_mfma_f32_16x16x32_bf16 v[14:17], v[134:137], v[238:241], v[14:17]
	v_mfma_f32_16x16x32_bf16 v[10:13], v[142:145], v[238:241], v[10:13]
	s_setprio 0
	s_setprio 1
	v_mfma_f32_16x16x32_bf16 v[54:57], v[158:161], v[210:213], v[54:57]
	v_mfma_f32_16x16x32_bf16 v[50:53], v[196:199], v[210:213], v[50:53]
	v_mfma_f32_16x16x32_bf16 v[38:41], v[158:161], v[218:221], v[38:41]
	v_mfma_f32_16x16x32_bf16 v[34:37], v[196:199], v[218:221], v[34:37]
	v_mfma_f32_16x16x32_bf16 v[22:25], v[158:161], v[226:229], v[22:25]
	v_mfma_f32_16x16x32_bf16 v[18:21], v[196:199], v[226:229], v[18:21]
	v_mfma_f32_16x16x32_bf16 v[6:9], v[158:161], v[234:237], v[6:9]
	v_mfma_f32_16x16x32_bf16 v[2:5], v[196:199], v[234:237], v[2:5]
	v_mfma_f32_16x16x32_bf16 v[54:57], v[192:195], v[214:217], v[54:57]
	v_mfma_f32_16x16x32_bf16 v[50:53], v[200:203], v[214:217], v[50:53]
	v_mfma_f32_16x16x32_bf16 v[38:41], v[192:195], v[222:225], v[38:41]
	v_mfma_f32_16x16x32_bf16 v[34:37], v[200:203], v[222:225], v[34:37]
	v_mfma_f32_16x16x32_bf16 v[22:25], v[192:195], v[230:233], v[22:25]
	v_mfma_f32_16x16x32_bf16 v[18:21], v[200:203], v[230:233], v[18:21]
	v_mfma_f32_16x16x32_bf16 v[6:9], v[192:195], v[238:241], v[6:9]
	v_mfma_f32_16x16x32_bf16 v[2:5], v[200:203], v[238:241], v[2:5]
	s_setprio 0
	s_waitcnt vmcnt(8)
	s_barrier
	s_add_i32 vcc_lo, vcc_lo, 2
	s_add_u32 s66, s66, 0x100
	s_addc_u32 s67, s67, 0
	s_add_u32 s92, s92, 0x100
	s_addc_u32 s93, s93, 0
	s_cmp_gt_u32 vcc_lo, 13
	s_cbranch_scc0 .LBB0_1333
	s_and_b64 vcc, exec, s[6:7]
	s_cbranch_vccz .LBB0_1336
	s_barrier

; #define PG8_STAGE(bufoff, gbase, voff) do { _Pragma("unroll") for (int _i = 0; _i < 2; ++_i) \
;         __builtin_amdgcn_global_load_lds((const unsigned*)((const char*)(gbase) + (voff)[_i]), (LAS unsigned*)(lds + (bufoff) + ldsw + _i * 8192), 16, 0, 0); } while (0)
; #define PG8_LDA(dst, b, h) do { _Pragma("unroll") for (int m = 0; m < 4; ++m) _Pragma("unroll") for (int k = 0; k < 2; ++k) dst[m][k] = *(const LAS bf16x8*)(lds + PG8_SA(b, h) + aoff + m * 2048 + k * 1024); } while (0)
; #define PG8_LDB(dst, b, h) do { _Pragma("unroll") for (int n = 0; n < 2; ++n) _Pragma("unroll") for (int k = 0; k < 2; ++k) dst[n][k] = *(const LAS bf16x8*)(lds + PG8_SB(b, h) + boff + n * 2048 + k * 1024); } while (0)
; #define PG8_MMA(ai, bj, At, Bt) do { __builtin_amdgcn_s_setprio(1); _Pragma("unroll") for (int m = 0; m < 4; ++m) _Pragma("unroll") for (int n = 0; n < 2; ++n) _Pragma("unroll") for (int k = 0; k < 2; ++k) \
;         acc[ai][bj][m][n] = __builtin_amdgcn_mfma_f32_16x16x32_bf16(Bt[n][k], At[m][k], acc[ai][bj][m][n], 0, 0, 0); __builtin_amdgcn_s_setprio(0); } while (0)
; #define PG8_BAR __builtin_amdgcn_s_barrier()
; template <class Epi>
; __device__ __forceinline__ void gemm_phase(LAS unsigned char* lds, const int tid, const Gemm g, const StaticOrder& S, const Epi& E) {
;     ...
;         const char* nA = has_next ? (const char*)g.A + (size_t)nxt.pm * tstepA : cA; const char* nB = has_next ? (const char*)g.Bt + (size_t)nxt.pn * tstepB : cB;
;         for (int t = 0; t < nt; t += 2) {
;             const bool last = (t == nt - 2);
;             const char* a1 = cA + (size_t)(t + 1) * kstep;
;             const char* a2 = last ? nA : cA + (size_t)(t + 2) * kstep; const char* b2 = last ? nB : cB + (size_t)(t + 2) * kstep;
;             const char* a3 = a2 + kstep; const char* b3 = b2 + kstep;
;             PG8_LDB(B0, 0, 0); PG8_LDB(B1, 0, 1); PG8_SCHED; PG8_LDA(At, 0, 0); PG8_STAGE(PG8_SA(1, 1), a1 + hstepA, voffA);
;             PG8_WAIT_V(8); PG8_WAIT_L(0); PG8_BAR; PG8_MMA(0, 0, At, B0); PG8_MMA(0, 1, At, B1); PG8_BAR; PG8_SCHED;
;     ...
; #pragma unroll
;         for (int a = 0; a < 2; ++a)
; #pragma unroll
;             for (int b = 0; b < 2; ++b)
; #pragma unroll
;                 for (int m = 0; m < 4; ++m)
; #pragma unroll
;                     for (int n = 0; n < 2; ++n) acc[a][b][m][n] = (f32x4){0.f, 0.f, 0.f, 0.f};
;         cur = nxt; cA = nA; cB = nB; ++ui;
.LBB0_1486:
	s_ashr_i32 s83, s82, 31
	s_lshl_b64 s[26:27], s[82:83], 19
	s_add_u32 s92, s60, s26
	s_addc_u32 s93, s61, s27
	s_and_b64 s[26:27], s[66:67], exec
	s_cselect_b32 s28, s93, s69
	s_cselect_b32 s71, s92, s68
	s_ashr_i32 s5, s4, 31
	s_lshl_b64 s[26:27], s[4:5], 19
	v_readlane_b32 s36, v252, 26
	v_readlane_b32 s37, v252, 27
	s_add_u32 s76, s36, s26
	s_addc_u32 s77, s37, s27
	s_and_b64 s[26:27], s[66:67], exec
	s_cselect_b32 s5, s77, s31
	s_cselect_b32 s73, s76, s30
	s_add_u32 s68, s68, 0x40080
	s_addc_u32 s69, s69, 0
	s_add_u32 s75, s30, 0x100
	v_mov_b32_e32 v2, 0
	s_addc_u32 s83, s31, 0
	s_mov_b32 s26, -2
	s_waitcnt lgkmcnt(0)
	v_mov_b32_e32 v3, v2
	v_mov_b32_e32 v4, v2
	v_mov_b32_e32 v5, v2
	v_mov_b32_e32 v6, v2
	v_mov_b32_e32 v7, v2
	v_mov_b32_e32 v8, v2
	v_mov_b32_e32 v9, v2
	v_mov_b32_e32 v18, v2
	v_mov_b32_e32 v19, v2
	v_mov_b32_e32 v20, v2
	v_mov_b32_e32 v21, v2
	v_mov_b32_e32 v22, v2
	v_mov_b32_e32 v23, v2
	v_mov_b32_e32 v24, v2
	v_mov_b32_e32 v25, v2
	v_mov_b32_e32 v34, v2
	v_mov_b32_e32 v35, v2
	v_mov_b32_e32 v36, v2
	v_mov_b32_e32 v37, v2
	v_mov_b32_e32 v38, v2
	v_mov_b32_e32 v39, v2
	v_mov_b32_e32 v40, v2
	v_mov_b32_e32 v41, v2
	v_mov_b32_e32 v50, v2
	v_mov_b32_e32 v51, v2
	v_mov_b32_e32 v52, v2
	v_mov_b32_e32 v53, v2
	v_mov_b32_e32 v54, v2
	v_mov_b32_e32 v55, v2
	v_mov_b32_e32 v56, v2
	v_mov_b32_e32 v57, v2
	v_mov_b32_e32 v10, v2
	v_mov_b32_e32 v11, v2
	v_mov_b32_e32 v12, v2
	v_mov_b32_e32 v13, v2
	v_mov_b32_e32 v14, v2
	v_mov_b32_e32 v15, v2
	v_mov_b32_e32 v16, v2
	v_mov_b32_e32 v17, v2
	v_mov_b32_e32 v26, v2
	v_mov_b32_e32 v27, v2
	v_mov_b32_e32 v28, v2
	v_mov_b32_e32 v29, v2
	v_mov_b32_e32 v30, v2
	v_mov_b32_e32 v31, v2
	v_mov_b32_e32 v32, v2
	v_mov_b32_e32 v33, v2
	v_mov_b32_e32 v42, v2
	v_mov_b32_e32 v43, v2
	v_mov_b32_e32 v44, v2
	v_mov_b32_e32 v45, v2
	v_mov_b32_e32 v46, v2
	v_mov_b32_e32 v47, v2
	v_mov_b32_e32 v48, v2
	v_mov_b32_e32 v49, v2
	v_mov_b32_e32 v58, v2
	v_mov_b32_e32 v59, v2
	v_mov_b32_e32 v60, v2
	v_mov_b32_e32 v61, v2
	v_mov_b32_e32 v62, v2
	v_mov_b32_e32 v63, v2
	v_mov_b32_e32 v64, v2
	v_mov_b32_e32 v65, v2
	v_mov_b32_e32 v66, v2
	v_mov_b32_e32 v67, v2
	v_mov_b32_e32 v68, v2
	v_mov_b32_e32 v69, v2
	v_mov_b32_e32 v70, v2
	v_mov_b32_e32 v71, v2
	v_mov_b32_e32 v72, v2
	v_mov_b32_e32 v73, v2
	v_mov_b32_e32 v82, v2
	v_mov_b32_e32 v83, v2
	v_mov_b32_e32 v84, v2
	v_mov_b32_e32 v85, v2
	v_mov_b32_e32 v86, v2
	v_mov_b32_e32 v87, v2
	v_mov_b32_e32 v88, v2
	v_mov_b32_e32 v89, v2
	v_mov_b32_e32 v98, v2
	v_mov_b32_e32 v99, v2
	s_waitcnt vmcnt(0)
	v_mov_b32_e32 v100, v2
	v_mov_b32_e32 v101, v2
	v_mov_b32_e32 v102, v2
	v_mov_b32_e32 v103, v2
	v_mov_b32_e32 v104, v2
	v_mov_b32_e32 v105, v2
	v_mov_b32_e32 v114, v2
	v_mov_b32_e32 v115, v2
	v_mov_b32_e32 v116, v2
	v_mov_b32_e32 v117, v2
	v_mov_b32_e32 v118, v2
	v_mov_b32_e32 v119, v2
	v_mov_b32_e32 v120, v2
	v_mov_b32_e32 v121, v2
	v_mov_b32_e32 v74, v2
	v_mov_b32_e32 v75, v2
	v_mov_b32_e32 v76, v2
	v_mov_b32_e32 v77, v2
	v_mov_b32_e32 v78, v2
	v_mov_b32_e32 v79, v2
	v_mov_b32_e32 v80, v2
	v_mov_b32_e32 v81, v2
	v_mov_b32_e32 v90, v2
	v_mov_b32_e32 v91, v2
	v_mov_b32_e32 v92, v2
	v_mov_b32_e32 v93, v2
	v_mov_b32_e32 v94, v2
	v_mov_b32_e32 v95, v2
	v_mov_b32_e32 v96, v2
	v_mov_b32_e32 v97, v2
	v_mov_b32_e32 v106, v2
	v_mov_b32_e32 v107, v2
	v_mov_b32_e32 v108, v2
	v_mov_b32_e32 v109, v2
	v_mov_b32_e32 v110, v2
	v_mov_b32_e32 v111, v2
	v_mov_b32_e32 v112, v2
	v_mov_b32_e32 v113, v2
	v_mov_b32_e32 v122, v2
	v_mov_b32_e32 v123, v2
	v_mov_b32_e32 v124, v2
	v_mov_b32_e32 v125, v2
	v_mov_b32_e32 v126, v2
	v_mov_b32_e32 v127, v2
	v_mov_b32_e32 v128, v2
	v_mov_b32_e32 v129, v2
	s_mov_b64 s[36:37], 0x80
	v_readlane_b32 s100, v255, 55
	v_readlane_b32 s101, v255, 56
	.p2align	6
.LBB0_1487:
	s_add_u32 s27, s68, 0xfffc0080
	s_addc_u32 s30, s69, -1
	s_add_i32 s62, 0, 0x10000
	s_cmp_eq_u32 s26, 12
	s_cselect_b32 vcc_hi, s28, s30
	s_cselect_b32 vcc_lo, s71, s27
	s_cselect_b32 s31, s5, s83
	s_cselect_b32 s30, s73, s75
	s_add_i32 s27, 0, 0x14000
	v_add_u32_e32 v142, s62, v216
	v_add_u32_e32 v158, s27, v216
	ds_read_b128 v[130:133], v142
	ds_read_b128 v[134:137], v142 offset:1024
	ds_read_b128 v[138:141], v142 offset:2048
	ds_read_b128 v[142:145], v142 offset:3072
	ds_read_b128 v[146:149], v158
	ds_read_b128 v[150:153], v158 offset:1024
	ds_read_b128 v[154:157], v158 offset:2048
	ds_read_b128 v[158:161], v158 offset:3072
	v_lshl_add_u64 v[162:163], s[68:69], 0, v[176:177]
	s_add_i32 m0, s1, 0xc000
	s_nop 0
	global_load_lds_dwordx4 v[162:163], off
	v_lshl_add_u64 v[162:163], s[68:69], 0, v[178:179]
	s_add_i32 m0, s1, 0xe000
	s_nop 0
	global_load_lds_dwordx4 v[162:163], off
	ds_read_b128 v[180:183], v218
	ds_read_b128 v[184:187], v218 offset:1024
	ds_read_b128 v[220:223], v218 offset:2048
	ds_read_b128 v[224:227], v218 offset:3072
	ds_read_b128 v[228:231], v218 offset:4096
	ds_read_b128 v[232:235], v218 offset:5120
	ds_read_b128 v[236:239], v218 offset:6144
	ds_read_b128 v[240:243], v218 offset:7168
	s_cmp_lg_u64 s[100:101], 0
	s_cbranch_scc1 .Lkw_20
	s_waitcnt vmcnt(8)
; #define PG8_STAGE(bufoff, gbase, voff) do { _Pragma("unroll") for (int _i = 0; _i < 2; ++_i) \
;         __builtin_amdgcn_global_load_lds((const unsigned*)((const char*)(gbase) + (voff)[_i]), (LAS unsigned*)(lds + (bufoff) + ldsw + _i * 8192), 16, 0, 0); } while (0)
; #define PG8_LDA(dst, b, h) do { _Pragma("unroll") for (int m = 0; m < 4; ++m) _Pragma("unroll") for (int k = 0; k < 2; ++k) dst[m][k] = *(const LAS bf16x8*)(lds + PG8_SA(b, h) + aoff + m * 2048 + k * 1024); } while (0)
; #define PG8_LDB(dst, b, h) do { _Pragma("unroll") for (int n = 0; n < 2; ++n) _Pragma("unroll") for (int k = 0; k < 2; ++k) dst[n][k] = *(const LAS bf16x8*)(lds + PG8_SB(b, h) + boff + n * 2048 + k * 1024); } while (0)
; #define PG8_MMA(ai, bj, At, Bt) do { __builtin_amdgcn_s_setprio(1); _Pragma("unroll") for (int m = 0; m < 4; ++m) _Pragma("unroll") for (int n = 0; n < 2; ++n) _Pragma("unroll") for (int k = 0; k < 2; ++k) \
;         acc[ai][bj][m][n] = __builtin_amdgcn_mfma_f32_16x16x32_bf16(Bt[n][k], At[m][k], acc[ai][bj][m][n], 0, 0, 0); __builtin_amdgcn_s_setprio(0); } while (0)
; #define PG8_WAIT_V(n) asm volatile("s_waitcnt vmcnt(" #n ")" ::: "memory")
; #define PG8_WAIT_L(n) asm volatile("s_waitcnt lgkmcnt(" #n ")" ::: "memory")
; #define PG8_BAR __builtin_amdgcn_s_barrier()
; #define PG8_SCHED __builtin_amdgcn_sched_barrier(0)
; template <class Epi>
; __device__ __forceinline__ void gemm_phase(LAS unsigned char* lds, const int tid, const Gemm g, const StaticOrder& S, const Epi& E) {
;     ...
;             PG8_WAIT_V(8); PG8_WAIT_L(0); PG8_BAR; PG8_MMA(0, 0, At, B0); PG8_MMA(0, 1, At, B1); PG8_BAR; PG8_SCHED;
;             PG8_LDA(At, 0, 1); PG8_STAGE(PG8_SB(0, 0), b2, voffB); PG8_STAGE(PG8_SB(0, 1), b2 + hstepB, voffB); PG8_STAGE(PG8_SA(0, 0), a2, voffA);
;             PG8_WAIT_V(8); PG8_WAIT_L(0); PG8_BAR; PG8_MMA(1, 0, At, B0); PG8_MMA(1, 1, At, B1); PG8_BAR; PG8_SCHED;
;             PG8_LDB(B0, 1, 0); PG8_LDB(B1, 1, 1); PG8_SCHED; PG8_LDA(At, 1, 0); PG8_STAGE(PG8_SA(0, 1), a2 + hstepA, voffA);
.Lkw_20:
	s_waitcnt lgkmcnt(0)
	s_barrier
	s_setprio 1
	s_waitcnt lgkmcnt(0)
	v_mfma_f32_16x16x32_bf16 v[126:129], v[130:133], v[180:183], v[126:129]
	v_mfma_f32_16x16x32_bf16 v[122:125], v[138:141], v[180:183], v[122:125]
	v_mfma_f32_16x16x32_bf16 v[110:113], v[130:133], v[220:223], v[110:113]
	v_mfma_f32_16x16x32_bf16 v[106:109], v[138:141], v[220:223], v[106:109]
	v_mfma_f32_16x16x32_bf16 v[94:97], v[130:133], v[228:231], v[94:97]
	v_mfma_f32_16x16x32_bf16 v[90:93], v[138:141], v[228:231], v[90:93]
	v_mfma_f32_16x16x32_bf16 v[78:81], v[130:133], v[236:239], v[78:81]
	v_mfma_f32_16x16x32_bf16 v[74:77], v[138:141], v[236:239], v[74:77]
	v_mfma_f32_16x16x32_bf16 v[126:129], v[134:137], v[184:187], v[126:129]
	v_mfma_f32_16x16x32_bf16 v[122:125], v[142:145], v[184:187], v[122:125]
	v_mfma_f32_16x16x32_bf16 v[110:113], v[134:137], v[224:227], v[110:113]
	v_mfma_f32_16x16x32_bf16 v[106:109], v[142:145], v[224:227], v[106:109]
	v_mfma_f32_16x16x32_bf16 v[94:97], v[134:137], v[232:235], v[94:97]
	v_mfma_f32_16x16x32_bf16 v[90:93], v[142:145], v[232:235], v[90:93]
	v_mfma_f32_16x16x32_bf16 v[78:81], v[134:137], v[240:243], v[78:81]
	v_mfma_f32_16x16x32_bf16 v[74:77], v[142:145], v[240:243], v[74:77]
	s_setprio 0
	s_setprio 1
	v_mfma_f32_16x16x32_bf16 v[118:121], v[146:149], v[180:183], v[118:121]
	v_mfma_f32_16x16x32_bf16 v[114:117], v[154:157], v[180:183], v[114:117]
	v_mfma_f32_16x16x32_bf16 v[102:105], v[146:149], v[220:223], v[102:105]
	v_mfma_f32_16x16x32_bf16 v[98:101], v[154:157], v[220:223], v[98:101]
	v_mfma_f32_16x16x32_bf16 v[86:89], v[146:149], v[228:231], v[86:89]
	v_mfma_f32_16x16x32_bf16 v[82:85], v[154:157], v[228:231], v[82:85]
	v_mfma_f32_16x16x32_bf16 v[70:73], v[146:149], v[236:239], v[70:73]
	v_mfma_f32_16x16x32_bf16 v[66:69], v[154:157], v[236:239], v[66:69]
	v_mfma_f32_16x16x32_bf16 v[118:121], v[150:153], v[184:187], v[118:121]
	v_mfma_f32_16x16x32_bf16 v[114:117], v[158:161], v[184:187], v[114:117]
	v_mfma_f32_16x16x32_bf16 v[102:105], v[150:153], v[224:227], v[102:105]
	v_mfma_f32_16x16x32_bf16 v[98:101], v[158:161], v[224:227], v[98:101]
	v_mfma_f32_16x16x32_bf16 v[86:89], v[150:153], v[232:235], v[86:89]
	v_mfma_f32_16x16x32_bf16 v[82:85], v[158:161], v[232:235], v[82:85]
	v_mfma_f32_16x16x32_bf16 v[70:73], v[150:153], v[240:243], v[70:73]
	v_mfma_f32_16x16x32_bf16 v[66:69], v[158:161], v[240:243], v[66:69]
	s_setprio 0
	s_waitcnt vmcnt(8)
	s_barrier
	s_add_i32 s62, s62, s0
	v_lshl_add_u64 v[162:163], s[30:31], 0, v[0:1]
	s_mov_b32 m0, s62
	s_nop 0
	global_load_lds_dwordx4 v[162:163], off
	s_add_i32 m0, s62, 0x2000
	s_add_u32 s62, s30, 0x40000
	v_lshl_add_u64 v[164:165], s[30:31], 0, v[170:171]
	s_addc_u32 s63, s31, 0
	s_add_i32 s27, s27, s0
	global_load_lds_dwordx4 v[164:165], off
	v_lshl_add_u64 v[206:207], s[62:63], 0, v[0:1]
	s_mov_b32 m0, s27
	v_lshl_add_u64 v[244:245], vcc, 0, v[174:175]
	global_load_lds_dwordx4 v[206:207], off
	v_lshl_add_u64 v[206:207], s[62:63], 0, v[170:171]
	s_add_i32 m0, s27, 0x2000
	s_nop 0
	global_load_lds_dwordx4 v[206:207], off
	v_lshl_add_u64 v[206:207], vcc, 0, v[172:173]
	s_mov_b32 m0, s1
	s_nop 0
	global_load_lds_dwordx4 v[206:207], off
	s_mov_b32 m0, s2
	s_nop 0
	global_load_lds_dwordx4 v[244:245], off
	ds_read_b128 v[180:183], v218 offset:16384
	ds_read_b128 v[184:187], v218 offset:17408
	ds_read_b128 v[220:223], v218 offset:18432
	ds_read_b128 v[224:227], v218 offset:19456
	ds_read_b128 v[228:231], v218 offset:20480
	ds_read_b128 v[232:235], v218 offset:21504
	ds_read_b128 v[236:239], v218 offset:22528
	ds_read_b128 v[240:243], v218 offset:23552
	s_cmp_lg_u64 s[100:101], 0
	s_cbranch_scc1 .Lkw_19
	s_waitcnt vmcnt(8)
.Lkw_19:
	s_waitcnt lgkmcnt(0)
	s_barrier
	s_setprio 1
	s_waitcnt lgkmcnt(0)
	v_mfma_f32_16x16x32_bf16 v[62:65], v[130:133], v[180:183], v[62:65]
	v_mfma_f32_16x16x32_bf16 v[58:61], v[138:141], v[180:183], v[58:61]
	v_mfma_f32_16x16x32_bf16 v[46:49], v[130:133], v[220:223], v[46:49]
	v_mfma_f32_16x16x32_bf16 v[42:45], v[138:141], v[220:223], v[42:45]
	v_mfma_f32_16x16x32_bf16 v[30:33], v[130:133], v[228:231], v[30:33]
	v_mfma_f32_16x16x32_bf16 v[26:29], v[138:141], v[228:231], v[26:29]
	v_mfma_f32_16x16x32_bf16 v[14:17], v[130:133], v[236:239], v[14:17]
	v_mfma_f32_16x16x32_bf16 v[10:13], v[138:141], v[236:239], v[10:13]
	v_mfma_f32_16x16x32_bf16 v[62:65], v[134:137], v[184:187], v[62:65]
	v_mfma_f32_16x16x32_bf16 v[58:61], v[142:145], v[184:187], v[58:61]
	v_mfma_f32_16x16x32_bf16 v[46:49], v[134:137], v[224:227], v[46:49]
	v_mfma_f32_16x16x32_bf16 v[42:45], v[142:145], v[224:227], v[42:45]
	v_mfma_f32_16x16x32_bf16 v[30:33], v[134:137], v[232:235], v[30:33]
	v_mfma_f32_16x16x32_bf16 v[26:29], v[142:145], v[232:235], v[26:29]
	v_mfma_f32_16x16x32_bf16 v[14:17], v[134:137], v[240:243], v[14:17]
	v_mfma_f32_16x16x32_bf16 v[10:13], v[142:145], v[240:243], v[10:13]
	s_setprio 0
	s_setprio 1
	v_mfma_f32_16x16x32_bf16 v[54:57], v[146:149], v[180:183], v[54:57]
	v_mfma_f32_16x16x32_bf16 v[50:53], v[154:157], v[180:183], v[50:53]
	v_mfma_f32_16x16x32_bf16 v[38:41], v[146:149], v[220:223], v[38:41]
	v_mfma_f32_16x16x32_bf16 v[34:37], v[154:157], v[220:223], v[34:37]
	v_mfma_f32_16x16x32_bf16 v[22:25], v[146:149], v[228:231], v[22:25]
	v_mfma_f32_16x16x32_bf16 v[18:21], v[154:157], v[228:231], v[18:21]
	v_mfma_f32_16x16x32_bf16 v[6:9], v[146:149], v[236:239], v[6:9]
	v_mfma_f32_16x16x32_bf16 v[2:5], v[154:157], v[236:239], v[2:5]
	v_mfma_f32_16x16x32_bf16 v[54:57], v[150:153], v[184:187], v[54:57]
	v_mfma_f32_16x16x32_bf16 v[50:53], v[158:161], v[184:187], v[50:53]
	v_mfma_f32_16x16x32_bf16 v[38:41], v[150:153], v[224:227], v[38:41]
	v_mfma_f32_16x16x32_bf16 v[34:37], v[158:161], v[224:227], v[34:37]
	v_mfma_f32_16x16x32_bf16 v[22:25], v[150:153], v[232:235], v[22:25]
	v_mfma_f32_16x16x32_bf16 v[18:21], v[158:161], v[232:235], v[18:21]
	v_mfma_f32_16x16x32_bf16 v[6:9], v[150:153], v[240:243], v[6:9]
	v_mfma_f32_16x16x32_bf16 v[2:5], v[158:161], v[240:243], v[2:5]
	s_setprio 0
	s_waitcnt vmcnt(8)
	s_barrier
; #define PG8_STAGE(bufoff, gbase, voff) do { _Pragma("unroll") for (int _i = 0; _i < 2; ++_i) \
;         __builtin_amdgcn_global_load_lds((const unsigned*)((const char*)(gbase) + (voff)[_i]), (LAS unsigned*)(lds + (bufoff) + ldsw + _i * 8192), 16, 0, 0); } while (0)
; #define PG8_LDA(dst, b, h) do { _Pragma("unroll") for (int m = 0; m < 4; ++m) _Pragma("unroll") for (int k = 0; k < 2; ++k) dst[m][k] = *(const LAS bf16x8*)(lds + PG8_SA(b, h) + aoff + m * 2048 + k * 1024); } while (0)
; #define PG8_LDB(dst, b, h) do { _Pragma("unroll") for (int n = 0; n < 2; ++n) _Pragma("unroll") for (int k = 0; k < 2; ++k) dst[n][k] = *(const LAS bf16x8*)(lds + PG8_SB(b, h) + boff + n * 2048 + k * 1024); } while (0)
; #define PG8_MMA(ai, bj, At, Bt) do { __builtin_amdgcn_s_setprio(1); _Pragma("unroll") for (int m = 0; m < 4; ++m) _Pragma("unroll") for (int n = 0; n < 2; ++n) _Pragma("unroll") for (int k = 0; k < 2; ++k) \
;         acc[ai][bj][m][n] = __builtin_amdgcn_mfma_f32_16x16x32_bf16(Bt[n][k], At[m][k], acc[ai][bj][m][n], 0, 0, 0); __builtin_amdgcn_s_setprio(0); } while (0)
; #define PG8_WAIT_V(n) asm volatile("s_waitcnt vmcnt(" #n ")" ::: "memory")
; #define PG8_WAIT_L(n) asm volatile("s_waitcnt lgkmcnt(" #n ")" ::: "memory")
; #define PG8_BAR __builtin_amdgcn_s_barrier()
; #define PG8_SCHED __builtin_amdgcn_sched_barrier(0)
; template <class Epi>
; __device__ __forceinline__ void gemm_phase(LAS unsigned char* lds, const int tid, const Gemm g, const StaticOrder& S, const Epi& E) {
;     ...
;             PG8_LDB(B0, 1, 0); PG8_LDB(B1, 1, 1); PG8_SCHED; PG8_LDA(At, 1, 0); PG8_STAGE(PG8_SA(0, 1), a2 + hstepA, voffA);
;             PG8_WAIT_V(8); PG8_WAIT_L(0); PG8_BAR; PG8_MMA(0, 0, At, B0); PG8_MMA(0, 1, At, B1); PG8_BAR; PG8_SCHED;
;             PG8_LDA(At, 1, 1); PG8_STAGE(PG8_SB(1, 0), b3, voffB); PG8_STAGE(PG8_SB(1, 1), b3 + hstepB, voffB); PG8_STAGE(PG8_SA(1, 0), a3, voffA);
;             PG8_WAIT_V(8); PG8_WAIT_L(0); PG8_BAR; PG8_MMA(1, 0, At, B0); PG8_MMA(1, 1, At, B1); PG8_BAR; PG8_SCHED;
	s_add_i32 s27, 0, 0x18000
	s_add_i32 s17, 0, 0x1c000
	v_add_u32_e32 v142, s27, v216
	v_add_u32_e32 v158, s17, v216
	ds_read_b128 v[130:133], v142
	ds_read_b128 v[134:137], v142 offset:1024
	ds_read_b128 v[138:141], v142 offset:2048
	ds_read_b128 v[142:145], v142 offset:3072
	ds_read_b128 v[146:149], v158
	ds_read_b128 v[150:153], v158 offset:1024
	ds_read_b128 v[154:157], v158 offset:2048
	ds_read_b128 v[158:161], v158 offset:3072
	s_add_u32 s62, vcc_lo, 0x40000
	s_addc_u32 s63, vcc_hi, 0
	s_mov_b32 m0, s3
	v_lshl_add_u64 v[246:247], s[62:63], 0, v[172:173]
	global_load_lds_dwordx4 v[246:247], off
	v_lshl_add_u64 v[246:247], s[62:63], 0, v[174:175]
	s_mov_b32 m0, s16
	s_nop 0
	global_load_lds_dwordx4 v[246:247], off
	ds_read_b128 v[180:183], v218 offset:32768
	ds_read_b128 v[184:187], v218 offset:33792
	ds_read_b128 v[220:223], v218 offset:34816
	ds_read_b128 v[224:227], v218 offset:35840
	ds_read_b128 v[228:231], v218 offset:36864
	ds_read_b128 v[232:235], v218 offset:37888
	ds_read_b128 v[236:239], v218 offset:38912
	ds_read_b128 v[240:243], v218 offset:39936
	s_cmp_lg_u64 s[100:101], 0
	s_cbranch_scc1 .Lkw_18
	s_waitcnt vmcnt(8)
.Lkw_18:
	s_waitcnt lgkmcnt(0)
	s_barrier
	s_setprio 1
	s_waitcnt lgkmcnt(0)
	v_mfma_f32_16x16x32_bf16 v[126:129], v[130:133], v[180:183], v[126:129]
	v_mfma_f32_16x16x32_bf16 v[122:125], v[138:141], v[180:183], v[122:125]
	v_mfma_f32_16x16x32_bf16 v[110:113], v[130:133], v[220:223], v[110:113]
	v_mfma_f32_16x16x32_bf16 v[106:109], v[138:141], v[220:223], v[106:109]
	v_mfma_f32_16x16x32_bf16 v[94:97], v[130:133], v[228:231], v[94:97]
	v_mfma_f32_16x16x32_bf16 v[90:93], v[138:141], v[228:231], v[90:93]
	v_mfma_f32_16x16x32_bf16 v[78:81], v[130:133], v[236:239], v[78:81]
	v_mfma_f32_16x16x32_bf16 v[74:77], v[138:141], v[236:239], v[74:77]
	v_mfma_f32_16x16x32_bf16 v[126:129], v[134:137], v[184:187], v[126:129]
	v_mfma_f32_16x16x32_bf16 v[122:125], v[142:145], v[184:187], v[122:125]
	v_mfma_f32_16x16x32_bf16 v[110:113], v[134:137], v[224:227], v[110:113]
	v_mfma_f32_16x16x32_bf16 v[106:109], v[142:145], v[224:227], v[106:109]
	v_mfma_f32_16x16x32_bf16 v[94:97], v[134:137], v[232:235], v[94:97]
	v_mfma_f32_16x16x32_bf16 v[90:93], v[142:145], v[232:235], v[90:93]
	v_mfma_f32_16x16x32_bf16 v[78:81], v[134:137], v[240:243], v[78:81]
	v_mfma_f32_16x16x32_bf16 v[74:77], v[142:145], v[240:243], v[74:77]
	s_setprio 0
	s_setprio 1
	v_mfma_f32_16x16x32_bf16 v[118:121], v[146:149], v[180:183], v[118:121]
	v_mfma_f32_16x16x32_bf16 v[114:117], v[154:157], v[180:183], v[114:117]
	v_mfma_f32_16x16x32_bf16 v[102:105], v[146:149], v[220:223], v[102:105]
	v_mfma_f32_16x16x32_bf16 v[98:101], v[154:157], v[220:223], v[98:101]
	v_mfma_f32_16x16x32_bf16 v[86:89], v[146:149], v[228:231], v[86:89]
	v_mfma_f32_16x16x32_bf16 v[82:85], v[154:157], v[228:231], v[82:85]
	v_mfma_f32_16x16x32_bf16 v[70:73], v[146:149], v[236:239], v[70:73]
	v_mfma_f32_16x16x32_bf16 v[66:69], v[154:157], v[236:239], v[66:69]
	v_mfma_f32_16x16x32_bf16 v[118:121], v[150:153], v[184:187], v[118:121]
	v_mfma_f32_16x16x32_bf16 v[114:117], v[158:161], v[184:187], v[114:117]
	v_mfma_f32_16x16x32_bf16 v[102:105], v[150:153], v[224:227], v[102:105]
	v_mfma_f32_16x16x32_bf16 v[98:101], v[158:161], v[224:227], v[98:101]
	v_mfma_f32_16x16x32_bf16 v[86:89], v[150:153], v[232:235], v[86:89]
	v_mfma_f32_16x16x32_bf16 v[82:85], v[158:161], v[232:235], v[82:85]
	v_mfma_f32_16x16x32_bf16 v[70:73], v[150:153], v[240:243], v[70:73]
	v_mfma_f32_16x16x32_bf16 v[66:69], v[158:161], v[240:243], v[66:69]
	s_setprio 0
	s_waitcnt vmcnt(8)
	s_barrier
	s_add_i32 s27, s27, s0
	v_lshl_add_u64 v[162:163], v[162:163], 0, s[36:37]
	s_mov_b32 m0, s27
	s_nop 0
	global_load_lds_dwordx4 v[162:163], off
	s_add_i32 m0, s27, 0x2000
	s_add_u32 s30, s30, 0x40080
	v_lshl_add_u64 v[162:163], v[164:165], 0, s[36:37]
	s_addc_u32 s31, s31, 0
	s_add_i32 s17, s17, s0
	global_load_lds_dwordx4 v[162:163], off
	v_lshl_add_u64 v[162:163], s[30:31], 0, v[0:1]
	s_mov_b32 m0, s17
	s_nop 0
	global_load_lds_dwordx4 v[162:163], off
	v_lshl_add_u64 v[162:163], s[30:31], 0, v[170:171]
	s_add_i32 m0, s17, 0x2000
	s_nop 0
	global_load_lds_dwordx4 v[162:163], off
	v_lshl_add_u64 v[162:163], v[206:207], 0, s[36:37]
	s_mov_b32 m0, s10
	s_nop 0
	global_load_lds_dwordx4 v[162:163], off
	v_lshl_add_u64 v[162:163], v[244:245], 0, s[36:37]
	s_mov_b32 m0, s11
	s_nop 0
	global_load_lds_dwordx4 v[162:163], off
	ds_read_b128 v[180:183], v218 offset:49152
	ds_read_b128 v[184:187], v218 offset:50176
	ds_read_b128 v[220:223], v218 offset:51200
	ds_read_b128 v[224:227], v218 offset:52224
	ds_read_b128 v[228:231], v218 offset:53248
	ds_read_b128 v[232:235], v218 offset:54272
	ds_read_b128 v[236:239], v218 offset:55296
	ds_read_b128 v[240:243], v218 offset:56320
	s_cmp_lg_u64 s[100:101], 0
	s_cbranch_scc1 .Lkw_17
	s_waitcnt vmcnt(8)
; #define PG8_MMA(ai, bj, At, Bt) do { __builtin_amdgcn_s_setprio(1); _Pragma("unroll") for (int m = 0; m < 4; ++m) _Pragma("unroll") for (int n = 0; n < 2; ++n) _Pragma("unroll") for (int k = 0; k < 2; ++k) \
;         acc[ai][bj][m][n] = __builtin_amdgcn_mfma_f32_16x16x32_bf16(Bt[n][k], At[m][k], acc[ai][bj][m][n], 0, 0, 0); __builtin_amdgcn_s_setprio(0); } while (0)
; #define PG8_WAIT_V(n) asm volatile("s_waitcnt vmcnt(" #n ")" ::: "memory")
; #define PG8_WAIT_L(n) asm volatile("s_waitcnt lgkmcnt(" #n ")" ::: "memory")
; #define PG8_BAR __builtin_amdgcn_s_barrier()
; #define PG8_SCHED __builtin_amdgcn_sched_barrier(0)
; template <class Epi>
; __device__ __forceinline__ void gemm_phase(LAS unsigned char* lds, const int tid, const Gemm g, const StaticOrder& S, const Epi& E) {
;     ...
;             PG8_WAIT_V(8); PG8_WAIT_L(0); PG8_BAR; PG8_MMA(1, 0, At, B0); PG8_MMA(1, 1, At, B1); PG8_BAR; PG8_SCHED;
;         }
;         if (wr == 0) PG8_BAR;
.Lkw_17:
	s_waitcnt lgkmcnt(0)
	s_barrier
	s_setprio 1
	s_waitcnt lgkmcnt(0)
	v_mfma_f32_16x16x32_bf16 v[62:65], v[130:133], v[180:183], v[62:65]
	v_mfma_f32_16x16x32_bf16 v[58:61], v[138:141], v[180:183], v[58:61]
	v_mfma_f32_16x16x32_bf16 v[46:49], v[130:133], v[220:223], v[46:49]
	v_mfma_f32_16x16x32_bf16 v[42:45], v[138:141], v[220:223], v[42:45]
	v_mfma_f32_16x16x32_bf16 v[30:33], v[130:133], v[228:231], v[30:33]
	v_mfma_f32_16x16x32_bf16 v[26:29], v[138:141], v[228:231], v[26:29]
	v_mfma_f32_16x16x32_bf16 v[14:17], v[130:133], v[236:239], v[14:17]
	v_mfma_f32_16x16x32_bf16 v[10:13], v[138:141], v[236:239], v[10:13]
	v_mfma_f32_16x16x32_bf16 v[62:65], v[134:137], v[184:187], v[62:65]
	v_mfma_f32_16x16x32_bf16 v[58:61], v[142:145], v[184:187], v[58:61]
	v_mfma_f32_16x16x32_bf16 v[46:49], v[134:137], v[224:227], v[46:49]
	v_mfma_f32_16x16x32_bf16 v[42:45], v[142:145], v[224:227], v[42:45]
	v_mfma_f32_16x16x32_bf16 v[30:33], v[134:137], v[232:235], v[30:33]
	v_mfma_f32_16x16x32_bf16 v[26:29], v[142:145], v[232:235], v[26:29]
	v_mfma_f32_16x16x32_bf16 v[14:17], v[134:137], v[240:243], v[14:17]
	v_mfma_f32_16x16x32_bf16 v[10:13], v[142:145], v[240:243], v[10:13]
	s_setprio 0
	s_setprio 1
	v_mfma_f32_16x16x32_bf16 v[54:57], v[146:149], v[180:183], v[54:57]
	v_mfma_f32_16x16x32_bf16 v[50:53], v[154:157], v[180:183], v[50:53]
	v_mfma_f32_16x16x32_bf16 v[38:41], v[146:149], v[220:223], v[38:41]
	v_mfma_f32_16x16x32_bf16 v[34:37], v[154:157], v[220:223], v[34:37]
	v_mfma_f32_16x16x32_bf16 v[22:25], v[146:149], v[228:231], v[22:25]
	v_mfma_f32_16x16x32_bf16 v[18:21], v[154:157], v[228:231], v[18:21]
	v_mfma_f32_16x16x32_bf16 v[6:9], v[146:149], v[236:239], v[6:9]
	v_mfma_f32_16x16x32_bf16 v[2:5], v[154:157], v[236:239], v[2:5]
	v_mfma_f32_16x16x32_bf16 v[54:57], v[150:153], v[184:187], v[54:57]
	v_mfma_f32_16x16x32_bf16 v[50:53], v[158:161], v[184:187], v[50:53]
	v_mfma_f32_16x16x32_bf16 v[38:41], v[150:153], v[224:227], v[38:41]
	v_mfma_f32_16x16x32_bf16 v[34:37], v[158:161], v[224:227], v[34:37]
	v_mfma_f32_16x16x32_bf16 v[22:25], v[150:153], v[232:235], v[22:25]
	v_mfma_f32_16x16x32_bf16 v[18:21], v[158:161], v[232:235], v[18:21]
	v_mfma_f32_16x16x32_bf16 v[6:9], v[150:153], v[240:243], v[6:9]
	v_mfma_f32_16x16x32_bf16 v[2:5], v[158:161], v[240:243], v[2:5]
	s_setprio 0
	s_waitcnt vmcnt(8)
	s_barrier
	s_add_i32 s26, s26, 2
	s_add_u32 s68, s68, 0x100
	s_addc_u32 s69, s69, 0
	s_add_u32 s75, s75, 0x100
	s_addc_u32 s83, s83, 0
	s_cmp_gt_u32 s26, 13
	s_cbranch_scc0 .LBB0_1487
	v_readlane_b32 s26, v255, 55
	v_readlane_b32 s27, v255, 56
	s_and_b64 vcc, exec, s[26:27]
	s_cbranch_vccz .LBB0_1490
	s_barrier

; #define PG8_STAGE(bufoff, gbase, voff) do { _Pragma("unroll") for (int _i = 0; _i < 2; ++_i) \
;         __builtin_amdgcn_global_load_lds((const unsigned*)((const char*)(gbase) + (voff)[_i]), (LAS unsigned*)(lds + (bufoff) + ldsw + _i * 8192), 16, 0, 0); } while (0)
; #define PG8_LDA(dst, b, h) do { _Pragma("unroll") for (int m = 0; m < 4; ++m) _Pragma("unroll") for (int k = 0; k < 2; ++k) dst[m][k] = *(const LAS bf16x8*)(lds + PG8_SA(b, h) + aoff + m * 2048 + k * 1024); } while (0)
; #define PG8_LDB(dst, b, h) do { _Pragma("unroll") for (int n = 0; n < 2; ++n) _Pragma("unroll") for (int k = 0; k < 2; ++k) dst[n][k] = *(const LAS bf16x8*)(lds + PG8_SB(b, h) + boff + n * 2048 + k * 1024); } while (0)
; #define PG8_MMA(ai, bj, At, Bt) do { __builtin_amdgcn_s_setprio(1); _Pragma("unroll") for (int m = 0; m < 4; ++m) _Pragma("unroll") for (int n = 0; n < 2; ++n) _Pragma("unroll") for (int k = 0; k < 2; ++k) \
;         acc[ai][bj][m][n] = __builtin_amdgcn_mfma_f32_16x16x32_bf16(Bt[n][k], At[m][k], acc[ai][bj][m][n], 0, 0, 0); __builtin_amdgcn_s_setprio(0); } while (0)
; #define PG8_WAIT_V(n) asm volatile("s_waitcnt vmcnt(" #n ")" ::: "memory")
; #define PG8_WAIT_L(n) asm volatile("s_waitcnt lgkmcnt(" #n ")" ::: "memory")
; #define PG8_BAR __builtin_amdgcn_s_barrier()
; #define PG8_SCHED __builtin_amdgcn_sched_barrier(0)
; template <class Epi>
; __device__ __forceinline__ void gemm_phase(LAS unsigned char* lds, const int tid, const Gemm g, const StaticOrder& S, const Epi& E) {
;     ...
;             PG8_LDB(B0, 0, 0); PG8_LDB(B1, 0, 1); PG8_SCHED; PG8_LDA(At, 0, 0); PG8_STAGE(PG8_SA(1, 1), a1 + hstepA, voffA);
;             PG8_WAIT_V(8); PG8_WAIT_L(0); PG8_BAR; PG8_MMA(0, 0, At, B0); PG8_MMA(0, 1, At, B1); PG8_BAR; PG8_SCHED;
;             PG8_LDA(At, 0, 1); PG8_STAGE(PG8_SB(0, 0), b2, voffB); PG8_STAGE(PG8_SB(0, 1), b2 + hstepB, voffB); PG8_STAGE(PG8_SA(0, 0), a2, voffA);
.LBB0_1912:
	s_add_u32 s30, s82, 0xfffc0080
	s_addc_u32 s31, s83, -1
	s_add_i32 s92, 0, 0x10000
	s_cmp_eq_u32 s17, 12
	s_cselect_b32 s89, s7, s31
	s_cselect_b32 s88, s65, s30
	s_cselect_b32 s31, s5, s27
	s_cselect_b32 s30, vcc_lo, vcc_hi
	s_add_i32 s11, 0, 0x14000
	v_add_u32_e32 v110, s92, v158
	v_add_u32_e32 v162, s11, v158
	ds_read_b128 v[98:101], v110
	ds_read_b128 v[102:105], v110 offset:1024
	ds_read_b128 v[106:109], v110 offset:2048
	ds_read_b128 v[110:113], v110 offset:3072
	ds_read_b128 v[174:177], v162
	ds_read_b128 v[178:181], v162 offset:1024
	ds_read_b128 v[182:185], v162 offset:2048
	ds_read_b128 v[186:189], v162 offset:3072
	v_lshl_add_u64 v[162:163], s[82:83], 0, v[152:153]
	s_add_i32 m0, s66, 0xc000
	s_nop 0
	global_load_lds_dwordx4 v[162:163], off
	v_lshl_add_u64 v[162:163], s[82:83], 0, v[154:155]
	s_add_i32 m0, s66, 0xe000
	s_nop 0
	global_load_lds_dwordx4 v[162:163], off
	ds_read_b128 v[190:193], v172
	ds_read_b128 v[194:197], v172 offset:1024
	ds_read_b128 v[198:201], v172 offset:2048
	ds_read_b128 v[210:213], v172 offset:3072
	ds_read_b128 v[214:217], v172 offset:4096
	ds_read_b128 v[218:221], v172 offset:5120
	ds_read_b128 v[222:225], v172 offset:6144
	ds_read_b128 v[226:229], v172 offset:7168
	s_cmp_lg_u64 s[2:3], 0
	s_cbranch_scc1 .Lkw_16
	s_waitcnt vmcnt(8)
.Lkw_16:
	s_waitcnt lgkmcnt(0)
	s_barrier
	s_setprio 1
	s_waitcnt lgkmcnt(0)
	v_mfma_f32_16x16x32_bf16 v[142:145], v[98:101], v[190:193], v[142:145]
	v_mfma_f32_16x16x32_bf16 v[138:141], v[106:109], v[190:193], v[138:141]
	v_mfma_f32_16x16x32_bf16 v[134:137], v[98:101], v[198:201], v[134:137]
	v_mfma_f32_16x16x32_bf16 v[130:133], v[106:109], v[198:201], v[130:133]
	v_mfma_f32_16x16x32_bf16 v[94:97], v[98:101], v[214:217], v[94:97]
	v_mfma_f32_16x16x32_bf16 v[90:93], v[106:109], v[214:217], v[90:93]
	v_mfma_f32_16x16x32_bf16 v[78:81], v[98:101], v[222:225], v[78:81]
	v_mfma_f32_16x16x32_bf16 v[74:77], v[106:109], v[222:225], v[74:77]
	v_mfma_f32_16x16x32_bf16 v[142:145], v[102:105], v[194:197], v[142:145]
	v_mfma_f32_16x16x32_bf16 v[138:141], v[110:113], v[194:197], v[138:141]
	v_mfma_f32_16x16x32_bf16 v[134:137], v[102:105], v[210:213], v[134:137]
	v_mfma_f32_16x16x32_bf16 v[130:133], v[110:113], v[210:213], v[130:133]
	v_mfma_f32_16x16x32_bf16 v[94:97], v[102:105], v[218:221], v[94:97]
	v_mfma_f32_16x16x32_bf16 v[90:93], v[110:113], v[218:221], v[90:93]
	v_mfma_f32_16x16x32_bf16 v[78:81], v[102:105], v[226:229], v[78:81]
	v_mfma_f32_16x16x32_bf16 v[74:77], v[110:113], v[226:229], v[74:77]
	s_setprio 0
	s_setprio 1
	v_mfma_f32_16x16x32_bf16 v[126:129], v[174:177], v[190:193], v[126:129]
	v_mfma_f32_16x16x32_bf16 v[122:125], v[182:185], v[190:193], v[122:125]
	v_mfma_f32_16x16x32_bf16 v[118:121], v[174:177], v[198:201], v[118:121]
	v_mfma_f32_16x16x32_bf16 v[114:117], v[182:185], v[198:201], v[114:117]
	v_mfma_f32_16x16x32_bf16 v[86:89], v[174:177], v[214:217], v[86:89]
	v_mfma_f32_16x16x32_bf16 v[82:85], v[182:185], v[214:217], v[82:85]
	v_mfma_f32_16x16x32_bf16 v[70:73], v[174:177], v[222:225], v[70:73]
	v_mfma_f32_16x16x32_bf16 v[66:69], v[182:185], v[222:225], v[66:69]
	v_mfma_f32_16x16x32_bf16 v[126:129], v[178:181], v[194:197], v[126:129]
	v_mfma_f32_16x16x32_bf16 v[122:125], v[186:189], v[194:197], v[122:125]
	v_mfma_f32_16x16x32_bf16 v[118:121], v[178:181], v[210:213], v[118:121]
	v_mfma_f32_16x16x32_bf16 v[114:117], v[186:189], v[210:213], v[114:117]
	v_mfma_f32_16x16x32_bf16 v[86:89], v[178:181], v[218:221], v[86:89]
	v_mfma_f32_16x16x32_bf16 v[82:85], v[186:189], v[218:221], v[82:85]
	v_mfma_f32_16x16x32_bf16 v[70:73], v[178:181], v[226:229], v[70:73]
	v_mfma_f32_16x16x32_bf16 v[66:69], v[186:189], v[226:229], v[66:69]
	s_setprio 0
	s_waitcnt vmcnt(8)
	s_barrier
	s_add_i32 s92, s92, s28
	v_lshl_add_u64 v[162:163], s[30:31], 0, v[0:1]
	s_mov_b32 m0, s92
	s_nop 0
	global_load_lds_dwordx4 v[162:163], off
	s_add_i32 m0, s92, 0x2000
	s_add_u32 s92, s30, 0x40000
	v_lshl_add_u64 v[164:165], s[30:31], 0, v[146:147]
	s_addc_u32 s93, s31, 0
	s_add_i32 s11, s11, s28
	global_load_lds_dwordx4 v[164:165], off
	v_lshl_add_u64 v[202:203], s[92:93], 0, v[0:1]
	s_mov_b32 m0, s11
	v_lshl_add_u64 v[206:207], s[88:89], 0, v[148:149]
	global_load_lds_dwordx4 v[202:203], off
	v_lshl_add_u64 v[202:203], s[92:93], 0, v[146:147]
	s_add_i32 m0, s11, 0x2000
	s_nop 0
	global_load_lds_dwordx4 v[202:203], off
	v_lshl_add_u64 v[202:203], s[88:89], 0, v[150:151]
	s_mov_b32 m0, s66
	s_nop 0
	global_load_lds_dwordx4 v[202:203], off
	s_mov_b32 m0, s67
	s_nop 0
	global_load_lds_dwordx4 v[206:207], off
	ds_read_b128 v[190:193], v172 offset:16384
	ds_read_b128 v[194:197], v172 offset:17408
	ds_read_b128 v[198:201], v172 offset:18432
	ds_read_b128 v[210:213], v172 offset:19456
	ds_read_b128 v[214:217], v172 offset:20480
	ds_read_b128 v[218:221], v172 offset:21504
	ds_read_b128 v[222:225], v172 offset:22528
	ds_read_b128 v[226:229], v172 offset:23552
	s_cmp_lg_u64 s[2:3], 0
	s_cbranch_scc1 .Lkw_15
	s_waitcnt vmcnt(8)
; #define PG8_STAGE(bufoff, gbase, voff) do { _Pragma("unroll") for (int _i = 0; _i < 2; ++_i) \
;         __builtin_amdgcn_global_load_lds((const unsigned*)((const char*)(gbase) + (voff)[_i]), (LAS unsigned*)(lds + (bufoff) + ldsw + _i * 8192), 16, 0, 0); } while (0)
; #define PG8_LDA(dst, b, h) do { _Pragma("unroll") for (int m = 0; m < 4; ++m) _Pragma("unroll") for (int k = 0; k < 2; ++k) dst[m][k] = *(const LAS bf16x8*)(lds + PG8_SA(b, h) + aoff + m * 2048 + k * 1024); } while (0)
; #define PG8_LDB(dst, b, h) do { _Pragma("unroll") for (int n = 0; n < 2; ++n) _Pragma("unroll") for (int k = 0; k < 2; ++k) dst[n][k] = *(const LAS bf16x8*)(lds + PG8_SB(b, h) + boff + n * 2048 + k * 1024); } while (0)
; #define PG8_MMA(ai, bj, At, Bt) do { __builtin_amdgcn_s_setprio(1); _Pragma("unroll") for (int m = 0; m < 4; ++m) _Pragma("unroll") for (int n = 0; n < 2; ++n) _Pragma("unroll") for (int k = 0; k < 2; ++k) \
;         acc[ai][bj][m][n] = __builtin_amdgcn_mfma_f32_16x16x32_bf16(Bt[n][k], At[m][k], acc[ai][bj][m][n], 0, 0, 0); __builtin_amdgcn_s_setprio(0); } while (0)
; #define PG8_WAIT_V(n) asm volatile("s_waitcnt vmcnt(" #n ")" ::: "memory")
; #define PG8_WAIT_L(n) asm volatile("s_waitcnt lgkmcnt(" #n ")" ::: "memory")
; #define PG8_BAR __builtin_amdgcn_s_barrier()
; #define PG8_SCHED __builtin_amdgcn_sched_barrier(0)
; template <class Epi>
; __device__ __forceinline__ void gemm_phase(LAS unsigned char* lds, const int tid, const Gemm g, const StaticOrder& S, const Epi& E) {
;     ...
;             PG8_LDA(At, 0, 1); PG8_STAGE(PG8_SB(0, 0), b2, voffB); PG8_STAGE(PG8_SB(0, 1), b2 + hstepB, voffB); PG8_STAGE(PG8_SA(0, 0), a2, voffA);
;             PG8_WAIT_V(8); PG8_WAIT_L(0); PG8_BAR; PG8_MMA(1, 0, At, B0); PG8_MMA(1, 1, At, B1); PG8_BAR; PG8_SCHED;
;             PG8_LDB(B0, 1, 0); PG8_LDB(B1, 1, 1); PG8_SCHED; PG8_LDA(At, 1, 0); PG8_STAGE(PG8_SA(0, 1), a2 + hstepA, voffA);
;             PG8_WAIT_V(8); PG8_WAIT_L(0); PG8_BAR; PG8_MMA(0, 0, At, B0); PG8_MMA(0, 1, At, B1); PG8_BAR; PG8_SCHED;
.Lkw_15:
	s_waitcnt lgkmcnt(0)
	s_barrier
	s_setprio 1
	s_waitcnt lgkmcnt(0)
	v_mfma_f32_16x16x32_bf16 v[62:65], v[98:101], v[190:193], v[62:65]
	v_mfma_f32_16x16x32_bf16 v[58:61], v[106:109], v[190:193], v[58:61]
	v_mfma_f32_16x16x32_bf16 v[54:57], v[98:101], v[198:201], v[54:57]
	v_mfma_f32_16x16x32_bf16 v[46:49], v[106:109], v[198:201], v[46:49]
	v_mfma_f32_16x16x32_bf16 v[30:33], v[98:101], v[214:217], v[30:33]
	v_mfma_f32_16x16x32_bf16 v[26:29], v[106:109], v[214:217], v[26:29]
	v_mfma_f32_16x16x32_bf16 v[22:25], v[98:101], v[222:225], v[22:25]
	v_mfma_f32_16x16x32_bf16 v[14:17], v[106:109], v[222:225], v[14:17]
	v_mfma_f32_16x16x32_bf16 v[62:65], v[102:105], v[194:197], v[62:65]
	v_mfma_f32_16x16x32_bf16 v[58:61], v[110:113], v[194:197], v[58:61]
	v_mfma_f32_16x16x32_bf16 v[54:57], v[102:105], v[210:213], v[54:57]
	v_mfma_f32_16x16x32_bf16 v[46:49], v[110:113], v[210:213], v[46:49]
	v_mfma_f32_16x16x32_bf16 v[30:33], v[102:105], v[218:221], v[30:33]
	v_mfma_f32_16x16x32_bf16 v[26:29], v[110:113], v[218:221], v[26:29]
	v_mfma_f32_16x16x32_bf16 v[22:25], v[102:105], v[226:229], v[22:25]
	v_mfma_f32_16x16x32_bf16 v[14:17], v[110:113], v[226:229], v[14:17]
	s_setprio 0
	s_setprio 1
	v_mfma_f32_16x16x32_bf16 v[50:53], v[174:177], v[190:193], v[50:53]
	v_mfma_f32_16x16x32_bf16 v[42:45], v[182:185], v[190:193], v[42:45]
	v_mfma_f32_16x16x32_bf16 v[38:41], v[174:177], v[198:201], v[38:41]
	v_mfma_f32_16x16x32_bf16 v[34:37], v[182:185], v[198:201], v[34:37]
	v_mfma_f32_16x16x32_bf16 v[18:21], v[174:177], v[214:217], v[18:21]
	v_mfma_f32_16x16x32_bf16 v[10:13], v[182:185], v[214:217], v[10:13]
	v_mfma_f32_16x16x32_bf16 v[6:9], v[174:177], v[222:225], v[6:9]
	v_mfma_f32_16x16x32_bf16 v[2:5], v[182:185], v[222:225], v[2:5]
	v_mfma_f32_16x16x32_bf16 v[50:53], v[178:181], v[194:197], v[50:53]
	v_mfma_f32_16x16x32_bf16 v[42:45], v[186:189], v[194:197], v[42:45]
	v_mfma_f32_16x16x32_bf16 v[38:41], v[178:181], v[210:213], v[38:41]
	v_mfma_f32_16x16x32_bf16 v[34:37], v[186:189], v[210:213], v[34:37]
	v_mfma_f32_16x16x32_bf16 v[18:21], v[178:181], v[218:221], v[18:21]
	v_mfma_f32_16x16x32_bf16 v[10:13], v[186:189], v[218:221], v[10:13]
	v_mfma_f32_16x16x32_bf16 v[6:9], v[178:181], v[226:229], v[6:9]
	v_mfma_f32_16x16x32_bf16 v[2:5], v[186:189], v[226:229], v[2:5]
	s_setprio 0
	s_waitcnt vmcnt(8)
	s_barrier
	s_add_i32 s11, 0, 0x18000
	s_add_i32 s92, 0, 0x1c000
	v_add_u32_e32 v110, s11, v158
	v_add_u32_e32 v173, s92, v158
	ds_read_b128 v[98:101], v110
	ds_read_b128 v[102:105], v110 offset:1024
	ds_read_b128 v[106:109], v110 offset:2048
	ds_read_b128 v[110:113], v110 offset:3072
	ds_read_b128 v[174:177], v173
	ds_read_b128 v[178:181], v173 offset:1024
	ds_read_b128 v[182:185], v173 offset:2048
	ds_read_b128 v[186:189], v173 offset:3072
	s_add_u32 s88, s88, 0x40000
	s_addc_u32 s89, s89, 0
	s_mov_b32 m0, s70
	v_lshl_add_u64 v[230:231], s[88:89], 0, v[150:151]
	global_load_lds_dwordx4 v[230:231], off
	v_lshl_add_u64 v[230:231], s[88:89], 0, v[148:149]
	s_mov_b32 m0, s71
	s_nop 0
	global_load_lds_dwordx4 v[230:231], off
	ds_read_b128 v[190:193], v172 offset:32768
	ds_read_b128 v[194:197], v172 offset:33792
	ds_read_b128 v[198:201], v172 offset:34816
	ds_read_b128 v[210:213], v172 offset:35840
	ds_read_b128 v[214:217], v172 offset:36864
	ds_read_b128 v[218:221], v172 offset:37888
	ds_read_b128 v[222:225], v172 offset:38912
	ds_read_b128 v[226:229], v172 offset:39936
	s_cmp_lg_u64 s[2:3], 0
	s_cbranch_scc1 .Lkw_14
	s_waitcnt vmcnt(8)
; #define PG8_STAGE(bufoff, gbase, voff) do { _Pragma("unroll") for (int _i = 0; _i < 2; ++_i) \
;         __builtin_amdgcn_global_load_lds((const unsigned*)((const char*)(gbase) + (voff)[_i]), (LAS unsigned*)(lds + (bufoff) + ldsw + _i * 8192), 16, 0, 0); } while (0)
; #define PG8_LDA(dst, b, h) do { _Pragma("unroll") for (int m = 0; m < 4; ++m) _Pragma("unroll") for (int k = 0; k < 2; ++k) dst[m][k] = *(const LAS bf16x8*)(lds + PG8_SA(b, h) + aoff + m * 2048 + k * 1024); } while (0)
; #define PG8_MMA(ai, bj, At, Bt) do { __builtin_amdgcn_s_setprio(1); _Pragma("unroll") for (int m = 0; m < 4; ++m) _Pragma("unroll") for (int n = 0; n < 2; ++n) _Pragma("unroll") for (int k = 0; k < 2; ++k) \
;         acc[ai][bj][m][n] = __builtin_amdgcn_mfma_f32_16x16x32_bf16(Bt[n][k], At[m][k], acc[ai][bj][m][n], 0, 0, 0); __builtin_amdgcn_s_setprio(0); } while (0)
; #define PG8_WAIT_V(n) asm volatile("s_waitcnt vmcnt(" #n ")" ::: "memory")
; #define PG8_WAIT_L(n) asm volatile("s_waitcnt lgkmcnt(" #n ")" ::: "memory")
; #define PG8_BAR __builtin_amdgcn_s_barrier()
; #define PG8_SCHED __builtin_amdgcn_sched_barrier(0)
; template <class Epi>
; __device__ __forceinline__ void gemm_phase(LAS unsigned char* lds, const int tid, const Gemm g, const StaticOrder& S, const Epi& E) {
;     ...
;             PG8_WAIT_V(8); PG8_WAIT_L(0); PG8_BAR; PG8_MMA(0, 0, At, B0); PG8_MMA(0, 1, At, B1); PG8_BAR; PG8_SCHED;
;             PG8_LDA(At, 1, 1); PG8_STAGE(PG8_SB(1, 0), b3, voffB); PG8_STAGE(PG8_SB(1, 1), b3 + hstepB, voffB); PG8_STAGE(PG8_SA(1, 0), a3, voffA);
;             PG8_WAIT_V(8); PG8_WAIT_L(0); PG8_BAR; PG8_MMA(1, 0, At, B0); PG8_MMA(1, 1, At, B1); PG8_BAR; PG8_SCHED;
;         }
;         if (wr == 0) PG8_BAR;
.Lkw_14:
	s_waitcnt lgkmcnt(0)
	s_barrier
	s_setprio 1
	s_waitcnt lgkmcnt(0)
	v_mfma_f32_16x16x32_bf16 v[142:145], v[98:101], v[190:193], v[142:145]
	v_mfma_f32_16x16x32_bf16 v[138:141], v[106:109], v[190:193], v[138:141]
	v_mfma_f32_16x16x32_bf16 v[134:137], v[98:101], v[198:201], v[134:137]
	v_mfma_f32_16x16x32_bf16 v[130:133], v[106:109], v[198:201], v[130:133]
	v_mfma_f32_16x16x32_bf16 v[94:97], v[98:101], v[214:217], v[94:97]
	v_mfma_f32_16x16x32_bf16 v[90:93], v[106:109], v[214:217], v[90:93]
	v_mfma_f32_16x16x32_bf16 v[78:81], v[98:101], v[222:225], v[78:81]
	v_mfma_f32_16x16x32_bf16 v[74:77], v[106:109], v[222:225], v[74:77]
	v_mfma_f32_16x16x32_bf16 v[142:145], v[102:105], v[194:197], v[142:145]
	v_mfma_f32_16x16x32_bf16 v[138:141], v[110:113], v[194:197], v[138:141]
	v_mfma_f32_16x16x32_bf16 v[134:137], v[102:105], v[210:213], v[134:137]
	v_mfma_f32_16x16x32_bf16 v[130:133], v[110:113], v[210:213], v[130:133]
	v_mfma_f32_16x16x32_bf16 v[94:97], v[102:105], v[218:221], v[94:97]
	v_mfma_f32_16x16x32_bf16 v[90:93], v[110:113], v[218:221], v[90:93]
	v_mfma_f32_16x16x32_bf16 v[78:81], v[102:105], v[226:229], v[78:81]
	v_mfma_f32_16x16x32_bf16 v[74:77], v[110:113], v[226:229], v[74:77]
	s_setprio 0
	s_setprio 1
	v_mfma_f32_16x16x32_bf16 v[126:129], v[174:177], v[190:193], v[126:129]
	v_mfma_f32_16x16x32_bf16 v[122:125], v[182:185], v[190:193], v[122:125]
	v_mfma_f32_16x16x32_bf16 v[118:121], v[174:177], v[198:201], v[118:121]
	v_mfma_f32_16x16x32_bf16 v[114:117], v[182:185], v[198:201], v[114:117]
	v_mfma_f32_16x16x32_bf16 v[86:89], v[174:177], v[214:217], v[86:89]
	v_mfma_f32_16x16x32_bf16 v[82:85], v[182:185], v[214:217], v[82:85]
	v_mfma_f32_16x16x32_bf16 v[70:73], v[174:177], v[222:225], v[70:73]
	v_mfma_f32_16x16x32_bf16 v[66:69], v[182:185], v[222:225], v[66:69]
	v_mfma_f32_16x16x32_bf16 v[126:129], v[178:181], v[194:197], v[126:129]
	v_mfma_f32_16x16x32_bf16 v[122:125], v[186:189], v[194:197], v[122:125]
	v_mfma_f32_16x16x32_bf16 v[118:121], v[178:181], v[210:213], v[118:121]
	v_mfma_f32_16x16x32_bf16 v[114:117], v[186:189], v[210:213], v[114:117]
	v_mfma_f32_16x16x32_bf16 v[86:89], v[178:181], v[218:221], v[86:89]
	v_mfma_f32_16x16x32_bf16 v[82:85], v[186:189], v[218:221], v[82:85]
	v_mfma_f32_16x16x32_bf16 v[70:73], v[178:181], v[226:229], v[70:73]
	v_mfma_f32_16x16x32_bf16 v[66:69], v[186:189], v[226:229], v[66:69]
	s_setprio 0
	s_waitcnt vmcnt(8)
	s_barrier
	s_add_i32 s11, s11, s28
	v_lshl_add_u64 v[162:163], v[162:163], 0, s[36:37]
	s_mov_b32 m0, s11
	s_nop 0
	global_load_lds_dwordx4 v[162:163], off
	s_add_i32 m0, s11, 0x2000
	s_add_u32 s30, s30, 0x40080
	v_lshl_add_u64 v[162:163], v[164:165], 0, s[36:37]
	s_addc_u32 s31, s31, 0
	s_add_i32 s11, s92, s28
	global_load_lds_dwordx4 v[162:163], off
	v_lshl_add_u64 v[162:163], s[30:31], 0, v[0:1]
	s_mov_b32 m0, s11
	s_nop 0
	global_load_lds_dwordx4 v[162:163], off
	v_lshl_add_u64 v[162:163], s[30:31], 0, v[146:147]
	s_add_i32 m0, s11, 0x2000
	s_nop 0
	global_load_lds_dwordx4 v[162:163], off
	v_lshl_add_u64 v[162:163], v[202:203], 0, s[36:37]
	s_mov_b32 m0, s72
	s_nop 0
	global_load_lds_dwordx4 v[162:163], off
	v_lshl_add_u64 v[162:163], v[206:207], 0, s[36:37]
	s_mov_b32 m0, s73
	s_nop 0
	global_load_lds_dwordx4 v[162:163], off
	ds_read_b128 v[190:193], v172 offset:49152
	ds_read_b128 v[194:197], v172 offset:50176
	ds_read_b128 v[198:201], v172 offset:51200
	ds_read_b128 v[210:213], v172 offset:52224
	ds_read_b128 v[214:217], v172 offset:53248
	ds_read_b128 v[218:221], v172 offset:54272
	ds_read_b128 v[222:225], v172 offset:55296
	ds_read_b128 v[226:229], v172 offset:56320
	s_cmp_lg_u64 s[2:3], 0
	s_cbranch_scc1 .Lkw_13
	s_waitcnt vmcnt(8)
.Lkw_13:
	s_waitcnt lgkmcnt(0)
	s_barrier
	s_setprio 1
	s_waitcnt lgkmcnt(0)
	v_mfma_f32_16x16x32_bf16 v[62:65], v[98:101], v[190:193], v[62:65]
	v_mfma_f32_16x16x32_bf16 v[58:61], v[106:109], v[190:193], v[58:61]
	v_mfma_f32_16x16x32_bf16 v[54:57], v[98:101], v[198:201], v[54:57]
	v_mfma_f32_16x16x32_bf16 v[46:49], v[106:109], v[198:201], v[46:49]
	v_mfma_f32_16x16x32_bf16 v[30:33], v[98:101], v[214:217], v[30:33]
	v_mfma_f32_16x16x32_bf16 v[26:29], v[106:109], v[214:217], v[26:29]
	v_mfma_f32_16x16x32_bf16 v[22:25], v[98:101], v[222:225], v[22:25]
	v_mfma_f32_16x16x32_bf16 v[14:17], v[106:109], v[222:225], v[14:17]
	v_mfma_f32_16x16x32_bf16 v[62:65], v[102:105], v[194:197], v[62:65]
	v_mfma_f32_16x16x32_bf16 v[58:61], v[110:113], v[194:197], v[58:61]
	v_mfma_f32_16x16x32_bf16 v[54:57], v[102:105], v[210:213], v[54:57]
	v_mfma_f32_16x16x32_bf16 v[46:49], v[110:113], v[210:213], v[46:49]
	v_mfma_f32_16x16x32_bf16 v[30:33], v[102:105], v[218:221], v[30:33]
	v_mfma_f32_16x16x32_bf16 v[26:29], v[110:113], v[218:221], v[26:29]
	v_mfma_f32_16x16x32_bf16 v[22:25], v[102:105], v[226:229], v[22:25]
	v_mfma_f32_16x16x32_bf16 v[14:17], v[110:113], v[226:229], v[14:17]
	s_setprio 0
	s_setprio 1
	v_mfma_f32_16x16x32_bf16 v[50:53], v[174:177], v[190:193], v[50:53]
	v_mfma_f32_16x16x32_bf16 v[42:45], v[182:185], v[190:193], v[42:45]
	v_mfma_f32_16x16x32_bf16 v[38:41], v[174:177], v[198:201], v[38:41]
	v_mfma_f32_16x16x32_bf16 v[34:37], v[182:185], v[198:201], v[34:37]
	v_mfma_f32_16x16x32_bf16 v[18:21], v[174:177], v[214:217], v[18:21]
	v_mfma_f32_16x16x32_bf16 v[10:13], v[182:185], v[214:217], v[10:13]
	v_mfma_f32_16x16x32_bf16 v[6:9], v[174:177], v[222:225], v[6:9]
	v_mfma_f32_16x16x32_bf16 v[2:5], v[182:185], v[222:225], v[2:5]
	v_mfma_f32_16x16x32_bf16 v[50:53], v[178:181], v[194:197], v[50:53]
	v_mfma_f32_16x16x32_bf16 v[42:45], v[186:189], v[194:197], v[42:45]
	v_mfma_f32_16x16x32_bf16 v[38:41], v[178:181], v[210:213], v[38:41]
	v_mfma_f32_16x16x32_bf16 v[34:37], v[186:189], v[210:213], v[34:37]
	v_mfma_f32_16x16x32_bf16 v[18:21], v[178:181], v[218:221], v[18:21]
	v_mfma_f32_16x16x32_bf16 v[10:13], v[186:189], v[218:221], v[10:13]
	v_mfma_f32_16x16x32_bf16 v[6:9], v[178:181], v[226:229], v[6:9]
	v_mfma_f32_16x16x32_bf16 v[2:5], v[186:189], v[226:229], v[2:5]
	s_setprio 0
	s_waitcnt vmcnt(8)
	s_barrier
	s_add_i32 s17, s17, 2
	s_add_u32 s82, s82, 0x100
	s_addc_u32 s83, s83, 0
	s_add_u32 vcc_hi, vcc_hi, 0x100
	s_addc_u32 s27, s27, 0
	s_cmp_gt_u32 s17, 13
	s_cbranch_scc0 .LBB0_1912
	s_and_b64 vcc, exec, s[2:3]
	s_cbranch_vccz .LBB0_1915
	s_barrier

; #define PG8_STAGE(bufoff, gbase, voff) do { _Pragma("unroll") for (int _i = 0; _i < 2; ++_i) \
;         __builtin_amdgcn_global_load_lds((const unsigned*)((const char*)(gbase) + (voff)[_i]), (LAS unsigned*)(lds + (bufoff) + ldsw + _i * 8192), 16, 0, 0); } while (0)
; #define PG8_LDA(dst, b, h) do { _Pragma("unroll") for (int m = 0; m < 4; ++m) _Pragma("unroll") for (int k = 0; k < 2; ++k) dst[m][k] = *(const LAS bf16x8*)(lds + PG8_SA(b, h) + aoff + m * 2048 + k * 1024); } while (0)
; #define PG8_LDB(dst, b, h) do { _Pragma("unroll") for (int n = 0; n < 2; ++n) _Pragma("unroll") for (int k = 0; k < 2; ++k) dst[n][k] = *(const LAS bf16x8*)(lds + PG8_SB(b, h) + boff + n * 2048 + k * 1024); } while (0)
; #define PG8_MMA(ai, bj, At, Bt) do { __builtin_amdgcn_s_setprio(1); _Pragma("unroll") for (int m = 0; m < 4; ++m) _Pragma("unroll") for (int n = 0; n < 2; ++n) _Pragma("unroll") for (int k = 0; k < 2; ++k) \
;         acc[ai][bj][m][n] = __builtin_amdgcn_mfma_f32_16x16x32_bf16(Bt[n][k], At[m][k], acc[ai][bj][m][n], 0, 0, 0); __builtin_amdgcn_s_setprio(0); } while (0)
; #define PG8_WAIT_V(n) asm volatile("s_waitcnt vmcnt(" #n ")" ::: "memory")
; #define PG8_WAIT_L(n) asm volatile("s_waitcnt lgkmcnt(" #n ")" ::: "memory")
; #define PG8_BAR __builtin_amdgcn_s_barrier()
; #define PG8_SCHED __builtin_amdgcn_sched_barrier(0)
; template <class Epi>
; __device__ __forceinline__ void gemm_phase(LAS unsigned char* lds, const int tid, const Gemm g, const StaticOrder& S, const Epi& E) {
;     ...
;             PG8_LDB(B0, 0, 0); PG8_LDB(B1, 0, 1); PG8_SCHED; PG8_LDA(At, 0, 0); PG8_STAGE(PG8_SA(1, 1), a1 + hstepA, voffA);
;             PG8_WAIT_V(8); PG8_WAIT_L(0); PG8_BAR; PG8_MMA(0, 0, At, B0); PG8_MMA(0, 1, At, B1); PG8_BAR; PG8_SCHED;
;             PG8_LDA(At, 0, 1); PG8_STAGE(PG8_SB(0, 0), b2, voffB); PG8_STAGE(PG8_SB(0, 1), b2 + hstepB, voffB); PG8_STAGE(PG8_SA(0, 0), a2, voffA);
.LBB0_2193:
	s_add_u32 s70, s30, 0x100
	s_addc_u32 s71, s31, 0
	s_add_i32 s76, 0, 0x10000
	s_cmp_eq_u32 vcc_hi, 40
	s_cselect_b32 s75, s1, s71
	s_cselect_b32 s74, s0, s70
	s_cselect_b32 s73, s69, vcc_lo
	s_cselect_b32 s72, s68, s28
	s_add_i32 s2, 0, 0x14000
	v_add_u32_e32 v154, s76, v179
	v_add_u32_e32 v162, s2, v179
	ds_read_b128 v[130:133], v154
	ds_read_b128 v[134:137], v154 offset:1024
	ds_read_b128 v[138:141], v154 offset:2048
	ds_read_b128 v[154:157], v154 offset:3072
	ds_read_b128 v[158:161], v162
	ds_read_b128 v[170:173], v162 offset:1024
	ds_read_b128 v[174:177], v162 offset:2048
	ds_read_b128 v[184:187], v162 offset:3072
	v_lshl_add_u64 v[162:163], s[30:31], 0, v[150:151]
	s_add_i32 m0, s5, 0xc000
	s_nop 0
	global_load_lds_dwordx4 v[162:163], off
	v_lshl_add_u64 v[162:163], s[30:31], 0, v[152:153]
	s_add_i32 m0, s5, 0xe000
	s_nop 0
	global_load_lds_dwordx4 v[162:163], off
	ds_read_b128 v[188:191], v181
	ds_read_b128 v[192:195], v181 offset:1024
	ds_read_b128 v[196:199], v181 offset:2048
	ds_read_b128 v[200:203], v181 offset:3072
	ds_read_b128 v[212:215], v181 offset:4096
	ds_read_b128 v[216:219], v181 offset:5120
	ds_read_b128 v[220:223], v181 offset:6144
	ds_read_b128 v[224:227], v181 offset:7168
	s_cmp_lg_u64 s[26:27], 0
	s_cbranch_scc1 .Lkw_12
	s_waitcnt vmcnt(8)
.Lkw_12:
	s_waitcnt lgkmcnt(0)
	s_barrier
	s_setprio 1
	s_waitcnt lgkmcnt(0)
	v_mfma_f32_16x16x32_bf16 v[126:129], v[130:133], v[188:191], v[126:129]
	v_mfma_f32_16x16x32_bf16 v[122:125], v[138:141], v[188:191], v[122:125]
	v_mfma_f32_16x16x32_bf16 v[110:113], v[130:133], v[196:199], v[110:113]
	v_mfma_f32_16x16x32_bf16 v[106:109], v[138:141], v[196:199], v[106:109]
	v_mfma_f32_16x16x32_bf16 v[94:97], v[130:133], v[212:215], v[94:97]
	v_mfma_f32_16x16x32_bf16 v[90:93], v[138:141], v[212:215], v[90:93]
	v_mfma_f32_16x16x32_bf16 v[78:81], v[130:133], v[220:223], v[78:81]
	v_mfma_f32_16x16x32_bf16 v[74:77], v[138:141], v[220:223], v[74:77]
	v_mfma_f32_16x16x32_bf16 v[126:129], v[134:137], v[192:195], v[126:129]
	v_mfma_f32_16x16x32_bf16 v[122:125], v[154:157], v[192:195], v[122:125]
	v_mfma_f32_16x16x32_bf16 v[110:113], v[134:137], v[200:203], v[110:113]
	v_mfma_f32_16x16x32_bf16 v[106:109], v[154:157], v[200:203], v[106:109]
	v_mfma_f32_16x16x32_bf16 v[94:97], v[134:137], v[216:219], v[94:97]
	v_mfma_f32_16x16x32_bf16 v[90:93], v[154:157], v[216:219], v[90:93]
	v_mfma_f32_16x16x32_bf16 v[78:81], v[134:137], v[224:227], v[78:81]
	v_mfma_f32_16x16x32_bf16 v[74:77], v[154:157], v[224:227], v[74:77]
	s_setprio 0
	s_setprio 1
	v_mfma_f32_16x16x32_bf16 v[118:121], v[158:161], v[188:191], v[118:121]
	v_mfma_f32_16x16x32_bf16 v[114:117], v[174:177], v[188:191], v[114:117]
	v_mfma_f32_16x16x32_bf16 v[102:105], v[158:161], v[196:199], v[102:105]
	v_mfma_f32_16x16x32_bf16 v[98:101], v[174:177], v[196:199], v[98:101]
	v_mfma_f32_16x16x32_bf16 v[86:89], v[158:161], v[212:215], v[86:89]
	v_mfma_f32_16x16x32_bf16 v[82:85], v[174:177], v[212:215], v[82:85]
	v_mfma_f32_16x16x32_bf16 v[70:73], v[158:161], v[220:223], v[70:73]
	v_mfma_f32_16x16x32_bf16 v[66:69], v[174:177], v[220:223], v[66:69]
	v_mfma_f32_16x16x32_bf16 v[118:121], v[170:173], v[192:195], v[118:121]
	v_mfma_f32_16x16x32_bf16 v[114:117], v[184:187], v[192:195], v[114:117]
	v_mfma_f32_16x16x32_bf16 v[102:105], v[170:173], v[200:203], v[102:105]
	v_mfma_f32_16x16x32_bf16 v[98:101], v[184:187], v[200:203], v[98:101]
	v_mfma_f32_16x16x32_bf16 v[86:89], v[170:173], v[216:219], v[86:89]
	v_mfma_f32_16x16x32_bf16 v[82:85], v[184:187], v[216:219], v[82:85]
	v_mfma_f32_16x16x32_bf16 v[70:73], v[170:173], v[224:227], v[70:73]
	v_mfma_f32_16x16x32_bf16 v[66:69], v[184:187], v[224:227], v[66:69]
	s_setprio 0
	s_waitcnt vmcnt(8)
	s_barrier
	s_add_i32 s3, s76, s4
	v_lshl_add_u64 v[162:163], s[72:73], 0, v[0:1]
	s_mov_b32 m0, s3
	s_nop 0
	global_load_lds_dwordx4 v[162:163], off
	s_add_i32 m0, s3, 0x2000
	s_add_u32 s30, s72, 0xb0000
	v_lshl_add_u64 v[164:165], s[72:73], 0, v[148:149]
	s_addc_u32 s31, s73, 0
	s_add_i32 s2, s2, s4
	global_load_lds_dwordx4 v[164:165], off
	v_lshl_add_u64 v[206:207], s[30:31], 0, v[0:1]
	s_mov_b32 m0, s2
	v_lshl_add_u64 v[228:229], s[74:75], 0, v[144:145]
	global_load_lds_dwordx4 v[206:207], off
	v_lshl_add_u64 v[206:207], s[30:31], 0, v[148:149]
	s_add_i32 m0, s2, 0x2000
	s_nop 0
	global_load_lds_dwordx4 v[206:207], off
	v_lshl_add_u64 v[206:207], s[74:75], 0, v[142:143]
	s_mov_b32 m0, s5
	s_nop 0
	global_load_lds_dwordx4 v[206:207], off
	s_mov_b32 m0, s6
	s_nop 0
	global_load_lds_dwordx4 v[228:229], off
	ds_read_b128 v[188:191], v181 offset:16384
	ds_read_b128 v[192:195], v181 offset:17408
	ds_read_b128 v[196:199], v181 offset:18432
	ds_read_b128 v[200:203], v181 offset:19456
	ds_read_b128 v[212:215], v181 offset:20480
	ds_read_b128 v[216:219], v181 offset:21504
	ds_read_b128 v[220:223], v181 offset:22528
	ds_read_b128 v[224:227], v181 offset:23552
	s_cmp_lg_u64 s[26:27], 0
	s_cbranch_scc1 .Lkw_11
	s_waitcnt vmcnt(8)
; #define PG8_STAGE(bufoff, gbase, voff) do { _Pragma("unroll") for (int _i = 0; _i < 2; ++_i) \
;         __builtin_amdgcn_global_load_lds((const unsigned*)((const char*)(gbase) + (voff)[_i]), (LAS unsigned*)(lds + (bufoff) + ldsw + _i * 8192), 16, 0, 0); } while (0)
; #define PG8_LDA(dst, b, h) do { _Pragma("unroll") for (int m = 0; m < 4; ++m) _Pragma("unroll") for (int k = 0; k < 2; ++k) dst[m][k] = *(const LAS bf16x8*)(lds + PG8_SA(b, h) + aoff + m * 2048 + k * 1024); } while (0)
; #define PG8_LDB(dst, b, h) do { _Pragma("unroll") for (int n = 0; n < 2; ++n) _Pragma("unroll") for (int k = 0; k < 2; ++k) dst[n][k] = *(const LAS bf16x8*)(lds + PG8_SB(b, h) + boff + n * 2048 + k * 1024); } while (0)
; #define PG8_MMA(ai, bj, At, Bt) do { __builtin_amdgcn_s_setprio(1); _Pragma("unroll") for (int m = 0; m < 4; ++m) _Pragma("unroll") for (int n = 0; n < 2; ++n) _Pragma("unroll") for (int k = 0; k < 2; ++k) \
;         acc[ai][bj][m][n] = __builtin_amdgcn_mfma_f32_16x16x32_bf16(Bt[n][k], At[m][k], acc[ai][bj][m][n], 0, 0, 0); __builtin_amdgcn_s_setprio(0); } while (0)
; #define PG8_WAIT_V(n) asm volatile("s_waitcnt vmcnt(" #n ")" ::: "memory")
; #define PG8_WAIT_L(n) asm volatile("s_waitcnt lgkmcnt(" #n ")" ::: "memory")
; #define PG8_BAR __builtin_amdgcn_s_barrier()
; #define PG8_SCHED __builtin_amdgcn_sched_barrier(0)
; template <class Epi>
; __device__ __forceinline__ void gemm_phase(LAS unsigned char* lds, const int tid, const Gemm g, const StaticOrder& S, const Epi& E) {
;     ...
;             PG8_WAIT_V(8); PG8_WAIT_L(0); PG8_BAR; PG8_MMA(1, 0, At, B0); PG8_MMA(1, 1, At, B1); PG8_BAR; PG8_SCHED;
;             PG8_LDB(B0, 1, 0); PG8_LDB(B1, 1, 1); PG8_SCHED; PG8_LDA(At, 1, 0); PG8_STAGE(PG8_SA(0, 1), a2 + hstepA, voffA);
;             PG8_WAIT_V(8); PG8_WAIT_L(0); PG8_BAR; PG8_MMA(0, 0, At, B0); PG8_MMA(0, 1, At, B1); PG8_BAR; PG8_SCHED;
.Lkw_11:
	s_waitcnt lgkmcnt(0)
	s_barrier
	s_setprio 1
	s_waitcnt lgkmcnt(0)
	v_mfma_f32_16x16x32_bf16 v[62:65], v[130:133], v[188:191], v[62:65]
	v_mfma_f32_16x16x32_bf16 v[58:61], v[138:141], v[188:191], v[58:61]
	v_mfma_f32_16x16x32_bf16 v[46:49], v[130:133], v[196:199], v[46:49]
	v_mfma_f32_16x16x32_bf16 v[42:45], v[138:141], v[196:199], v[42:45]
	v_mfma_f32_16x16x32_bf16 v[30:33], v[130:133], v[212:215], v[30:33]
	v_mfma_f32_16x16x32_bf16 v[26:29], v[138:141], v[212:215], v[26:29]
	v_mfma_f32_16x16x32_bf16 v[14:17], v[130:133], v[220:223], v[14:17]
	v_mfma_f32_16x16x32_bf16 v[10:13], v[138:141], v[220:223], v[10:13]
	v_mfma_f32_16x16x32_bf16 v[62:65], v[134:137], v[192:195], v[62:65]
	v_mfma_f32_16x16x32_bf16 v[58:61], v[154:157], v[192:195], v[58:61]
	v_mfma_f32_16x16x32_bf16 v[46:49], v[134:137], v[200:203], v[46:49]
	v_mfma_f32_16x16x32_bf16 v[42:45], v[154:157], v[200:203], v[42:45]
	v_mfma_f32_16x16x32_bf16 v[30:33], v[134:137], v[216:219], v[30:33]
	v_mfma_f32_16x16x32_bf16 v[26:29], v[154:157], v[216:219], v[26:29]
	v_mfma_f32_16x16x32_bf16 v[14:17], v[134:137], v[224:227], v[14:17]
	v_mfma_f32_16x16x32_bf16 v[10:13], v[154:157], v[224:227], v[10:13]
	s_setprio 0
	s_setprio 1
	v_mfma_f32_16x16x32_bf16 v[54:57], v[158:161], v[188:191], v[54:57]
	v_mfma_f32_16x16x32_bf16 v[50:53], v[174:177], v[188:191], v[50:53]
	v_mfma_f32_16x16x32_bf16 v[38:41], v[158:161], v[196:199], v[38:41]
	v_mfma_f32_16x16x32_bf16 v[34:37], v[174:177], v[196:199], v[34:37]
	v_mfma_f32_16x16x32_bf16 v[22:25], v[158:161], v[212:215], v[22:25]
	v_mfma_f32_16x16x32_bf16 v[18:21], v[174:177], v[212:215], v[18:21]
	v_mfma_f32_16x16x32_bf16 v[6:9], v[158:161], v[220:223], v[6:9]
	v_mfma_f32_16x16x32_bf16 v[2:5], v[174:177], v[220:223], v[2:5]
	v_mfma_f32_16x16x32_bf16 v[54:57], v[170:173], v[192:195], v[54:57]
	v_mfma_f32_16x16x32_bf16 v[50:53], v[184:187], v[192:195], v[50:53]
	v_mfma_f32_16x16x32_bf16 v[38:41], v[170:173], v[200:203], v[38:41]
	v_mfma_f32_16x16x32_bf16 v[34:37], v[184:187], v[200:203], v[34:37]
	v_mfma_f32_16x16x32_bf16 v[22:25], v[170:173], v[216:219], v[22:25]
	v_mfma_f32_16x16x32_bf16 v[18:21], v[184:187], v[216:219], v[18:21]
	v_mfma_f32_16x16x32_bf16 v[6:9], v[170:173], v[224:227], v[6:9]
	v_mfma_f32_16x16x32_bf16 v[2:5], v[184:187], v[224:227], v[2:5]
	s_setprio 0
	s_waitcnt vmcnt(8)
	s_barrier
	s_add_i32 s2, 0, 0x18000
	s_add_i32 s3, 0, 0x1c000
	v_add_u32_e32 v154, s2, v179
	v_add_u32_e32 v183, s3, v179
	ds_read_b128 v[130:133], v154
	ds_read_b128 v[134:137], v154 offset:1024
	ds_read_b128 v[138:141], v154 offset:2048
	ds_read_b128 v[154:157], v154 offset:3072
	ds_read_b128 v[158:161], v183
	ds_read_b128 v[170:173], v183 offset:1024
	ds_read_b128 v[174:177], v183 offset:2048
	ds_read_b128 v[184:187], v183 offset:3072
	s_add_u32 s30, s74, 0x160000
	s_addc_u32 s31, s75, 0
	s_mov_b32 m0, s7
	v_lshl_add_u64 v[230:231], s[30:31], 0, v[142:143]
	global_load_lds_dwordx4 v[230:231], off
	v_lshl_add_u64 v[230:231], s[30:31], 0, v[144:145]
	s_mov_b32 m0, s77
	s_nop 0
	global_load_lds_dwordx4 v[230:231], off
	ds_read_b128 v[188:191], v181 offset:32768
	ds_read_b128 v[192:195], v181 offset:33792
	ds_read_b128 v[196:199], v181 offset:34816
	ds_read_b128 v[200:203], v181 offset:35840
	ds_read_b128 v[212:215], v181 offset:36864
	ds_read_b128 v[216:219], v181 offset:37888
	ds_read_b128 v[220:223], v181 offset:38912
	ds_read_b128 v[224:227], v181 offset:39936
	s_cmp_lg_u64 s[26:27], 0
	s_cbranch_scc1 .Lkw_10
	s_waitcnt vmcnt(8)
; #define PG8_STAGE(bufoff, gbase, voff) do { _Pragma("unroll") for (int _i = 0; _i < 2; ++_i) \
;         __builtin_amdgcn_global_load_lds((const unsigned*)((const char*)(gbase) + (voff)[_i]), (LAS unsigned*)(lds + (bufoff) + ldsw + _i * 8192), 16, 0, 0); } while (0)
; #define PG8_LDA(dst, b, h) do { _Pragma("unroll") for (int m = 0; m < 4; ++m) _Pragma("unroll") for (int k = 0; k < 2; ++k) dst[m][k] = *(const LAS bf16x8*)(lds + PG8_SA(b, h) + aoff + m * 2048 + k * 1024); } while (0)
; #define PG8_MMA(ai, bj, At, Bt) do { __builtin_amdgcn_s_setprio(1); _Pragma("unroll") for (int m = 0; m < 4; ++m) _Pragma("unroll") for (int n = 0; n < 2; ++n) _Pragma("unroll") for (int k = 0; k < 2; ++k) \
;         acc[ai][bj][m][n] = __builtin_amdgcn_mfma_f32_16x16x32_bf16(Bt[n][k], At[m][k], acc[ai][bj][m][n], 0, 0, 0); __builtin_amdgcn_s_setprio(0); } while (0)
; #define PG8_WAIT_V(n) asm volatile("s_waitcnt vmcnt(" #n ")" ::: "memory")
; #define PG8_WAIT_L(n) asm volatile("s_waitcnt lgkmcnt(" #n ")" ::: "memory")
; #define PG8_BAR __builtin_amdgcn_s_barrier()
; #define PG8_SCHED __builtin_amdgcn_sched_barrier(0)
; template <class Epi>
; __device__ __forceinline__ void gemm_phase(LAS unsigned char* lds, const int tid, const Gemm g, const StaticOrder& S, const Epi& E) {
;     ...
;             PG8_WAIT_V(8); PG8_WAIT_L(0); PG8_BAR; PG8_MMA(0, 0, At, B0); PG8_MMA(0, 1, At, B1); PG8_BAR; PG8_SCHED;
;             PG8_LDA(At, 1, 1); PG8_STAGE(PG8_SB(1, 0), b3, voffB); PG8_STAGE(PG8_SB(1, 1), b3 + hstepB, voffB); PG8_STAGE(PG8_SA(1, 0), a3, voffA);
;             PG8_WAIT_V(8); PG8_WAIT_L(0); PG8_BAR; PG8_MMA(1, 0, At, B0); PG8_MMA(1, 1, At, B1); PG8_BAR; PG8_SCHED;
;         }
;         if (wr == 0) PG8_BAR;
.Lkw_10:
	s_waitcnt lgkmcnt(0)
	s_barrier
	s_setprio 1
	s_waitcnt lgkmcnt(0)
	v_mfma_f32_16x16x32_bf16 v[126:129], v[130:133], v[188:191], v[126:129]
	v_mfma_f32_16x16x32_bf16 v[122:125], v[138:141], v[188:191], v[122:125]
	v_mfma_f32_16x16x32_bf16 v[110:113], v[130:133], v[196:199], v[110:113]
	v_mfma_f32_16x16x32_bf16 v[106:109], v[138:141], v[196:199], v[106:109]
	v_mfma_f32_16x16x32_bf16 v[94:97], v[130:133], v[212:215], v[94:97]
	v_mfma_f32_16x16x32_bf16 v[90:93], v[138:141], v[212:215], v[90:93]
	v_mfma_f32_16x16x32_bf16 v[78:81], v[130:133], v[220:223], v[78:81]
	v_mfma_f32_16x16x32_bf16 v[74:77], v[138:141], v[220:223], v[74:77]
	v_mfma_f32_16x16x32_bf16 v[126:129], v[134:137], v[192:195], v[126:129]
	v_mfma_f32_16x16x32_bf16 v[122:125], v[154:157], v[192:195], v[122:125]
	v_mfma_f32_16x16x32_bf16 v[110:113], v[134:137], v[200:203], v[110:113]
	v_mfma_f32_16x16x32_bf16 v[106:109], v[154:157], v[200:203], v[106:109]
	v_mfma_f32_16x16x32_bf16 v[94:97], v[134:137], v[216:219], v[94:97]
	v_mfma_f32_16x16x32_bf16 v[90:93], v[154:157], v[216:219], v[90:93]
	v_mfma_f32_16x16x32_bf16 v[78:81], v[134:137], v[224:227], v[78:81]
	v_mfma_f32_16x16x32_bf16 v[74:77], v[154:157], v[224:227], v[74:77]
	s_setprio 0
	s_setprio 1
	v_mfma_f32_16x16x32_bf16 v[118:121], v[158:161], v[188:191], v[118:121]
	v_mfma_f32_16x16x32_bf16 v[114:117], v[174:177], v[188:191], v[114:117]
	v_mfma_f32_16x16x32_bf16 v[102:105], v[158:161], v[196:199], v[102:105]
	v_mfma_f32_16x16x32_bf16 v[98:101], v[174:177], v[196:199], v[98:101]
	v_mfma_f32_16x16x32_bf16 v[86:89], v[158:161], v[212:215], v[86:89]
	v_mfma_f32_16x16x32_bf16 v[82:85], v[174:177], v[212:215], v[82:85]
	v_mfma_f32_16x16x32_bf16 v[70:73], v[158:161], v[220:223], v[70:73]
	v_mfma_f32_16x16x32_bf16 v[66:69], v[174:177], v[220:223], v[66:69]
	v_mfma_f32_16x16x32_bf16 v[118:121], v[170:173], v[192:195], v[118:121]
	v_mfma_f32_16x16x32_bf16 v[114:117], v[184:187], v[192:195], v[114:117]
	v_mfma_f32_16x16x32_bf16 v[102:105], v[170:173], v[200:203], v[102:105]
	v_mfma_f32_16x16x32_bf16 v[98:101], v[184:187], v[200:203], v[98:101]
	v_mfma_f32_16x16x32_bf16 v[86:89], v[170:173], v[216:219], v[86:89]
	v_mfma_f32_16x16x32_bf16 v[82:85], v[184:187], v[216:219], v[82:85]
	v_mfma_f32_16x16x32_bf16 v[70:73], v[170:173], v[224:227], v[70:73]
	v_mfma_f32_16x16x32_bf16 v[66:69], v[184:187], v[224:227], v[66:69]
	s_setprio 0
	s_waitcnt vmcnt(8)
	s_barrier
	s_add_i32 s2, s2, s4
	v_lshl_add_u64 v[162:163], v[162:163], 0, s[36:37]
	s_mov_b32 m0, s2
	s_nop 0
	global_load_lds_dwordx4 v[162:163], off
	s_add_i32 m0, s2, 0x2000
	s_add_u32 s30, s72, 0xb0080
	v_lshl_add_u64 v[162:163], v[164:165], 0, s[36:37]
	s_addc_u32 s31, s73, 0
	s_add_i32 s2, s3, s4
	global_load_lds_dwordx4 v[162:163], off
	v_lshl_add_u64 v[162:163], s[30:31], 0, v[0:1]
	s_mov_b32 m0, s2
	s_nop 0
	global_load_lds_dwordx4 v[162:163], off
	v_lshl_add_u64 v[162:163], s[30:31], 0, v[148:149]
	s_add_i32 m0, s2, 0x2000
	s_nop 0
	global_load_lds_dwordx4 v[162:163], off
	v_lshl_add_u64 v[162:163], v[206:207], 0, s[36:37]
	s_mov_b32 m0, s83
	s_nop 0
	global_load_lds_dwordx4 v[162:163], off
	v_lshl_add_u64 v[162:163], v[228:229], 0, s[36:37]
	s_mov_b32 m0, s88
	s_nop 0
	global_load_lds_dwordx4 v[162:163], off
	ds_read_b128 v[188:191], v181 offset:49152
	ds_read_b128 v[192:195], v181 offset:50176
	ds_read_b128 v[196:199], v181 offset:51200
	ds_read_b128 v[200:203], v181 offset:52224
	ds_read_b128 v[212:215], v181 offset:53248
	ds_read_b128 v[216:219], v181 offset:54272
	ds_read_b128 v[220:223], v181 offset:55296
	ds_read_b128 v[224:227], v181 offset:56320
	s_cmp_lg_u64 s[26:27], 0
	s_cbranch_scc1 .Lkw_9
	s_waitcnt vmcnt(8)
.Lkw_9:
	s_waitcnt lgkmcnt(0)
	s_barrier
	s_setprio 1
	s_waitcnt lgkmcnt(0)
	v_mfma_f32_16x16x32_bf16 v[62:65], v[130:133], v[188:191], v[62:65]
	v_mfma_f32_16x16x32_bf16 v[58:61], v[138:141], v[188:191], v[58:61]
	v_mfma_f32_16x16x32_bf16 v[46:49], v[130:133], v[196:199], v[46:49]
	v_mfma_f32_16x16x32_bf16 v[42:45], v[138:141], v[196:199], v[42:45]
	v_mfma_f32_16x16x32_bf16 v[30:33], v[130:133], v[212:215], v[30:33]
	v_mfma_f32_16x16x32_bf16 v[26:29], v[138:141], v[212:215], v[26:29]
	v_mfma_f32_16x16x32_bf16 v[14:17], v[130:133], v[220:223], v[14:17]
	v_mfma_f32_16x16x32_bf16 v[10:13], v[138:141], v[220:223], v[10:13]
	v_mfma_f32_16x16x32_bf16 v[62:65], v[134:137], v[192:195], v[62:65]
	v_mfma_f32_16x16x32_bf16 v[58:61], v[154:157], v[192:195], v[58:61]
	v_mfma_f32_16x16x32_bf16 v[46:49], v[134:137], v[200:203], v[46:49]
	v_mfma_f32_16x16x32_bf16 v[42:45], v[154:157], v[200:203], v[42:45]
	v_mfma_f32_16x16x32_bf16 v[30:33], v[134:137], v[216:219], v[30:33]
	v_mfma_f32_16x16x32_bf16 v[26:29], v[154:157], v[216:219], v[26:29]
	v_mfma_f32_16x16x32_bf16 v[14:17], v[134:137], v[224:227], v[14:17]
	v_mfma_f32_16x16x32_bf16 v[10:13], v[154:157], v[224:227], v[10:13]
	s_setprio 0
	s_setprio 1
	v_mfma_f32_16x16x32_bf16 v[54:57], v[158:161], v[188:191], v[54:57]
	v_mfma_f32_16x16x32_bf16 v[50:53], v[174:177], v[188:191], v[50:53]
	v_mfma_f32_16x16x32_bf16 v[38:41], v[158:161], v[196:199], v[38:41]
	v_mfma_f32_16x16x32_bf16 v[34:37], v[174:177], v[196:199], v[34:37]
	v_mfma_f32_16x16x32_bf16 v[22:25], v[158:161], v[212:215], v[22:25]
	v_mfma_f32_16x16x32_bf16 v[18:21], v[174:177], v[212:215], v[18:21]
	v_mfma_f32_16x16x32_bf16 v[6:9], v[158:161], v[220:223], v[6:9]
	v_mfma_f32_16x16x32_bf16 v[2:5], v[174:177], v[220:223], v[2:5]
	v_mfma_f32_16x16x32_bf16 v[54:57], v[170:173], v[192:195], v[54:57]
	v_mfma_f32_16x16x32_bf16 v[50:53], v[184:187], v[192:195], v[50:53]
	v_mfma_f32_16x16x32_bf16 v[38:41], v[170:173], v[200:203], v[38:41]
	v_mfma_f32_16x16x32_bf16 v[34:37], v[184:187], v[200:203], v[34:37]
	v_mfma_f32_16x16x32_bf16 v[22:25], v[170:173], v[216:219], v[22:25]
	v_mfma_f32_16x16x32_bf16 v[18:21], v[184:187], v[216:219], v[18:21]
	v_mfma_f32_16x16x32_bf16 v[6:9], v[170:173], v[224:227], v[6:9]
	v_mfma_f32_16x16x32_bf16 v[2:5], v[184:187], v[224:227], v[2:5]
	s_setprio 0
	s_waitcnt vmcnt(8)
	s_barrier
	s_add_i32 vcc_hi, vcc_hi, 2
	s_add_u32 s28, s28, 0x100
	s_addc_u32 vcc_lo, vcc_lo, 0
	s_cmp_gt_u32 vcc_hi, 41
	s_mov_b64 s[30:31], s[70:71]
	s_cbranch_scc0 .LBB0_2193
	s_and_b64 vcc, exec, s[26:27]
	s_cbranch_vccz .LBB0_2196
	s_barrier

; #define PG8_STAGE(bufoff, gbase, voff) do { _Pragma("unroll") for (int _i = 0; _i < 2; ++_i) \
;         __builtin_amdgcn_global_load_lds((const unsigned*)((const char*)(gbase) + (voff)[_i]), (LAS unsigned*)(lds + (bufoff) + ldsw + _i * 8192), 16, 0, 0); } while (0)
; #define PG8_LDA(dst, b, h) do { _Pragma("unroll") for (int m = 0; m < 4; ++m) _Pragma("unroll") for (int k = 0; k < 2; ++k) dst[m][k] = *(const LAS bf16x8*)(lds + PG8_SA(b, h) + aoff + m * 2048 + k * 1024); } while (0)
; #define PG8_LDB(dst, b, h) do { _Pragma("unroll") for (int n = 0; n < 2; ++n) _Pragma("unroll") for (int k = 0; k < 2; ++k) dst[n][k] = *(const LAS bf16x8*)(lds + PG8_SB(b, h) + boff + n * 2048 + k * 1024); } while (0)
; #define PG8_MMA(ai, bj, At, Bt) do { __builtin_amdgcn_s_setprio(1); _Pragma("unroll") for (int m = 0; m < 4; ++m) _Pragma("unroll") for (int n = 0; n < 2; ++n) _Pragma("unroll") for (int k = 0; k < 2; ++k) \
;         acc[ai][bj][m][n] = __builtin_amdgcn_mfma_f32_16x16x32_bf16(Bt[n][k], At[m][k], acc[ai][bj][m][n], 0, 0, 0); __builtin_amdgcn_s_setprio(0); } while (0)
; #define PG8_WAIT_V(n) asm volatile("s_waitcnt vmcnt(" #n ")" ::: "memory")
; #define PG8_WAIT_L(n) asm volatile("s_waitcnt lgkmcnt(" #n ")" ::: "memory")
; #define PG8_BAR __builtin_amdgcn_s_barrier()
; #define PG8_SCHED __builtin_amdgcn_sched_barrier(0)
; template <class Epi>
; __device__ __forceinline__ void gemm_phase(LAS unsigned char* lds, const int tid, const Gemm g, const StaticOrder& S, const Epi& E) {
;     ...
;         for (int t = 0; t < nt; t += 2) {
;             const bool last = (t == nt - 2);
;             const char* a1 = cA + (size_t)(t + 1) * kstep;
;             const char* a2 = last ? nA : cA + (size_t)(t + 2) * kstep; const char* b2 = last ? nB : cB + (size_t)(t + 2) * kstep;
;             const char* a3 = a2 + kstep; const char* b3 = b2 + kstep;
;             PG8_LDB(B0, 0, 0); PG8_LDB(B1, 0, 1); PG8_SCHED; PG8_LDA(At, 0, 0); PG8_STAGE(PG8_SA(1, 1), a1 + hstepA, voffA);
;             PG8_WAIT_V(8); PG8_WAIT_L(0); PG8_BAR; PG8_MMA(0, 0, At, B0); PG8_MMA(0, 1, At, B1); PG8_BAR; PG8_SCHED;
;             PG8_LDA(At, 0, 1); PG8_STAGE(PG8_SB(0, 0), b2, voffB); PG8_STAGE(PG8_SB(0, 1), b2 + hstepB, voffB); PG8_STAGE(PG8_SA(0, 0), a2, voffA);
;             PG8_WAIT_V(8); PG8_WAIT_L(0); PG8_BAR; PG8_MMA(1, 0, At, B0); PG8_MMA(1, 1, At, B1); PG8_BAR; PG8_SCHED;
.LBB0_2303:
	s_add_u32 s68, s66, 0x100
	s_addc_u32 s69, s67, 0
	s_add_i32 s76, 0, 0x10000
	s_cmp_eq_u32 s93, 40
	s_cselect_b32 s73, s1, s69
	s_cselect_b32 s72, s0, s68
	s_cselect_b32 s71, s31, s28
	s_cselect_b32 s70, s30, s11
	s_add_i32 vcc_lo, 0, 0x14000
	v_add_u32_e32 v70, s76, v212
	v_add_u32_e32 v162, vcc_lo, v212
	ds_read_b128 v[42:45], v70
	ds_read_b128 v[46:49], v70 offset:1024
	ds_read_b128 v[66:69], v70 offset:2048
	ds_read_b128 v[70:73], v70 offset:3072
	ds_read_b128 v[158:161], v162
	ds_read_b128 v[170:173], v162 offset:1024
	ds_read_b128 v[174:177], v162 offset:2048
	ds_read_b128 v[178:181], v162 offset:3072
	v_lshl_add_u64 v[162:163], s[66:67], 0, v[154:155]
	s_add_i32 m0, s5, 0xc000
	s_nop 0
	global_load_lds_dwordx4 v[162:163], off
	v_lshl_add_u64 v[162:163], s[66:67], 0, v[156:157]
	s_add_i32 m0, s5, 0xe000
	s_nop 0
	global_load_lds_dwordx4 v[162:163], off
	ds_read_b128 v[182:185], v214
	ds_read_b128 v[186:189], v214 offset:1024
	ds_read_b128 v[190:193], v214 offset:2048
	ds_read_b128 v[194:197], v214 offset:3072
	ds_read_b128 v[198:201], v214 offset:4096
	ds_read_b128 v[216:219], v214 offset:5120
	ds_read_b128 v[220:223], v214 offset:6144
	ds_read_b128 v[224:227], v214 offset:7168
	s_cmp_lg_u64 s[26:27], 0
	s_cbranch_scc1 .Lkw_8
	s_waitcnt vmcnt(8)
.Lkw_8:
	s_waitcnt lgkmcnt(0)
	s_barrier
	s_setprio 1
	s_waitcnt lgkmcnt(0)
	v_mfma_f32_16x16x32_bf16 v[142:145], v[42:45], v[182:185], v[142:145]
	v_mfma_f32_16x16x32_bf16 v[138:141], v[66:69], v[182:185], v[138:141]
	v_mfma_f32_16x16x32_bf16 v[126:129], v[42:45], v[190:193], v[126:129]
	v_mfma_f32_16x16x32_bf16 v[122:125], v[66:69], v[190:193], v[122:125]
	v_mfma_f32_16x16x32_bf16 v[110:113], v[42:45], v[198:201], v[110:113]
	v_mfma_f32_16x16x32_bf16 v[106:109], v[66:69], v[198:201], v[106:109]
	v_mfma_f32_16x16x32_bf16 v[94:97], v[42:45], v[220:223], v[94:97]
	v_mfma_f32_16x16x32_bf16 v[90:93], v[66:69], v[220:223], v[90:93]
	v_mfma_f32_16x16x32_bf16 v[142:145], v[46:49], v[186:189], v[142:145]
	v_mfma_f32_16x16x32_bf16 v[138:141], v[70:73], v[186:189], v[138:141]
	v_mfma_f32_16x16x32_bf16 v[126:129], v[46:49], v[194:197], v[126:129]
	v_mfma_f32_16x16x32_bf16 v[122:125], v[70:73], v[194:197], v[122:125]
	v_mfma_f32_16x16x32_bf16 v[110:113], v[46:49], v[216:219], v[110:113]
	v_mfma_f32_16x16x32_bf16 v[106:109], v[70:73], v[216:219], v[106:109]
	v_mfma_f32_16x16x32_bf16 v[94:97], v[46:49], v[224:227], v[94:97]
	v_mfma_f32_16x16x32_bf16 v[90:93], v[70:73], v[224:227], v[90:93]
	s_setprio 0
	s_setprio 1
	v_mfma_f32_16x16x32_bf16 v[134:137], v[158:161], v[182:185], v[134:137]
	v_mfma_f32_16x16x32_bf16 v[130:133], v[174:177], v[182:185], v[130:133]
	v_mfma_f32_16x16x32_bf16 v[118:121], v[158:161], v[190:193], v[118:121]
	v_mfma_f32_16x16x32_bf16 v[114:117], v[174:177], v[190:193], v[114:117]
	v_mfma_f32_16x16x32_bf16 v[102:105], v[158:161], v[198:201], v[102:105]
	v_mfma_f32_16x16x32_bf16 v[98:101], v[174:177], v[198:201], v[98:101]
	v_mfma_f32_16x16x32_bf16 v[86:89], v[158:161], v[220:223], v[86:89]
	v_mfma_f32_16x16x32_bf16 v[82:85], v[174:177], v[220:223], v[82:85]
	v_mfma_f32_16x16x32_bf16 v[134:137], v[170:173], v[186:189], v[134:137]
	v_mfma_f32_16x16x32_bf16 v[130:133], v[178:181], v[186:189], v[130:133]
	v_mfma_f32_16x16x32_bf16 v[118:121], v[170:173], v[194:197], v[118:121]
	v_mfma_f32_16x16x32_bf16 v[114:117], v[178:181], v[194:197], v[114:117]
	v_mfma_f32_16x16x32_bf16 v[102:105], v[170:173], v[216:219], v[102:105]
	v_mfma_f32_16x16x32_bf16 v[98:101], v[178:181], v[216:219], v[98:101]
	v_mfma_f32_16x16x32_bf16 v[86:89], v[170:173], v[224:227], v[86:89]
	v_mfma_f32_16x16x32_bf16 v[82:85], v[178:181], v[224:227], v[82:85]
	s_setprio 0
	s_waitcnt vmcnt(8)
	s_barrier
	s_add_i32 s66, s76, s4
	v_lshl_add_u64 v[162:163], s[70:71], 0, v[0:1]
	s_mov_b32 m0, s66
	s_nop 0
	global_load_lds_dwordx4 v[162:163], off
	s_add_i32 m0, s66, 0x2000
	s_add_u32 s66, s70, 0xb0000
	v_lshl_add_u64 v[164:165], s[70:71], 0, v[152:153]
	s_addc_u32 s67, s71, 0
	s_add_i32 s76, vcc_lo, s4
	global_load_lds_dwordx4 v[164:165], off
	v_lshl_add_u64 v[202:203], s[66:67], 0, v[0:1]
	s_mov_b32 m0, s76
	v_lshl_add_u64 v[206:207], s[72:73], 0, v[150:151]
	global_load_lds_dwordx4 v[202:203], off
	v_lshl_add_u64 v[202:203], s[66:67], 0, v[152:153]
	s_add_i32 m0, s76, 0x2000
	s_nop 0
	global_load_lds_dwordx4 v[202:203], off
	v_lshl_add_u64 v[202:203], s[72:73], 0, v[148:149]
	s_mov_b32 m0, s5
	s_nop 0
	global_load_lds_dwordx4 v[202:203], off
	s_mov_b32 m0, s6
	s_nop 0
	global_load_lds_dwordx4 v[206:207], off
	ds_read_b128 v[182:185], v214 offset:16384
	ds_read_b128 v[186:189], v214 offset:17408
	ds_read_b128 v[190:193], v214 offset:18432
	ds_read_b128 v[194:197], v214 offset:19456
	ds_read_b128 v[198:201], v214 offset:20480
	ds_read_b128 v[216:219], v214 offset:21504
	ds_read_b128 v[220:223], v214 offset:22528
	ds_read_b128 v[224:227], v214 offset:23552
	s_cmp_lg_u64 s[26:27], 0
	s_cbranch_scc1 .Lkw_7
	s_waitcnt vmcnt(8)
; #define PG8_STAGE(bufoff, gbase, voff) do { _Pragma("unroll") for (int _i = 0; _i < 2; ++_i) \
;         __builtin_amdgcn_global_load_lds((const unsigned*)((const char*)(gbase) + (voff)[_i]), (LAS unsigned*)(lds + (bufoff) + ldsw + _i * 8192), 16, 0, 0); } while (0)
; #define PG8_LDA(dst, b, h) do { _Pragma("unroll") for (int m = 0; m < 4; ++m) _Pragma("unroll") for (int k = 0; k < 2; ++k) dst[m][k] = *(const LAS bf16x8*)(lds + PG8_SA(b, h) + aoff + m * 2048 + k * 1024); } while (0)
; #define PG8_LDB(dst, b, h) do { _Pragma("unroll") for (int n = 0; n < 2; ++n) _Pragma("unroll") for (int k = 0; k < 2; ++k) dst[n][k] = *(const LAS bf16x8*)(lds + PG8_SB(b, h) + boff + n * 2048 + k * 1024); } while (0)
; #define PG8_MMA(ai, bj, At, Bt) do { __builtin_amdgcn_s_setprio(1); _Pragma("unroll") for (int m = 0; m < 4; ++m) _Pragma("unroll") for (int n = 0; n < 2; ++n) _Pragma("unroll") for (int k = 0; k < 2; ++k) \
;         acc[ai][bj][m][n] = __builtin_amdgcn_mfma_f32_16x16x32_bf16(Bt[n][k], At[m][k], acc[ai][bj][m][n], 0, 0, 0); __builtin_amdgcn_s_setprio(0); } while (0)
; #define PG8_WAIT_V(n) asm volatile("s_waitcnt vmcnt(" #n ")" ::: "memory")
; #define PG8_WAIT_L(n) asm volatile("s_waitcnt lgkmcnt(" #n ")" ::: "memory")
; #define PG8_BAR __builtin_amdgcn_s_barrier()
; #define PG8_SCHED __builtin_amdgcn_sched_barrier(0)
; template <class Epi>
; __device__ __forceinline__ void gemm_phase(LAS unsigned char* lds, const int tid, const Gemm g, const StaticOrder& S, const Epi& E) {
;     ...
;             PG8_WAIT_V(8); PG8_WAIT_L(0); PG8_BAR; PG8_MMA(1, 0, At, B0); PG8_MMA(1, 1, At, B1); PG8_BAR; PG8_SCHED;
;             PG8_LDB(B0, 1, 0); PG8_LDB(B1, 1, 1); PG8_SCHED; PG8_LDA(At, 1, 0); PG8_STAGE(PG8_SA(0, 1), a2 + hstepA, voffA);
;             PG8_WAIT_V(8); PG8_WAIT_L(0); PG8_BAR; PG8_MMA(0, 0, At, B0); PG8_MMA(0, 1, At, B1); PG8_BAR; PG8_SCHED;
.Lkw_7:
	s_waitcnt lgkmcnt(0)
	s_barrier
	s_setprio 1
	s_waitcnt lgkmcnt(0)
	v_mfma_f32_16x16x32_bf16 v[78:81], v[42:45], v[182:185], v[78:81]
	v_mfma_f32_16x16x32_bf16 v[74:77], v[66:69], v[182:185], v[74:77]
	v_mfma_f32_16x16x32_bf16 v[54:57], v[42:45], v[190:193], v[54:57]
	v_mfma_f32_16x16x32_bf16 v[50:53], v[66:69], v[190:193], v[50:53]
	v_mfma_f32_16x16x32_bf16 v[30:33], v[42:45], v[198:201], v[30:33]
	v_mfma_f32_16x16x32_bf16 v[26:29], v[66:69], v[198:201], v[26:29]
	v_mfma_f32_16x16x32_bf16 v[14:17], v[42:45], v[220:223], v[14:17]
	v_mfma_f32_16x16x32_bf16 v[10:13], v[66:69], v[220:223], v[10:13]
	v_mfma_f32_16x16x32_bf16 v[78:81], v[46:49], v[186:189], v[78:81]
	v_mfma_f32_16x16x32_bf16 v[74:77], v[70:73], v[186:189], v[74:77]
	v_mfma_f32_16x16x32_bf16 v[54:57], v[46:49], v[194:197], v[54:57]
	v_mfma_f32_16x16x32_bf16 v[50:53], v[70:73], v[194:197], v[50:53]
	v_mfma_f32_16x16x32_bf16 v[30:33], v[46:49], v[216:219], v[30:33]
	v_mfma_f32_16x16x32_bf16 v[26:29], v[70:73], v[216:219], v[26:29]
	v_mfma_f32_16x16x32_bf16 v[14:17], v[46:49], v[224:227], v[14:17]
	v_mfma_f32_16x16x32_bf16 v[10:13], v[70:73], v[224:227], v[10:13]
	s_setprio 0
	s_setprio 1
	v_mfma_f32_16x16x32_bf16 v[38:41], v[158:161], v[190:193], v[38:41]
	v_mfma_f32_16x16x32_bf16 v[34:37], v[174:177], v[190:193], v[34:37]
	v_mfma_f32_16x16x32_bf16 v[22:25], v[158:161], v[198:201], v[22:25]
	v_mfma_f32_16x16x32_bf16 v[18:21], v[174:177], v[198:201], v[18:21]
	v_mfma_f32_16x16x32_bf16 v[6:9], v[158:161], v[220:223], v[6:9]
	v_mfma_f32_16x16x32_bf16 v[2:5], v[174:177], v[220:223], v[2:5]
	v_mfma_f32_16x16x32_bf16 v[42:45], v[158:161], v[182:185], v[62:65]
	v_mfma_f32_16x16x32_bf16 v[46:49], v[174:177], v[182:185], v[58:61]
	v_mfma_f32_16x16x32_bf16 v[38:41], v[170:173], v[194:197], v[38:41]
	v_mfma_f32_16x16x32_bf16 v[34:37], v[178:181], v[194:197], v[34:37]
	v_mfma_f32_16x16x32_bf16 v[22:25], v[170:173], v[216:219], v[22:25]
	v_mfma_f32_16x16x32_bf16 v[18:21], v[178:181], v[216:219], v[18:21]
	v_mfma_f32_16x16x32_bf16 v[6:9], v[170:173], v[224:227], v[6:9]
	v_mfma_f32_16x16x32_bf16 v[2:5], v[178:181], v[224:227], v[2:5]
	v_mfma_f32_16x16x32_bf16 v[42:45], v[170:173], v[186:189], v[42:45]
	v_mfma_f32_16x16x32_bf16 v[46:49], v[178:181], v[186:189], v[46:49]
	s_setprio 0
	s_waitcnt vmcnt(8)
	s_barrier
	s_add_i32 s76, 0, 0x18000
	s_add_i32 vcc_lo, 0, 0x1c000
	v_add_u32_e32 v70, s76, v212
	v_add_u32_e32 v178, vcc_lo, v212
	ds_read_b128 v[58:61], v70
	ds_read_b128 v[62:65], v70 offset:1024
	ds_read_b128 v[66:69], v70 offset:2048
	ds_read_b128 v[70:73], v70 offset:3072
	ds_read_b128 v[158:161], v178
	ds_read_b128 v[170:173], v178 offset:1024
	ds_read_b128 v[174:177], v178 offset:2048
	ds_read_b128 v[178:181], v178 offset:3072
	s_add_u32 s66, s72, 0x160000
	s_addc_u32 s67, s73, 0
	s_mov_b32 m0, s7
	v_lshl_add_u64 v[228:229], s[66:67], 0, v[148:149]
	global_load_lds_dwordx4 v[228:229], off
	v_lshl_add_u64 v[228:229], s[66:67], 0, v[150:151]
	s_mov_b32 m0, s74
	s_nop 0
	global_load_lds_dwordx4 v[228:229], off
	ds_read_b128 v[182:185], v214 offset:32768
	ds_read_b128 v[186:189], v214 offset:33792
	ds_read_b128 v[190:193], v214 offset:34816
	ds_read_b128 v[194:197], v214 offset:35840
	ds_read_b128 v[198:201], v214 offset:36864
	ds_read_b128 v[216:219], v214 offset:37888
	ds_read_b128 v[220:223], v214 offset:38912
	ds_read_b128 v[224:227], v214 offset:39936
	s_cmp_lg_u64 s[26:27], 0
	s_cbranch_scc1 .Lkw_6
	s_waitcnt vmcnt(8)
; #define PG8_STAGE(bufoff, gbase, voff) do { _Pragma("unroll") for (int _i = 0; _i < 2; ++_i) \
;         __builtin_amdgcn_global_load_lds((const unsigned*)((const char*)(gbase) + (voff)[_i]), (LAS unsigned*)(lds + (bufoff) + ldsw + _i * 8192), 16, 0, 0); } while (0)
; #define PG8_LDA(dst, b, h) do { _Pragma("unroll") for (int m = 0; m < 4; ++m) _Pragma("unroll") for (int k = 0; k < 2; ++k) dst[m][k] = *(const LAS bf16x8*)(lds + PG8_SA(b, h) + aoff + m * 2048 + k * 1024); } while (0)
; #define PG8_MMA(ai, bj, At, Bt) do { __builtin_amdgcn_s_setprio(1); _Pragma("unroll") for (int m = 0; m < 4; ++m) _Pragma("unroll") for (int n = 0; n < 2; ++n) _Pragma("unroll") for (int k = 0; k < 2; ++k) \
;         acc[ai][bj][m][n] = __builtin_amdgcn_mfma_f32_16x16x32_bf16(Bt[n][k], At[m][k], acc[ai][bj][m][n], 0, 0, 0); __builtin_amdgcn_s_setprio(0); } while (0)
; #define PG8_WAIT_V(n) asm volatile("s_waitcnt vmcnt(" #n ")" ::: "memory")
; #define PG8_WAIT_L(n) asm volatile("s_waitcnt lgkmcnt(" #n ")" ::: "memory")
; #define PG8_BAR __builtin_amdgcn_s_barrier()
; #define PG8_SCHED __builtin_amdgcn_sched_barrier(0)
; template <class Epi>
; __device__ __forceinline__ void gemm_phase(LAS unsigned char* lds, const int tid, const Gemm g, const StaticOrder& S, const Epi& E) {
;     ...
;             PG8_WAIT_V(8); PG8_WAIT_L(0); PG8_BAR; PG8_MMA(0, 0, At, B0); PG8_MMA(0, 1, At, B1); PG8_BAR; PG8_SCHED;
;             PG8_LDA(At, 1, 1); PG8_STAGE(PG8_SB(1, 0), b3, voffB); PG8_STAGE(PG8_SB(1, 1), b3 + hstepB, voffB); PG8_STAGE(PG8_SA(1, 0), a3, voffA);
;             PG8_WAIT_V(8); PG8_WAIT_L(0); PG8_BAR; PG8_MMA(1, 0, At, B0); PG8_MMA(1, 1, At, B1); PG8_BAR; PG8_SCHED;
;         }
;         if (wr == 0) PG8_BAR;
.Lkw_6:
	s_waitcnt lgkmcnt(0)
	s_barrier
	s_setprio 1
	s_waitcnt lgkmcnt(0)
	v_mfma_f32_16x16x32_bf16 v[142:145], v[58:61], v[182:185], v[142:145]
	v_mfma_f32_16x16x32_bf16 v[138:141], v[66:69], v[182:185], v[138:141]
	v_mfma_f32_16x16x32_bf16 v[126:129], v[58:61], v[190:193], v[126:129]
	v_mfma_f32_16x16x32_bf16 v[122:125], v[66:69], v[190:193], v[122:125]
	v_mfma_f32_16x16x32_bf16 v[110:113], v[58:61], v[198:201], v[110:113]
	v_mfma_f32_16x16x32_bf16 v[106:109], v[66:69], v[198:201], v[106:109]
	v_mfma_f32_16x16x32_bf16 v[94:97], v[58:61], v[220:223], v[94:97]
	v_mfma_f32_16x16x32_bf16 v[90:93], v[66:69], v[220:223], v[90:93]
	v_mfma_f32_16x16x32_bf16 v[142:145], v[62:65], v[186:189], v[142:145]
	v_mfma_f32_16x16x32_bf16 v[138:141], v[70:73], v[186:189], v[138:141]
	v_mfma_f32_16x16x32_bf16 v[126:129], v[62:65], v[194:197], v[126:129]
	v_mfma_f32_16x16x32_bf16 v[122:125], v[70:73], v[194:197], v[122:125]
	v_mfma_f32_16x16x32_bf16 v[110:113], v[62:65], v[216:219], v[110:113]
	v_mfma_f32_16x16x32_bf16 v[106:109], v[70:73], v[216:219], v[106:109]
	v_mfma_f32_16x16x32_bf16 v[94:97], v[62:65], v[224:227], v[94:97]
	v_mfma_f32_16x16x32_bf16 v[90:93], v[70:73], v[224:227], v[90:93]
	s_setprio 0
	s_setprio 1
	v_mfma_f32_16x16x32_bf16 v[134:137], v[158:161], v[182:185], v[134:137]
	v_mfma_f32_16x16x32_bf16 v[130:133], v[174:177], v[182:185], v[130:133]
	v_mfma_f32_16x16x32_bf16 v[118:121], v[158:161], v[190:193], v[118:121]
	v_mfma_f32_16x16x32_bf16 v[114:117], v[174:177], v[190:193], v[114:117]
	v_mfma_f32_16x16x32_bf16 v[102:105], v[158:161], v[198:201], v[102:105]
	v_mfma_f32_16x16x32_bf16 v[98:101], v[174:177], v[198:201], v[98:101]
	v_mfma_f32_16x16x32_bf16 v[86:89], v[158:161], v[220:223], v[86:89]
	v_mfma_f32_16x16x32_bf16 v[82:85], v[174:177], v[220:223], v[82:85]
	v_mfma_f32_16x16x32_bf16 v[134:137], v[170:173], v[186:189], v[134:137]
	v_mfma_f32_16x16x32_bf16 v[130:133], v[178:181], v[186:189], v[130:133]
	v_mfma_f32_16x16x32_bf16 v[118:121], v[170:173], v[194:197], v[118:121]
	v_mfma_f32_16x16x32_bf16 v[114:117], v[178:181], v[194:197], v[114:117]
	v_mfma_f32_16x16x32_bf16 v[102:105], v[170:173], v[216:219], v[102:105]
	v_mfma_f32_16x16x32_bf16 v[98:101], v[178:181], v[216:219], v[98:101]
	v_mfma_f32_16x16x32_bf16 v[86:89], v[170:173], v[224:227], v[86:89]
	v_mfma_f32_16x16x32_bf16 v[82:85], v[178:181], v[224:227], v[82:85]
	s_setprio 0
	s_waitcnt vmcnt(8)
	s_barrier
	s_add_i32 s66, s76, s4
	v_lshl_add_u64 v[162:163], v[162:163], 0, s[36:37]
	s_mov_b32 m0, s66
	s_nop 0
	global_load_lds_dwordx4 v[162:163], off
	s_add_i32 m0, s66, 0x2000
	s_add_u32 s66, s70, 0xb0080
	v_lshl_add_u64 v[162:163], v[164:165], 0, s[36:37]
	s_addc_u32 s67, s71, 0
	s_add_i32 s70, vcc_lo, s4
	global_load_lds_dwordx4 v[162:163], off
	v_lshl_add_u64 v[162:163], s[66:67], 0, v[0:1]
	s_mov_b32 m0, s70
	s_nop 0
	global_load_lds_dwordx4 v[162:163], off
	v_lshl_add_u64 v[162:163], s[66:67], 0, v[152:153]
	s_add_i32 m0, s70, 0x2000
	s_nop 0
	global_load_lds_dwordx4 v[162:163], off
	v_lshl_add_u64 v[162:163], v[202:203], 0, s[36:37]
	s_mov_b32 m0, s77
	s_nop 0
	global_load_lds_dwordx4 v[162:163], off
	v_lshl_add_u64 v[162:163], v[206:207], 0, s[36:37]
	s_mov_b32 m0, s79
	s_nop 0
	global_load_lds_dwordx4 v[162:163], off
	ds_read_b128 v[182:185], v214 offset:49152
	ds_read_b128 v[186:189], v214 offset:50176
	ds_read_b128 v[190:193], v214 offset:51200
	ds_read_b128 v[194:197], v214 offset:52224
	ds_read_b128 v[198:201], v214 offset:53248
	ds_read_b128 v[216:219], v214 offset:54272
	ds_read_b128 v[220:223], v214 offset:55296
	ds_read_b128 v[224:227], v214 offset:56320
	s_cmp_lg_u64 s[26:27], 0
	s_cbranch_scc1 .Lkw_5
	s_waitcnt vmcnt(8)
.Lkw_5:
	s_waitcnt lgkmcnt(0)
	s_barrier
	s_setprio 1
	s_waitcnt lgkmcnt(0)
	v_mfma_f32_16x16x32_bf16 v[78:81], v[58:61], v[182:185], v[78:81]
	v_mfma_f32_16x16x32_bf16 v[74:77], v[66:69], v[182:185], v[74:77]
	v_mfma_f32_16x16x32_bf16 v[54:57], v[58:61], v[190:193], v[54:57]
	v_mfma_f32_16x16x32_bf16 v[50:53], v[66:69], v[190:193], v[50:53]
	v_mfma_f32_16x16x32_bf16 v[30:33], v[58:61], v[198:201], v[30:33]
	v_mfma_f32_16x16x32_bf16 v[26:29], v[66:69], v[198:201], v[26:29]
	v_mfma_f32_16x16x32_bf16 v[14:17], v[58:61], v[220:223], v[14:17]
	v_mfma_f32_16x16x32_bf16 v[10:13], v[66:69], v[220:223], v[10:13]
	v_mfma_f32_16x16x32_bf16 v[78:81], v[62:65], v[186:189], v[78:81]
	v_mfma_f32_16x16x32_bf16 v[74:77], v[70:73], v[186:189], v[74:77]
	v_mfma_f32_16x16x32_bf16 v[54:57], v[62:65], v[194:197], v[54:57]
	v_mfma_f32_16x16x32_bf16 v[50:53], v[70:73], v[194:197], v[50:53]
	v_mfma_f32_16x16x32_bf16 v[30:33], v[62:65], v[216:219], v[30:33]
	v_mfma_f32_16x16x32_bf16 v[26:29], v[70:73], v[216:219], v[26:29]
	v_mfma_f32_16x16x32_bf16 v[14:17], v[62:65], v[224:227], v[14:17]
	v_mfma_f32_16x16x32_bf16 v[10:13], v[70:73], v[224:227], v[10:13]
	s_setprio 0
	s_setprio 1
	v_mfma_f32_16x16x32_bf16 v[42:45], v[158:161], v[182:185], v[42:45]
	v_mfma_f32_16x16x32_bf16 v[62:65], v[170:173], v[186:189], v[42:45]
	v_mfma_f32_16x16x32_bf16 v[42:45], v[174:177], v[182:185], v[46:49]
	v_mfma_f32_16x16x32_bf16 v[38:41], v[158:161], v[190:193], v[38:41]
	v_mfma_f32_16x16x32_bf16 v[34:37], v[174:177], v[190:193], v[34:37]
	v_mfma_f32_16x16x32_bf16 v[22:25], v[158:161], v[198:201], v[22:25]
	v_mfma_f32_16x16x32_bf16 v[18:21], v[174:177], v[198:201], v[18:21]
	v_mfma_f32_16x16x32_bf16 v[6:9], v[158:161], v[220:223], v[6:9]
	v_mfma_f32_16x16x32_bf16 v[2:5], v[174:177], v[220:223], v[2:5]
	v_mfma_f32_16x16x32_bf16 v[58:61], v[178:181], v[186:189], v[42:45]
	v_mfma_f32_16x16x32_bf16 v[38:41], v[170:173], v[194:197], v[38:41]
	v_mfma_f32_16x16x32_bf16 v[34:37], v[178:181], v[194:197], v[34:37]
	v_mfma_f32_16x16x32_bf16 v[22:25], v[170:173], v[216:219], v[22:25]
	v_mfma_f32_16x16x32_bf16 v[18:21], v[178:181], v[216:219], v[18:21]
	v_mfma_f32_16x16x32_bf16 v[6:9], v[170:173], v[224:227], v[6:9]
	v_mfma_f32_16x16x32_bf16 v[2:5], v[178:181], v[224:227], v[2:5]
	s_setprio 0
	s_waitcnt vmcnt(8)
	s_barrier
	s_add_i32 s93, s93, 2
	s_add_u32 s11, s11, 0x100
	s_addc_u32 s28, s28, 0
	s_cmp_gt_u32 s93, 41
	s_mov_b64 s[66:67], s[68:69]
	s_cbranch_scc0 .LBB0_2303
	s_and_b64 vcc, exec, s[26:27]
	s_cbranch_vccz .LBB0_2306
	s_barrier

; #define PG8_STAGE(bufoff, gbase, voff) do { _Pragma("unroll") for (int _i = 0; _i < 2; ++_i) \
;         __builtin_amdgcn_global_load_lds((const unsigned*)((const char*)(gbase) + (voff)[_i]), (LAS unsigned*)(lds + (bufoff) + ldsw + _i * 8192), 16, 0, 0); } while (0)
; #define PG8_LDA(dst, b, h) do { _Pragma("unroll") for (int m = 0; m < 4; ++m) _Pragma("unroll") for (int k = 0; k < 2; ++k) dst[m][k] = *(const LAS bf16x8*)(lds + PG8_SA(b, h) + aoff + m * 2048 + k * 1024); } while (0)
; #define PG8_LDB(dst, b, h) do { _Pragma("unroll") for (int n = 0; n < 2; ++n) _Pragma("unroll") for (int k = 0; k < 2; ++k) dst[n][k] = *(const LAS bf16x8*)(lds + PG8_SB(b, h) + boff + n * 2048 + k * 1024); } while (0)
; #define PG8_MMA(ai, bj, At, Bt) do { __builtin_amdgcn_s_setprio(1); _Pragma("unroll") for (int m = 0; m < 4; ++m) _Pragma("unroll") for (int n = 0; n < 2; ++n) _Pragma("unroll") for (int k = 0; k < 2; ++k) \
;         acc[ai][bj][m][n] = __builtin_amdgcn_mfma_f32_16x16x32_bf16(Bt[n][k], At[m][k], acc[ai][bj][m][n], 0, 0, 0); __builtin_amdgcn_s_setprio(0); } while (0)
; #define PG8_WAIT_V(n) asm volatile("s_waitcnt vmcnt(" #n ")" ::: "memory")
; #define PG8_WAIT_L(n) asm volatile("s_waitcnt lgkmcnt(" #n ")" ::: "memory")
; #define PG8_BAR __builtin_amdgcn_s_barrier()
; #define PG8_SCHED __builtin_amdgcn_sched_barrier(0)
; template <class Epi>
; __device__ __forceinline__ void gemm_phase(LAS unsigned char* lds, const int tid, const Gemm g, const StaticOrder& S, const Epi& E) {
;     ...
;         for (int t = 0; t < nt; t += 2) {
;             const bool last = (t == nt - 2);
;             const char* a1 = cA + (size_t)(t + 1) * kstep;
;             const char* a2 = last ? nA : cA + (size_t)(t + 2) * kstep; const char* b2 = last ? nB : cB + (size_t)(t + 2) * kstep;
;             const char* a3 = a2 + kstep; const char* b3 = b2 + kstep;
;             PG8_LDB(B0, 0, 0); PG8_LDB(B1, 0, 1); PG8_SCHED; PG8_LDA(At, 0, 0); PG8_STAGE(PG8_SA(1, 1), a1 + hstepA, voffA);
;             PG8_WAIT_V(8); PG8_WAIT_L(0); PG8_BAR; PG8_MMA(0, 0, At, B0); PG8_MMA(0, 1, At, B1); PG8_BAR; PG8_SCHED;
;             PG8_LDA(At, 0, 1); PG8_STAGE(PG8_SB(0, 0), b2, voffB); PG8_STAGE(PG8_SB(0, 1), b2 + hstepB, voffB); PG8_STAGE(PG8_SA(0, 0), a2, voffA);
;             PG8_WAIT_V(8); PG8_WAIT_L(0); PG8_BAR; PG8_MMA(1, 0, At, B0); PG8_MMA(1, 1, At, B1); PG8_BAR; PG8_SCHED;
.LBB0_2353:
	s_add_u32 s70, s68, 0x100
	s_addc_u32 s71, s69, 0
	s_add_i32 s76, 0, 0x10000
	s_cmp_eq_u32 vcc_hi, 40
	s_cselect_b32 s75, s1, s71
	s_cselect_b32 s74, s0, s70
	s_cselect_b32 s73, s31, vcc_lo
	s_cselect_b32 s72, s30, s11
	s_add_i32 s2, 0, 0x14000
	v_add_u32_e32 v154, s76, v199
	v_add_u32_e32 v162, s2, v199
	ds_read_b128 v[130:133], v154
	ds_read_b128 v[134:137], v154 offset:1024
	ds_read_b128 v[138:141], v154 offset:2048
	ds_read_b128 v[154:157], v154 offset:3072
	ds_read_b128 v[158:161], v162
	ds_read_b128 v[170:173], v162 offset:1024
	ds_read_b128 v[174:177], v162 offset:2048
	ds_read_b128 v[212:215], v162 offset:3072
	v_lshl_add_u64 v[162:163], s[68:69], 0, v[150:151]
	s_add_i32 m0, s83, 0xc000
	s_nop 0
	global_load_lds_dwordx4 v[162:163], off
	v_lshl_add_u64 v[162:163], s[68:69], 0, v[152:153]
	s_add_i32 m0, s83, 0xe000
	s_nop 0
	global_load_lds_dwordx4 v[162:163], off
	ds_read_b128 v[216:219], v201
	ds_read_b128 v[220:223], v201 offset:1024
	ds_read_b128 v[224:227], v201 offset:2048
	ds_read_b128 v[228:231], v201 offset:3072
	ds_read_b128 v[232:235], v201 offset:4096
	ds_read_b128 v[236:239], v201 offset:5120
	ds_read_b128 v[240:243], v201 offset:6144
	ds_read_b128 v[244:247], v201 offset:7168
	s_cmp_lg_u64 s[26:27], 0
	s_cbranch_scc1 .Lkw_4
	s_waitcnt vmcnt(8)
.Lkw_4:
	s_waitcnt lgkmcnt(0)
	s_barrier
	s_setprio 1
	s_waitcnt lgkmcnt(0)
	v_mfma_f32_16x16x32_bf16 v[126:129], v[130:133], v[216:219], v[126:129]
	v_mfma_f32_16x16x32_bf16 v[122:125], v[138:141], v[216:219], v[122:125]
	v_mfma_f32_16x16x32_bf16 v[110:113], v[130:133], v[224:227], v[110:113]
	v_mfma_f32_16x16x32_bf16 v[106:109], v[138:141], v[224:227], v[106:109]
	v_mfma_f32_16x16x32_bf16 v[94:97], v[130:133], v[232:235], v[94:97]
	v_mfma_f32_16x16x32_bf16 v[90:93], v[138:141], v[232:235], v[90:93]
	v_mfma_f32_16x16x32_bf16 v[78:81], v[130:133], v[240:243], v[78:81]
	v_mfma_f32_16x16x32_bf16 v[74:77], v[138:141], v[240:243], v[74:77]
	v_mfma_f32_16x16x32_bf16 v[126:129], v[134:137], v[220:223], v[126:129]
	v_mfma_f32_16x16x32_bf16 v[122:125], v[154:157], v[220:223], v[122:125]
	v_mfma_f32_16x16x32_bf16 v[110:113], v[134:137], v[228:231], v[110:113]
	v_mfma_f32_16x16x32_bf16 v[106:109], v[154:157], v[228:231], v[106:109]
	v_mfma_f32_16x16x32_bf16 v[94:97], v[134:137], v[236:239], v[94:97]
	v_mfma_f32_16x16x32_bf16 v[90:93], v[154:157], v[236:239], v[90:93]
	v_mfma_f32_16x16x32_bf16 v[78:81], v[134:137], v[244:247], v[78:81]
	v_mfma_f32_16x16x32_bf16 v[74:77], v[154:157], v[244:247], v[74:77]
	s_setprio 0
	s_setprio 1
	v_mfma_f32_16x16x32_bf16 v[118:121], v[158:161], v[216:219], v[118:121]
	v_mfma_f32_16x16x32_bf16 v[114:117], v[174:177], v[216:219], v[114:117]
	v_mfma_f32_16x16x32_bf16 v[102:105], v[158:161], v[224:227], v[102:105]
	v_mfma_f32_16x16x32_bf16 v[98:101], v[174:177], v[224:227], v[98:101]
	v_mfma_f32_16x16x32_bf16 v[86:89], v[158:161], v[232:235], v[86:89]
	v_mfma_f32_16x16x32_bf16 v[82:85], v[174:177], v[232:235], v[82:85]
	v_mfma_f32_16x16x32_bf16 v[70:73], v[158:161], v[240:243], v[70:73]
	v_mfma_f32_16x16x32_bf16 v[66:69], v[174:177], v[240:243], v[66:69]
	v_mfma_f32_16x16x32_bf16 v[118:121], v[170:173], v[220:223], v[118:121]
	v_mfma_f32_16x16x32_bf16 v[114:117], v[212:215], v[220:223], v[114:117]
	v_mfma_f32_16x16x32_bf16 v[102:105], v[170:173], v[228:231], v[102:105]
	v_mfma_f32_16x16x32_bf16 v[98:101], v[212:215], v[228:231], v[98:101]
	v_mfma_f32_16x16x32_bf16 v[86:89], v[170:173], v[236:239], v[86:89]
	v_mfma_f32_16x16x32_bf16 v[82:85], v[212:215], v[236:239], v[82:85]
	v_mfma_f32_16x16x32_bf16 v[70:73], v[170:173], v[244:247], v[70:73]
	v_mfma_f32_16x16x32_bf16 v[66:69], v[212:215], v[244:247], v[66:69]
	s_setprio 0
	s_waitcnt vmcnt(8)
	s_barrier
	s_add_i32 s3, s76, s82
	v_lshl_add_u64 v[162:163], s[72:73], 0, v[0:1]
	s_mov_b32 m0, s3
	s_nop 0
	global_load_lds_dwordx4 v[162:163], off
	s_add_i32 m0, s3, 0x2000
	s_add_u32 s68, s72, 0xb0000
	v_lshl_add_u64 v[164:165], s[72:73], 0, v[142:143]
	s_addc_u32 s69, s73, 0
	s_add_i32 s2, s2, s82
	global_load_lds_dwordx4 v[164:165], off
	v_lshl_add_u64 v[178:179], s[68:69], 0, v[0:1]
	s_mov_b32 m0, s2
	v_lshl_add_u64 v[206:207], s[74:75], 0, v[148:149]
	global_load_lds_dwordx4 v[178:179], off
	v_lshl_add_u64 v[178:179], s[68:69], 0, v[142:143]
	s_add_i32 m0, s2, 0x2000
	s_nop 0
	global_load_lds_dwordx4 v[178:179], off
	v_lshl_add_u64 v[178:179], s[74:75], 0, v[144:145]
	s_mov_b32 m0, s83
	s_nop 0
	global_load_lds_dwordx4 v[178:179], off
	s_mov_b32 m0, s88
	s_nop 0
	global_load_lds_dwordx4 v[206:207], off
	ds_read_b128 v[216:219], v201 offset:16384
	ds_read_b128 v[220:223], v201 offset:17408
	ds_read_b128 v[224:227], v201 offset:18432
	ds_read_b128 v[228:231], v201 offset:19456
	ds_read_b128 v[232:235], v201 offset:20480
	ds_read_b128 v[236:239], v201 offset:21504
	ds_read_b128 v[240:243], v201 offset:22528
	ds_read_b128 v[244:247], v201 offset:23552
	s_cmp_lg_u64 s[26:27], 0
	s_cbranch_scc1 .Lkw_3
	s_waitcnt vmcnt(8)
; #define PG8_STAGE(bufoff, gbase, voff) do { _Pragma("unroll") for (int _i = 0; _i < 2; ++_i) \
;         __builtin_amdgcn_global_load_lds((const unsigned*)((const char*)(gbase) + (voff)[_i]), (LAS unsigned*)(lds + (bufoff) + ldsw + _i * 8192), 16, 0, 0); } while (0)
; #define PG8_LDA(dst, b, h) do { _Pragma("unroll") for (int m = 0; m < 4; ++m) _Pragma("unroll") for (int k = 0; k < 2; ++k) dst[m][k] = *(const LAS bf16x8*)(lds + PG8_SA(b, h) + aoff + m * 2048 + k * 1024); } while (0)
; #define PG8_LDB(dst, b, h) do { _Pragma("unroll") for (int n = 0; n < 2; ++n) _Pragma("unroll") for (int k = 0; k < 2; ++k) dst[n][k] = *(const LAS bf16x8*)(lds + PG8_SB(b, h) + boff + n * 2048 + k * 1024); } while (0)
; #define PG8_MMA(ai, bj, At, Bt) do { __builtin_amdgcn_s_setprio(1); _Pragma("unroll") for (int m = 0; m < 4; ++m) _Pragma("unroll") for (int n = 0; n < 2; ++n) _Pragma("unroll") for (int k = 0; k < 2; ++k) \
;         acc[ai][bj][m][n] = __builtin_amdgcn_mfma_f32_16x16x32_bf16(Bt[n][k], At[m][k], acc[ai][bj][m][n], 0, 0, 0); __builtin_amdgcn_s_setprio(0); } while (0)
; #define PG8_WAIT_V(n) asm volatile("s_waitcnt vmcnt(" #n ")" ::: "memory")
; #define PG8_WAIT_L(n) asm volatile("s_waitcnt lgkmcnt(" #n ")" ::: "memory")
; #define PG8_BAR __builtin_amdgcn_s_barrier()
; #define PG8_SCHED __builtin_amdgcn_sched_barrier(0)
; template <class Epi>
; __device__ __forceinline__ void gemm_phase(LAS unsigned char* lds, const int tid, const Gemm g, const StaticOrder& S, const Epi& E) {
;     ...
;             PG8_WAIT_V(8); PG8_WAIT_L(0); PG8_BAR; PG8_MMA(1, 0, At, B0); PG8_MMA(1, 1, At, B1); PG8_BAR; PG8_SCHED;
;             PG8_LDB(B0, 1, 0); PG8_LDB(B1, 1, 1); PG8_SCHED; PG8_LDA(At, 1, 0); PG8_STAGE(PG8_SA(0, 1), a2 + hstepA, voffA);
;             PG8_WAIT_V(8); PG8_WAIT_L(0); PG8_BAR; PG8_MMA(0, 0, At, B0); PG8_MMA(0, 1, At, B1); PG8_BAR; PG8_SCHED;
.Lkw_3:
	s_waitcnt lgkmcnt(0)
	s_barrier
	s_setprio 1
	s_waitcnt lgkmcnt(0)
	v_mfma_f32_16x16x32_bf16 v[62:65], v[130:133], v[216:219], v[62:65]
	v_mfma_f32_16x16x32_bf16 v[58:61], v[138:141], v[216:219], v[58:61]
	v_mfma_f32_16x16x32_bf16 v[46:49], v[130:133], v[224:227], v[46:49]
	v_mfma_f32_16x16x32_bf16 v[42:45], v[138:141], v[224:227], v[42:45]
	v_mfma_f32_16x16x32_bf16 v[30:33], v[130:133], v[232:235], v[30:33]
	v_mfma_f32_16x16x32_bf16 v[26:29], v[138:141], v[232:235], v[26:29]
	v_mfma_f32_16x16x32_bf16 v[14:17], v[130:133], v[240:243], v[14:17]
	v_mfma_f32_16x16x32_bf16 v[10:13], v[138:141], v[240:243], v[10:13]
	v_mfma_f32_16x16x32_bf16 v[62:65], v[134:137], v[220:223], v[62:65]
	v_mfma_f32_16x16x32_bf16 v[58:61], v[154:157], v[220:223], v[58:61]
	v_mfma_f32_16x16x32_bf16 v[46:49], v[134:137], v[228:231], v[46:49]
	v_mfma_f32_16x16x32_bf16 v[42:45], v[154:157], v[228:231], v[42:45]
	v_mfma_f32_16x16x32_bf16 v[30:33], v[134:137], v[236:239], v[30:33]
	v_mfma_f32_16x16x32_bf16 v[26:29], v[154:157], v[236:239], v[26:29]
	v_mfma_f32_16x16x32_bf16 v[14:17], v[134:137], v[244:247], v[14:17]
	v_mfma_f32_16x16x32_bf16 v[10:13], v[154:157], v[244:247], v[10:13]
	s_setprio 0
	s_setprio 1
	v_mfma_f32_16x16x32_bf16 v[54:57], v[158:161], v[216:219], v[54:57]
	v_mfma_f32_16x16x32_bf16 v[50:53], v[174:177], v[216:219], v[50:53]
	v_mfma_f32_16x16x32_bf16 v[38:41], v[158:161], v[224:227], v[38:41]
	v_mfma_f32_16x16x32_bf16 v[34:37], v[174:177], v[224:227], v[34:37]
	v_mfma_f32_16x16x32_bf16 v[22:25], v[158:161], v[232:235], v[22:25]
	v_mfma_f32_16x16x32_bf16 v[18:21], v[174:177], v[232:235], v[18:21]
	v_mfma_f32_16x16x32_bf16 v[6:9], v[158:161], v[240:243], v[6:9]
	v_mfma_f32_16x16x32_bf16 v[2:5], v[174:177], v[240:243], v[2:5]
	v_mfma_f32_16x16x32_bf16 v[54:57], v[170:173], v[220:223], v[54:57]
	v_mfma_f32_16x16x32_bf16 v[50:53], v[212:215], v[220:223], v[50:53]
	v_mfma_f32_16x16x32_bf16 v[38:41], v[170:173], v[228:231], v[38:41]
	v_mfma_f32_16x16x32_bf16 v[34:37], v[212:215], v[228:231], v[34:37]
	v_mfma_f32_16x16x32_bf16 v[22:25], v[170:173], v[236:239], v[22:25]
	v_mfma_f32_16x16x32_bf16 v[18:21], v[212:215], v[236:239], v[18:21]
	v_mfma_f32_16x16x32_bf16 v[6:9], v[170:173], v[244:247], v[6:9]
	v_mfma_f32_16x16x32_bf16 v[2:5], v[212:215], v[244:247], v[2:5]
	s_setprio 0
	s_waitcnt vmcnt(8)
	s_barrier
	s_add_i32 s2, 0, 0x18000
	s_add_i32 s3, 0, 0x1c000
	v_add_u32_e32 v154, s2, v199
	v_add_u32_e32 v192, s3, v199
	ds_read_b128 v[130:133], v154
	ds_read_b128 v[134:137], v154 offset:1024
	ds_read_b128 v[138:141], v154 offset:2048
	ds_read_b128 v[154:157], v154 offset:3072
	ds_read_b128 v[158:161], v192
	ds_read_b128 v[170:173], v192 offset:1024
	ds_read_b128 v[174:177], v192 offset:2048
	ds_read_b128 v[212:215], v192 offset:3072
	s_add_u32 s68, s74, 0x160000
	s_addc_u32 s69, s75, 0
	s_mov_b32 m0, s89
	v_lshl_add_u64 v[192:193], s[68:69], 0, v[144:145]
	global_load_lds_dwordx4 v[192:193], off
	v_lshl_add_u64 v[192:193], s[68:69], 0, v[148:149]
	s_mov_b32 m0, s92
	s_nop 0
	global_load_lds_dwordx4 v[192:193], off
	ds_read_b128 v[216:219], v201 offset:32768
	ds_read_b128 v[220:223], v201 offset:33792
	ds_read_b128 v[224:227], v201 offset:34816
	ds_read_b128 v[228:231], v201 offset:35840
	ds_read_b128 v[232:235], v201 offset:36864
	ds_read_b128 v[236:239], v201 offset:37888
	ds_read_b128 v[240:243], v201 offset:38912
	ds_read_b128 v[244:247], v201 offset:39936
	s_cmp_lg_u64 s[26:27], 0
	s_cbranch_scc1 .Lkw_2
	s_waitcnt vmcnt(8)
; #define PG8_STAGE(bufoff, gbase, voff) do { _Pragma("unroll") for (int _i = 0; _i < 2; ++_i) \
;         __builtin_amdgcn_global_load_lds((const unsigned*)((const char*)(gbase) + (voff)[_i]), (LAS unsigned*)(lds + (bufoff) + ldsw + _i * 8192), 16, 0, 0); } while (0)
; #define PG8_LDA(dst, b, h) do { _Pragma("unroll") for (int m = 0; m < 4; ++m) _Pragma("unroll") for (int k = 0; k < 2; ++k) dst[m][k] = *(const LAS bf16x8*)(lds + PG8_SA(b, h) + aoff + m * 2048 + k * 1024); } while (0)
; #define PG8_MMA(ai, bj, At, Bt) do { __builtin_amdgcn_s_setprio(1); _Pragma("unroll") for (int m = 0; m < 4; ++m) _Pragma("unroll") for (int n = 0; n < 2; ++n) _Pragma("unroll") for (int k = 0; k < 2; ++k) \
;         acc[ai][bj][m][n] = __builtin_amdgcn_mfma_f32_16x16x32_bf16(Bt[n][k], At[m][k], acc[ai][bj][m][n], 0, 0, 0); __builtin_amdgcn_s_setprio(0); } while (0)
; #define PG8_WAIT_V(n) asm volatile("s_waitcnt vmcnt(" #n ")" ::: "memory")
; #define PG8_WAIT_L(n) asm volatile("s_waitcnt lgkmcnt(" #n ")" ::: "memory")
; #define PG8_BAR __builtin_amdgcn_s_barrier()
; #define PG8_SCHED __builtin_amdgcn_sched_barrier(0)
; template <class Epi>
; __device__ __forceinline__ void gemm_phase(LAS unsigned char* lds, const int tid, const Gemm g, const StaticOrder& S, const Epi& E) {
;     ...
;             PG8_WAIT_V(8); PG8_WAIT_L(0); PG8_BAR; PG8_MMA(0, 0, At, B0); PG8_MMA(0, 1, At, B1); PG8_BAR; PG8_SCHED;
;             PG8_LDA(At, 1, 1); PG8_STAGE(PG8_SB(1, 0), b3, voffB); PG8_STAGE(PG8_SB(1, 1), b3 + hstepB, voffB); PG8_STAGE(PG8_SA(1, 0), a3, voffA);
;             PG8_WAIT_V(8); PG8_WAIT_L(0); PG8_BAR; PG8_MMA(1, 0, At, B0); PG8_MMA(1, 1, At, B1); PG8_BAR; PG8_SCHED;
;         }
;         if (wr == 0) PG8_BAR;
.Lkw_2:
	s_waitcnt lgkmcnt(0)
	s_barrier
	s_setprio 1
	s_waitcnt lgkmcnt(0)
	v_mfma_f32_16x16x32_bf16 v[126:129], v[130:133], v[216:219], v[126:129]
	v_mfma_f32_16x16x32_bf16 v[122:125], v[138:141], v[216:219], v[122:125]
	v_mfma_f32_16x16x32_bf16 v[110:113], v[130:133], v[224:227], v[110:113]
	v_mfma_f32_16x16x32_bf16 v[106:109], v[138:141], v[224:227], v[106:109]
	v_mfma_f32_16x16x32_bf16 v[94:97], v[130:133], v[232:235], v[94:97]
	v_mfma_f32_16x16x32_bf16 v[90:93], v[138:141], v[232:235], v[90:93]
	v_mfma_f32_16x16x32_bf16 v[78:81], v[130:133], v[240:243], v[78:81]
	v_mfma_f32_16x16x32_bf16 v[74:77], v[138:141], v[240:243], v[74:77]
	v_mfma_f32_16x16x32_bf16 v[126:129], v[134:137], v[220:223], v[126:129]
	v_mfma_f32_16x16x32_bf16 v[122:125], v[154:157], v[220:223], v[122:125]
	v_mfma_f32_16x16x32_bf16 v[110:113], v[134:137], v[228:231], v[110:113]
	v_mfma_f32_16x16x32_bf16 v[106:109], v[154:157], v[228:231], v[106:109]
	v_mfma_f32_16x16x32_bf16 v[94:97], v[134:137], v[236:239], v[94:97]
	v_mfma_f32_16x16x32_bf16 v[90:93], v[154:157], v[236:239], v[90:93]
	v_mfma_f32_16x16x32_bf16 v[78:81], v[134:137], v[244:247], v[78:81]
	v_mfma_f32_16x16x32_bf16 v[74:77], v[154:157], v[244:247], v[74:77]
	s_setprio 0
	s_setprio 1
	v_mfma_f32_16x16x32_bf16 v[118:121], v[158:161], v[216:219], v[118:121]
	v_mfma_f32_16x16x32_bf16 v[114:117], v[174:177], v[216:219], v[114:117]
	v_mfma_f32_16x16x32_bf16 v[102:105], v[158:161], v[224:227], v[102:105]
	v_mfma_f32_16x16x32_bf16 v[98:101], v[174:177], v[224:227], v[98:101]
	v_mfma_f32_16x16x32_bf16 v[86:89], v[158:161], v[232:235], v[86:89]
	v_mfma_f32_16x16x32_bf16 v[82:85], v[174:177], v[232:235], v[82:85]
	v_mfma_f32_16x16x32_bf16 v[70:73], v[158:161], v[240:243], v[70:73]
	v_mfma_f32_16x16x32_bf16 v[66:69], v[174:177], v[240:243], v[66:69]
	v_mfma_f32_16x16x32_bf16 v[118:121], v[170:173], v[220:223], v[118:121]
	v_mfma_f32_16x16x32_bf16 v[114:117], v[212:215], v[220:223], v[114:117]
	v_mfma_f32_16x16x32_bf16 v[102:105], v[170:173], v[228:231], v[102:105]
	v_mfma_f32_16x16x32_bf16 v[98:101], v[212:215], v[228:231], v[98:101]
	v_mfma_f32_16x16x32_bf16 v[86:89], v[170:173], v[236:239], v[86:89]
	v_mfma_f32_16x16x32_bf16 v[82:85], v[212:215], v[236:239], v[82:85]
	v_mfma_f32_16x16x32_bf16 v[70:73], v[170:173], v[244:247], v[70:73]
	v_mfma_f32_16x16x32_bf16 v[66:69], v[212:215], v[244:247], v[66:69]
	s_setprio 0
	s_waitcnt vmcnt(8)
	s_barrier
	s_add_i32 s2, s2, s82
	v_lshl_add_u64 v[162:163], v[162:163], 0, s[36:37]
	s_mov_b32 m0, s2
	s_nop 0
	global_load_lds_dwordx4 v[162:163], off
	s_add_i32 m0, s2, 0x2000
	s_add_u32 s68, s72, 0xb0080
	v_lshl_add_u64 v[162:163], v[164:165], 0, s[36:37]
	s_addc_u32 s69, s73, 0
	s_add_i32 s2, s3, s82
	global_load_lds_dwordx4 v[162:163], off
	v_lshl_add_u64 v[162:163], s[68:69], 0, v[0:1]
	s_mov_b32 m0, s2
	s_nop 0
	global_load_lds_dwordx4 v[162:163], off
	v_lshl_add_u64 v[162:163], s[68:69], 0, v[142:143]
	s_add_i32 m0, s2, 0x2000
	s_nop 0
	global_load_lds_dwordx4 v[162:163], off
	v_lshl_add_u64 v[162:163], v[178:179], 0, s[36:37]
	s_mov_b32 m0, s4
	s_nop 0
	global_load_lds_dwordx4 v[162:163], off
	v_lshl_add_u64 v[162:163], v[206:207], 0, s[36:37]
	s_mov_b32 m0, s5
	s_nop 0
	global_load_lds_dwordx4 v[162:163], off
	ds_read_b128 v[216:219], v201 offset:49152
	ds_read_b128 v[220:223], v201 offset:50176
	ds_read_b128 v[224:227], v201 offset:51200
	ds_read_b128 v[228:231], v201 offset:52224
	ds_read_b128 v[232:235], v201 offset:53248
	ds_read_b128 v[236:239], v201 offset:54272
	ds_read_b128 v[240:243], v201 offset:55296
	ds_read_b128 v[244:247], v201 offset:56320
	s_cmp_lg_u64 s[26:27], 0
	s_cbranch_scc1 .Lkw_1
	s_waitcnt vmcnt(8)
.Lkw_1:
	s_waitcnt lgkmcnt(0)
	s_barrier
	s_setprio 1
	s_waitcnt lgkmcnt(0)
	v_mfma_f32_16x16x32_bf16 v[62:65], v[130:133], v[216:219], v[62:65]
	v_mfma_f32_16x16x32_bf16 v[58:61], v[138:141], v[216:219], v[58:61]
	v_mfma_f32_16x16x32_bf16 v[46:49], v[130:133], v[224:227], v[46:49]
	v_mfma_f32_16x16x32_bf16 v[42:45], v[138:141], v[224:227], v[42:45]
	v_mfma_f32_16x16x32_bf16 v[30:33], v[130:133], v[232:235], v[30:33]
	v_mfma_f32_16x16x32_bf16 v[26:29], v[138:141], v[232:235], v[26:29]
	v_mfma_f32_16x16x32_bf16 v[14:17], v[130:133], v[240:243], v[14:17]
	v_mfma_f32_16x16x32_bf16 v[10:13], v[138:141], v[240:243], v[10:13]
	v_mfma_f32_16x16x32_bf16 v[62:65], v[134:137], v[220:223], v[62:65]
	v_mfma_f32_16x16x32_bf16 v[58:61], v[154:157], v[220:223], v[58:61]
	v_mfma_f32_16x16x32_bf16 v[46:49], v[134:137], v[228:231], v[46:49]
	v_mfma_f32_16x16x32_bf16 v[42:45], v[154:157], v[228:231], v[42:45]
	v_mfma_f32_16x16x32_bf16 v[30:33], v[134:137], v[236:239], v[30:33]
	v_mfma_f32_16x16x32_bf16 v[26:29], v[154:157], v[236:239], v[26:29]
	v_mfma_f32_16x16x32_bf16 v[14:17], v[134:137], v[244:247], v[14:17]
	v_mfma_f32_16x16x32_bf16 v[10:13], v[154:157], v[244:247], v[10:13]
	s_setprio 0
	s_setprio 1
	v_mfma_f32_16x16x32_bf16 v[54:57], v[158:161], v[216:219], v[54:57]
	v_mfma_f32_16x16x32_bf16 v[50:53], v[174:177], v[216:219], v[50:53]
	v_mfma_f32_16x16x32_bf16 v[38:41], v[158:161], v[224:227], v[38:41]
	v_mfma_f32_16x16x32_bf16 v[34:37], v[174:177], v[224:227], v[34:37]
	v_mfma_f32_16x16x32_bf16 v[22:25], v[158:161], v[232:235], v[22:25]
	v_mfma_f32_16x16x32_bf16 v[18:21], v[174:177], v[232:235], v[18:21]
	v_mfma_f32_16x16x32_bf16 v[6:9], v[158:161], v[240:243], v[6:9]
	v_mfma_f32_16x16x32_bf16 v[2:5], v[174:177], v[240:243], v[2:5]
	v_mfma_f32_16x16x32_bf16 v[54:57], v[170:173], v[220:223], v[54:57]
	v_mfma_f32_16x16x32_bf16 v[50:53], v[212:215], v[220:223], v[50:53]
	v_mfma_f32_16x16x32_bf16 v[38:41], v[170:173], v[228:231], v[38:41]
	v_mfma_f32_16x16x32_bf16 v[34:37], v[212:215], v[228:231], v[34:37]
	v_mfma_f32_16x16x32_bf16 v[22:25], v[170:173], v[236:239], v[22:25]
	v_mfma_f32_16x16x32_bf16 v[18:21], v[212:215], v[236:239], v[18:21]
	v_mfma_f32_16x16x32_bf16 v[6:9], v[170:173], v[244:247], v[6:9]
	v_mfma_f32_16x16x32_bf16 v[2:5], v[212:215], v[244:247], v[2:5]
	s_setprio 0
	s_waitcnt vmcnt(8)
	s_barrier
	s_add_i32 vcc_hi, vcc_hi, 2
	s_add_u32 s11, s11, 0x100
	s_addc_u32 vcc_lo, vcc_lo, 0
	s_cmp_gt_u32 vcc_hi, 41
	s_mov_b64 s[68:69], s[70:71]
	s_cbranch_scc0 .LBB0_2353
	s_and_b64 vcc, exec, s[26:27]
	s_cbranch_vccz .LBB0_2356
	s_barrier
